# v3
# speedup vs baseline: 1.0070x; 1.0070x over previous
.LBB0_757:
	v_lshlrev_b32_e32 v48, 4, v46
	s_waitcnt vmcnt(0) lgkmcnt(0)
	v_add_u32_e32 v36, 0, v48
	v_mul_lo_u32 v37, v154, s38
	v_lshlrev_b32_e32 v39, 16, v23
	v_lshlrev_b32_e32 v38, 16, v22
	v_and_b32_e32 v50, 0xffff0000, v20
	v_and_b32_e32 v51, 0xffff0000, v21
	v_and_b32_e32 v52, 0xffff0000, v22
	v_and_b32_e32 v53, 0xffff0000, v23
	v_add_u32_e32 v36, v36, v37
	v_lshlrev_b32_e32 v22, 16, v24
	v_lshlrev_b32_e32 v23, 16, v25
	v_lshlrev_b32_e32 v24, 16, v26
	v_lshlrev_b32_e32 v25, 16, v27
	ds_write_b128 v36, v[50:53]
	ds_write_b128 v36, v[32:35] offset:256
	ds_write_b128 v36, v[28:31] offset:512
	ds_write_b128 v36, v[40:43] offset:768
	ds_write_b128 v36, v[22:25] offset:1280
	v_lshlrev_b32_e32 v25, 16, v21
	v_lshlrev_b32_e32 v24, 16, v20
	v_pk_mul_f32 v[22:23], v[34:35], v[38:39]
	v_pk_mul_f32 v[20:21], v[32:33], v[24:25]
	ds_write_b128 v36, v[20:23] offset:1024
	v_mov_b32_e32 v21, v41
	v_mov_b32_e32 v41, v29
	v_mov_b32_e32 v20, v28
	v_pk_mul_f32 v[22:23], v[40:41], v[24:25]
	v_cmp_eq_u32_e64 s[8:9], 0, v46
	v_pk_fma_f32 v[20:21], v[20:21], v[24:25], v[22:23] op_sel:[0,0,1] op_sel_hi:[1,1,0]
	v_mov_b32_e32 v22, v30
	v_mov_b32_e32 v23, v42
	v_pk_fma_f32 v[20:21], v[38:39], v[22:23], v[20:21] op_sel_hi:[0,1,1]
	v_mov_b32_e32 v42, v31
	v_mov_b32_e32 v22, v39
	v_pk_fma_f32 v[20:21], v[22:23], v[42:43], v[20:21] op_sel_hi:[0,1,1]
	s_nop 1
	v_add_f32_dpp v20, v20, v20 quad_perm:[1,0,3,2] row_mask:0xf bank_mask:0xf bound_ctrl:1
	v_add_f32_dpp v21, v21, v21 quad_perm:[1,0,3,2] row_mask:0xf bank_mask:0xf bound_ctrl:1
	s_nop 1
	v_add_f32_dpp v20, v20, v20 quad_perm:[2,3,0,1] row_mask:0xf bank_mask:0xf bound_ctrl:1
	v_add_f32_dpp v21, v21, v21 quad_perm:[2,3,0,1] row_mask:0xf bank_mask:0xf bound_ctrl:1
	s_nop 1
	v_add_f32_dpp v20, v20, v20 row_half_mirror row_mask:0xf bank_mask:0xf bound_ctrl:1
	v_add_f32_dpp v21, v21, v21 row_half_mirror row_mask:0xf bank_mask:0xf bound_ctrl:1
	s_nop 1
	v_mov_b32_dpp v23, v21 row_mirror row_mask:0xf bank_mask:0xf bound_ctrl:1
	v_mov_b32_dpp v22, v20 row_mirror row_mask:0xf bank_mask:0xf bound_ctrl:1
	s_and_saveexec_b64 s[24:25], s[8:9]
	v_pk_add_f32 v[20:21], v[20:21], v[22:23]
	s_nop 0
	v_pk_mov_b32 v[20:21], v[20:21], v[20:21] op_sel:[1,0]
	ds_write_b64 v36, v[20:21] offset:1536
	s_or_b64 exec, exec, s[24:25]
	s_and_b64 vcc, exec, s[6:7]
	s_mov_b64 s[24:25], -1
	s_cbranch_vccnz .LBB0_763
	v_and_b32_e32 v20, 0xffff0000, v16
	v_and_b32_e32 v21, 0xffff0000, v17
	v_and_b32_e32 v22, 0xffff0000, v18
	v_and_b32_e32 v23, 0xffff0000, v19
	s_cbranch_execz .LBB0_764

.LBB0_767:
	v_and_b32_e32 v12, 0xffff0000, v0
	v_and_b32_e32 v13, 0xffff0000, v1
	v_and_b32_e32 v14, 0xffff0000, v2
	v_and_b32_e32 v15, 0xffff0000, v3
	v_lshlrev_b32_e32 v8, 16, v8
	v_lshlrev_b32_e32 v9, 16, v9
	v_lshlrev_b32_e32 v10, 16, v10
	v_lshlrev_b32_e32 v11, 16, v11
	v_lshlrev_b32_e32 v25, 16, v3
	v_lshlrev_b32_e32 v24, 16, v2
	ds_write_b128 v36, v[12:15] offset:25088
	ds_write_b128 v36, v[4:7] offset:25344
	ds_write_b128 v36, v[20:23] offset:25600
	ds_write_b128 v36, v[16:19] offset:25856
	ds_write_b128 v36, v[8:11] offset:26368
	v_lshlrev_b32_e32 v9, 16, v1
	v_lshlrev_b32_e32 v8, 16, v0
	v_pk_mul_f32 v[2:3], v[6:7], v[24:25]
	v_pk_mul_f32 v[0:1], v[4:5], v[8:9]
	ds_write_b128 v36, v[0:3] offset:26112
	v_mov_b32_e32 v1, v17
	v_mov_b32_e32 v17, v21
	v_mov_b32_e32 v0, v20
	v_pk_mul_f32 v[2:3], v[16:17], v[8:9]
	s_nop 0
	v_pk_fma_f32 v[0:1], v[0:1], v[8:9], v[2:3] op_sel:[0,0,1] op_sel_hi:[1,1,0]
	v_mov_b32_e32 v2, v22
	v_mov_b32_e32 v3, v18
	v_pk_fma_f32 v[0:1], v[24:25], v[2:3], v[0:1] op_sel_hi:[0,1,1]
	v_mov_b32_e32 v18, v23
	v_mov_b32_e32 v2, v25
	v_pk_fma_f32 v[0:1], v[2:3], v[18:19], v[0:1] op_sel_hi:[0,1,1]
	s_nop 1
	v_add_f32_dpp v0, v0, v0 quad_perm:[1,0,3,2] row_mask:0xf bank_mask:0xf bound_ctrl:1
	v_add_f32_dpp v1, v1, v1 quad_perm:[1,0,3,2] row_mask:0xf bank_mask:0xf bound_ctrl:1
	s_nop 1
	v_add_f32_dpp v0, v0, v0 quad_perm:[2,3,0,1] row_mask:0xf bank_mask:0xf bound_ctrl:1
	v_add_f32_dpp v1, v1, v1 quad_perm:[2,3,0,1] row_mask:0xf bank_mask:0xf bound_ctrl:1
	s_nop 1
	v_add_f32_dpp v0, v0, v0 row_half_mirror row_mask:0xf bank_mask:0xf bound_ctrl:1
	v_add_f32_dpp v1, v1, v1 row_half_mirror row_mask:0xf bank_mask:0xf bound_ctrl:1
	s_nop 1
	v_mov_b32_dpp v3, v1 row_mirror row_mask:0xf bank_mask:0xf bound_ctrl:1
	v_mov_b32_dpp v2, v0 row_mirror row_mask:0xf bank_mask:0xf bound_ctrl:1
	s_and_saveexec_b64 s[24:25], s[8:9]
	v_pk_add_f32 v[0:1], v[0:1], v[2:3]
	s_nop 0
	v_pk_mov_b32 v[0:1], v[0:1], v[0:1] op_sel:[1,0]
	ds_write_b64 v36, v[0:1] offset:26624
	s_or_b64 exec, exec, s[24:25]
	v_add_u32_e32 v0, 32, v154
	v_sub_u32_e32 v1, 0xdf, v154
	v_add_u32_e32 v18, 48, v154
	v_sub_u32_e32 v19, 0xcf, v154
	v_cndmask_b32_e64 v0, v1, v0, s[0:1]
	v_cndmask_b32_e64 v18, v19, v18, s[0:1]
	v_add_u32_e32 v0, s33, v0
	v_add_u32_e32 v18, s33, v18
	v_ashrrev_i32_e32 v1, 31, v0
	v_ashrrev_i32_e32 v19, 31, v18
	v_lshlrev_b64 v[0:1], 11, v[0:1]
	v_lshlrev_b64 v[18:19], 11, v[18:19]
	v_or_b32_e32 v17, v1, v45
	v_or_b32_e32 v16, v0, v44
	v_or_b32_e32 v33, v19, v45
	v_or_b32_e32 v32, v18, v44
	v_lshl_add_u64 v[0:1], s[12:13], 0, v[16:17]
	v_lshl_add_u64 v[4:5], s[14:15], 0, v[16:17]
	v_lshl_add_u64 v[8:9], s[16:17], 0, v[16:17]
	v_lshl_add_u64 v[12:13], s[18:19], 0, v[16:17]
	v_lshl_add_u64 v[16:17], s[20:21], 0, v[16:17]
	v_lshl_add_u64 v[20:21], s[12:13], 0, v[32:33]
	v_lshl_add_u64 v[24:25], s[14:15], 0, v[32:33]
	v_lshl_add_u64 v[28:29], s[16:17], 0, v[32:33]
	v_lshl_add_u64 v[34:35], s[18:19], 0, v[32:33]
	v_lshl_add_u64 v[36:37], s[20:21], 0, v[32:33]
	flat_load_dwordx4 v[0:3], v[0:1]
	s_nop 0
	flat_load_dwordx4 v[4:7], v[4:5]
	s_nop 0
	flat_load_dwordx4 v[8:11], v[8:9]
	s_nop 0
	flat_load_dwordx4 v[12:15], v[12:13]
	s_nop 0
	flat_load_dwordx4 v[16:19], v[16:17]
	s_nop 0
	flat_load_dwordx4 v[20:23], v[20:21]
	s_nop 0
	flat_load_dwordx4 v[24:27], v[24:25]
	s_nop 0
	flat_load_dwordx4 v[28:31], v[28:29]
	s_nop 0
	flat_load_dwordx4 v[32:35], v[34:35]
	s_nop 0
	flat_load_dwordx4 v[36:39], v[36:37]

.LBB0_777:
	v_or_b32_e32 v56, s30, v161
	v_mad_u32_u24 v162, v56, s38, 0
	v_lshl_add_u32 v163, v155, 2, v162
	v_or_b32_e32 v56, s30, v160
	ds_read_b128 v[120:123], v163
	ds_read_b128 v[128:131], v163 offset:16
	ds_read_b128 v[88:91], v163 offset:256
	ds_read_b128 v[64:67], v163 offset:272
	ds_read_b128 v[100:103], v163 offset:512
	ds_read_b128 v[76:79], v163 offset:528
	ds_read_b128 v[108:111], v163 offset:768
	ds_read_b128 v[84:87], v163 offset:784
	ds_read_b128 v[138:141], v163 offset:1024
	v_sub_u32_e32 v57, 0xff, v56
	v_cndmask_b32_e64 v56, v57, v56, s[0:1]
	v_add_u32_e32 v56, s33, v56
	v_ashrrev_i32_e32 v57, 31, v56
	s_waitcnt lgkmcnt(0)
	v_pk_mul_f32 v[146:147], v[54:55], v[122:123]
	v_pk_mul_f32 v[122:123], v[50:51], v[122:123]
	v_lshlrev_b64 v[56:57], 12, v[56:57]
	v_lshl_add_u32 v164, v156, 2, v162
	v_pk_fma_f32 v[146:147], v[52:53], v[120:121], v[146:147]
	v_pk_fma_f32 v[120:121], v[48:49], v[120:121], v[122:123]
	v_pk_mul_f32 v[122:123], v[54:55], v[140:141]
	v_pk_mul_f32 v[140:141], v[50:51], v[140:141]
	v_lshl_add_u64 v[134:135], v[132:133], 0, v[56:57]
	v_add_u32_e32 v56, 0x400, v164
	v_pk_fma_f32 v[122:123], v[52:53], v[138:139], v[122:123]
	v_pk_fma_f32 v[138:139], v[48:49], v[138:139], v[140:141]
	v_pk_fma_f32 v[140:141], v[44:45], v[128:129], v[146:147]
	v_pk_fma_f32 v[120:121], v[40:41], v[128:129], v[120:121]
	ds_read2_b64 v[56:59], v56 offset0:32 offset1:228
	ds_read_b128 v[142:145], v163 offset:1040
	ds_read_b128 v[116:119], v163 offset:1568
	ds_read_b128 v[104:107], v163 offset:1584
	ds_read_b128 v[80:83], v163 offset:1824
	ds_read_b128 v[60:63], v163 offset:1840
	ds_read_b128 v[92:95], v163 offset:2080
	ds_read_b128 v[68:71], v163 offset:2096
	ds_read_b128 v[96:99], v163 offset:2336
	ds_read_b128 v[72:75], v163 offset:2352
	ds_read_b128 v[124:127], v163 offset:2592
	ds_read_b128 v[112:115], v163 offset:2608
	ds_read_b64 v[136:137], v162 offset:3104
	s_waitcnt lgkmcnt(0)
	v_pk_fma_f32 v[128:129], v[40:41], v[142:143], v[138:139]
	v_pk_fma_f32 v[138:139], v[46:47], v[130:131], v[140:141]
	v_pk_fma_f32 v[120:121], v[42:43], v[130:131], v[120:121]
	v_add_f32_e32 v121, v120, v121
	v_add_f32_e32 v120, v138, v139
	v_pk_fma_f32 v[122:123], v[44:45], v[142:143], v[122:123]
	v_pk_fma_f32 v[128:129], v[42:43], v[144:145], v[128:129]
	v_add_f32_dpp v120, v120, v120 quad_perm:[1,0,3,2] row_mask:0xf bank_mask:0xf bound_ctrl:1
	v_add_f32_dpp v121, v121, v121 quad_perm:[1,0,3,2] row_mask:0xf bank_mask:0xf bound_ctrl:1
	v_pk_fma_f32 v[122:123], v[46:47], v[144:145], v[122:123]
	s_nop 0
	v_add_f32_dpp v120, v120, v120 quad_perm:[2,3,0,1] row_mask:0xf bank_mask:0xf bound_ctrl:1
	v_add_f32_dpp v121, v121, v121 quad_perm:[2,3,0,1] row_mask:0xf bank_mask:0xf bound_ctrl:1
	s_nop 1
	v_add_f32_dpp v120, v120, v120 row_half_mirror row_mask:0xf bank_mask:0xf bound_ctrl:1
	v_add_f32_dpp v121, v121, v121 row_half_mirror row_mask:0xf bank_mask:0xf bound_ctrl:1
	v_add_f32_e32 v122, v122, v123
	v_add_f32_e32 v123, v128, v129
	s_nop 1
	v_add_f32_dpp v122, v122, v122 quad_perm:[1,0,3,2] row_mask:0xf bank_mask:0xf bound_ctrl:1
	v_add_f32_dpp v123, v123, v123 quad_perm:[1,0,3,2] row_mask:0xf bank_mask:0xf bound_ctrl:1
	s_nop 1
	v_add_f32_dpp v122, v122, v122 quad_perm:[2,3,0,1] row_mask:0xf bank_mask:0xf bound_ctrl:1
	v_add_f32_dpp v123, v123, v123 quad_perm:[2,3,0,1] row_mask:0xf bank_mask:0xf bound_ctrl:1
	s_nop 1
	v_mov_b32_dpp v128, v122 row_half_mirror row_mask:0xf bank_mask:0xf bound_ctrl:1
	v_mov_b32_dpp v129, v123 row_half_mirror row_mask:0xf bank_mask:0xf bound_ctrl:1
	s_and_saveexec_b64 s[30:31], s[8:9]
	s_cbranch_execz .LBB0_779
	ds_read_b64 v[130:131], v162 offset:1536
	v_pk_add_f32 v[122:123], v[122:123], v[128:129]
	s_waitcnt lgkmcnt(0)
	v_pk_fma_f32 v[122:123], v[56:57], v[130:131], v[122:123] op_sel:[0,1,0]
	s_nop 0
	v_pk_fma_f32 v[122:123], v[120:121], v[130:131], v[122:123] op_sel_hi:[1,0,1] neg_lo:[1,0,0] neg_hi:[1,0,0]
	flat_store_dwordx2 v[134:135], v[122:123]
.LBB0_779:
	s_or_b64 exec, exec, s[30:31]
	v_pk_mul_f32 v[122:123], v[108:109], v[120:121] op_sel_hi:[1,0]
	v_pk_mul_f32 v[108:109], v[108:109], v[120:121] op_sel:[0,1]
	v_pk_fma_f32 v[122:123], v[100:101], v[56:57], v[122:123] op_sel_hi:[1,0,1] neg_lo:[0,0,1] neg_hi:[0,0,1]
	v_pk_fma_f32 v[100:101], v[100:101], v[56:57], v[108:109] op_sel:[0,1,0] neg_lo:[0,0,1] neg_hi:[0,0,1]
	v_pk_fma_f32 v[140:141], v[52:53], v[88:89], v[122:123]
	v_pk_mul_f32 v[52:53], v[110:111], v[120:121] op_sel_hi:[1,0]
	v_pk_fma_f32 v[48:49], v[48:49], v[88:89], v[100:101]
	v_pk_fma_f32 v[52:53], v[102:103], v[56:57], v[52:53] op_sel_hi:[1,0,1] neg_lo:[0,0,1] neg_hi:[0,0,1]
	v_pk_mul_f32 v[88:89], v[110:111], v[120:121] op_sel:[0,1]
	v_pk_fma_f32 v[144:145], v[54:55], v[90:91], v[52:53]
	v_pk_fma_f32 v[88:89], v[102:103], v[56:57], v[88:89] op_sel:[0,1,0] neg_lo:[0,0,1] neg_hi:[0,0,1]
	v_pk_mul_f32 v[52:53], v[84:85], v[120:121] op_sel_hi:[1,0]
	v_pk_fma_f32 v[50:51], v[50:51], v[90:91], v[88:89]
	v_pk_fma_f32 v[52:53], v[76:77], v[56:57], v[52:53] op_sel_hi:[1,0,1] neg_lo:[0,0,1] neg_hi:[0,0,1]
	v_pk_mul_f32 v[54:55], v[84:85], v[120:121] op_sel:[0,1]
	v_pk_fma_f32 v[146:147], v[44:45], v[64:65], v[52:53]
	v_pk_fma_f32 v[54:55], v[76:77], v[56:57], v[54:55] op_sel:[0,1,0] neg_lo:[0,0,1] neg_hi:[0,0,1]
	v_pk_mul_f32 v[44:45], v[86:87], v[120:121] op_sel_hi:[1,0]
	v_pk_mul_f32 v[52:53], v[86:87], v[120:121] op_sel:[0,1]
	v_pk_mul_f32 v[148:149], v[118:119], v[144:145]
	v_pk_mul_f32 v[118:119], v[118:119], v[50:51]
	v_pk_fma_f32 v[40:41], v[40:41], v[64:65], v[54:55]
	v_pk_fma_f32 v[44:45], v[78:79], v[56:57], v[44:45] op_sel_hi:[1,0,1] neg_lo:[0,0,1] neg_hi:[0,0,1]
	v_pk_fma_f32 v[52:53], v[78:79], v[56:57], v[52:53] op_sel:[0,1,0] neg_lo:[0,0,1] neg_hi:[0,0,1]
	v_pk_fma_f32 v[148:149], v[116:117], v[140:141], v[148:149]
	v_pk_fma_f32 v[116:117], v[116:117], v[48:49], v[118:119]
	v_pk_mul_f32 v[118:119], v[126:127], v[144:145]
	v_pk_mul_f32 v[126:127], v[126:127], v[50:51]
	v_pk_fma_f32 v[56:57], v[46:47], v[66:67], v[44:45]
	v_pk_fma_f32 v[42:43], v[42:43], v[66:67], v[52:53]
	v_pk_fma_f32 v[118:119], v[124:125], v[140:141], v[118:119]
	v_pk_fma_f32 v[124:125], v[124:125], v[48:49], v[126:127]
	v_pk_fma_f32 v[126:127], v[104:105], v[146:147], v[148:149]
	v_pk_fma_f32 v[104:105], v[104:105], v[40:41], v[116:117]
	ds_read_b128 v[100:103], v163 offset:3152
	ds_read_b128 v[76:79], v163 offset:3392
	ds_read_b128 v[44:47], v163 offset:3408
	ds_read_b128 v[84:87], v163 offset:3648
	ds_read_b128 v[52:55], v163 offset:3664
	ds_read_b128 v[88:91], v163 offset:3904
	ds_read_b128 v[64:67], v163 offset:3920
	ds_read_b128 v[120:123], v163 offset:4160
	ds_read_b128 v[108:111], v163 offset:4176
	ds_read_b64 v[138:139], v164 offset:4416
	ds_read_b128 v[128:131], v163 offset:3136
	ds_read_b64 v[142:143], v162 offset:4672
	v_pk_fma_f32 v[116:117], v[112:113], v[146:147], v[118:119]
	v_pk_fma_f32 v[112:113], v[112:113], v[40:41], v[124:125]
	v_pk_fma_f32 v[118:119], v[106:107], v[56:57], v[126:127]
	v_pk_fma_f32 v[104:105], v[106:107], v[42:43], v[104:105]
	v_pk_fma_f32 v[106:107], v[114:115], v[56:57], v[116:117]
	v_pk_fma_f32 v[112:113], v[114:115], v[42:43], v[112:113]
	v_add_f32_e32 v105, v104, v105
	v_add_f32_e32 v104, v118, v119
	s_nop 1
	v_add_f32_dpp v104, v104, v104 quad_perm:[1,0,3,2] row_mask:0xf bank_mask:0xf bound_ctrl:1
	v_add_f32_dpp v105, v105, v105 quad_perm:[1,0,3,2] row_mask:0xf bank_mask:0xf bound_ctrl:1
	s_nop 1
	v_add_f32_dpp v104, v104, v104 quad_perm:[2,3,0,1] row_mask:0xf bank_mask:0xf bound_ctrl:1
	v_add_f32_dpp v105, v105, v105 quad_perm:[2,3,0,1] row_mask:0xf bank_mask:0xf bound_ctrl:1
	s_nop 1
	v_add_f32_dpp v104, v104, v104 row_half_mirror row_mask:0xf bank_mask:0xf bound_ctrl:1
	v_add_f32_dpp v105, v105, v105 row_half_mirror row_mask:0xf bank_mask:0xf bound_ctrl:1
	v_add_f32_e32 v106, v106, v107
	v_add_f32_e32 v107, v112, v113
	s_nop 1
	v_add_f32_dpp v106, v106, v106 quad_perm:[1,0,3,2] row_mask:0xf bank_mask:0xf bound_ctrl:1
	v_add_f32_dpp v107, v107, v107 quad_perm:[1,0,3,2] row_mask:0xf bank_mask:0xf bound_ctrl:1
	s_nop 1
	v_add_f32_dpp v106, v106, v106 quad_perm:[2,3,0,1] row_mask:0xf bank_mask:0xf bound_ctrl:1
	v_add_f32_dpp v107, v107, v107 quad_perm:[2,3,0,1] row_mask:0xf bank_mask:0xf bound_ctrl:1
	s_nop 1
	v_mov_b32_dpp v112, v106 row_half_mirror row_mask:0xf bank_mask:0xf bound_ctrl:1
	v_mov_b32_dpp v113, v107 row_half_mirror row_mask:0xf bank_mask:0xf bound_ctrl:1
	s_and_saveexec_b64 s[30:31], s[8:9]
	s_cbranch_execz .LBB0_781
	v_pk_add_f32 v[106:107], v[106:107], v[112:113]
	v_lshl_add_u64 v[112:113], s[36:37], 2, v[134:135]
	v_pk_fma_f32 v[106:107], v[58:59], v[136:137], v[106:107] op_sel:[0,1,0]
	s_nop 0
	v_pk_fma_f32 v[106:107], v[136:137], v[104:105], v[106:107] op_sel_hi:[0,1,1] neg_lo:[1,0,0] neg_hi:[1,0,0]
	flat_store_dwordx2 v[112:113], v[106:107]
.LBB0_781:
	s_or_b64 exec, exec, s[30:31]
	v_pk_mul_f32 v[106:107], v[96:97], v[104:105] op_sel_hi:[1,0]
	v_pk_mul_f32 v[96:97], v[96:97], v[104:105] op_sel:[0,1]
	v_pk_fma_f32 v[106:107], v[92:93], v[58:59], v[106:107] op_sel_hi:[1,0,1] neg_lo:[0,0,1] neg_hi:[0,0,1]
	v_pk_fma_f32 v[92:93], v[92:93], v[58:59], v[96:97] op_sel:[0,1,0] neg_lo:[0,0,1] neg_hi:[0,0,1]
	v_pk_fma_f32 v[96:97], v[80:81], v[140:141], v[106:107]
	v_pk_fma_f32 v[116:117], v[80:81], v[48:49], v[92:93]
	v_pk_mul_f32 v[48:49], v[98:99], v[104:105] op_sel_hi:[1,0]
	v_pk_mul_f32 v[80:81], v[98:99], v[104:105] op_sel:[0,1]
	v_pk_fma_f32 v[48:49], v[94:95], v[58:59], v[48:49] op_sel_hi:[1,0,1] neg_lo:[0,0,1] neg_hi:[0,0,1]
	v_pk_fma_f32 v[80:81], v[94:95], v[58:59], v[80:81] op_sel:[0,1,0] neg_lo:[0,0,1] neg_hi:[0,0,1]
	v_pk_fma_f32 v[98:99], v[82:83], v[144:145], v[48:49]
	v_pk_fma_f32 v[118:119], v[82:83], v[50:51], v[80:81]
	v_pk_mul_f32 v[48:49], v[72:73], v[104:105] op_sel_hi:[1,0]
	v_pk_mul_f32 v[50:51], v[72:73], v[104:105] op_sel:[0,1]
	v_pk_fma_f32 v[48:49], v[68:69], v[58:59], v[48:49] op_sel_hi:[1,0,1] neg_lo:[0,0,1] neg_hi:[0,0,1]
	v_pk_fma_f32 v[50:51], v[68:69], v[58:59], v[50:51] op_sel:[0,1,0] neg_lo:[0,0,1] neg_hi:[0,0,1]
	v_pk_fma_f32 v[144:145], v[60:61], v[146:147], v[48:49]
	v_pk_fma_f32 v[60:61], v[60:61], v[40:41], v[50:51]
	v_pk_mul_f32 v[40:41], v[74:75], v[104:105] op_sel_hi:[1,0]
	v_pk_mul_f32 v[48:49], v[74:75], v[104:105] op_sel:[0,1]
	s_waitcnt lgkmcnt(0)
	v_pk_mul_f32 v[148:149], v[130:131], v[98:99]
	v_pk_mul_f32 v[130:131], v[130:131], v[118:119]
	v_pk_fma_f32 v[40:41], v[70:71], v[58:59], v[40:41] op_sel_hi:[1,0,1] neg_lo:[0,0,1] neg_hi:[0,0,1]
	v_pk_fma_f32 v[48:49], v[70:71], v[58:59], v[48:49] op_sel:[0,1,0] neg_lo:[0,0,1] neg_hi:[0,0,1]
	v_pk_fma_f32 v[148:149], v[128:129], v[96:97], v[148:149]
	v_pk_fma_f32 v[128:129], v[128:129], v[116:117], v[130:131]
	v_pk_mul_f32 v[130:131], v[122:123], v[98:99]
	v_pk_mul_f32 v[122:123], v[122:123], v[118:119]
	v_pk_fma_f32 v[146:147], v[62:63], v[56:57], v[40:41]
	v_pk_fma_f32 v[62:63], v[62:63], v[42:43], v[48:49]
	v_pk_fma_f32 v[130:131], v[120:121], v[96:97], v[130:131]
	v_pk_fma_f32 v[120:121], v[120:121], v[116:117], v[122:123]
	v_pk_fma_f32 v[122:123], v[100:101], v[144:145], v[148:149]
	v_pk_fma_f32 v[100:101], v[100:101], v[60:61], v[128:129]
	ds_read_b128 v[92:95], v163 offset:4720
	ds_read_b128 v[68:71], v163 offset:4960
	ds_read_b128 v[40:43], v163 offset:4976
	ds_read_b128 v[72:75], v163 offset:5216
	ds_read_b128 v[48:51], v163 offset:5232
	ds_read_b128 v[80:83], v163 offset:5472
	ds_read_b128 v[56:59], v163 offset:5488
	ds_read_b128 v[112:115], v163 offset:5728
	ds_read_b128 v[104:107], v163 offset:5744
	ds_read_b64 v[136:137], v164 offset:5984
	ds_read_b128 v[124:127], v163 offset:4704
	ds_read_b64 v[140:141], v162 offset:6240
	v_pk_fma_f32 v[128:129], v[108:109], v[144:145], v[130:131]
	v_pk_fma_f32 v[108:109], v[108:109], v[60:61], v[120:121]
	v_pk_fma_f32 v[120:121], v[102:103], v[146:147], v[122:123]
	v_pk_fma_f32 v[100:101], v[102:103], v[62:63], v[100:101]
	v_pk_fma_f32 v[102:103], v[110:111], v[146:147], v[128:129]
	v_pk_fma_f32 v[110:111], v[110:111], v[62:63], v[108:109]
	v_add_f32_e32 v101, v100, v101
	v_add_f32_e32 v100, v120, v121
	s_nop 1
	v_add_f32_dpp v100, v100, v100 quad_perm:[1,0,3,2] row_mask:0xf bank_mask:0xf bound_ctrl:1
	v_add_f32_dpp v101, v101, v101 quad_perm:[1,0,3,2] row_mask:0xf bank_mask:0xf bound_ctrl:1
	s_nop 1
	v_add_f32_dpp v100, v100, v100 quad_perm:[2,3,0,1] row_mask:0xf bank_mask:0xf bound_ctrl:1
	v_add_f32_dpp v101, v101, v101 quad_perm:[2,3,0,1] row_mask:0xf bank_mask:0xf bound_ctrl:1
	s_nop 1
	v_mov_b32_dpp v108, v100 row_half_mirror row_mask:0xf bank_mask:0xf bound_ctrl:1
	v_mov_b32_dpp v109, v101 row_half_mirror row_mask:0xf bank_mask:0xf bound_ctrl:1
	v_pk_add_f32 v[108:109], v[100:101], v[108:109]
	v_add_f32_e32 v100, v102, v103
	v_add_f32_e32 v101, v110, v111
	s_nop 1
	v_add_f32_dpp v100, v100, v100 quad_perm:[1,0,3,2] row_mask:0xf bank_mask:0xf bound_ctrl:1
	v_add_f32_dpp v101, v101, v101 quad_perm:[1,0,3,2] row_mask:0xf bank_mask:0xf bound_ctrl:1
	s_nop 1
	v_add_f32_dpp v100, v100, v100 quad_perm:[2,3,0,1] row_mask:0xf bank_mask:0xf bound_ctrl:1
	v_add_f32_dpp v101, v101, v101 quad_perm:[2,3,0,1] row_mask:0xf bank_mask:0xf bound_ctrl:1
	s_nop 1
	v_mov_b32_dpp v102, v100 row_half_mirror row_mask:0xf bank_mask:0xf bound_ctrl:1
	v_mov_b32_dpp v103, v101 row_half_mirror row_mask:0xf bank_mask:0xf bound_ctrl:1
	s_and_saveexec_b64 s[30:31], s[8:9]
	s_cbranch_execz .LBB0_783
	v_pk_add_f32 v[100:101], v[100:101], v[102:103]
	v_readlane_b32 s60, v253, 2
	v_pk_fma_f32 v[100:101], v[138:139], v[142:143], v[100:101] op_sel:[0,1,0]
	v_readlane_b32 s61, v253, 3
	v_pk_fma_f32 v[100:101], v[142:143], v[108:109], v[100:101] op_sel_hi:[0,1,1] neg_lo:[1,0,0] neg_hi:[1,0,0]
	s_nop 0
	v_lshl_add_u64 v[102:103], v[134:135], 0, s[60:61]
	flat_store_dwordx2 v[102:103], v[100:101]
.LBB0_783:
	s_or_b64 exec, exec, s[30:31]
	v_pk_mul_f32 v[100:101], v[88:89], v[108:109] op_sel_hi:[1,0]
	v_pk_mul_f32 v[88:89], v[88:89], v[108:109] op_sel:[0,1]
	v_pk_fma_f32 v[100:101], v[84:85], v[138:139], v[100:101] op_sel_hi:[1,0,1] neg_lo:[0,0,1] neg_hi:[0,0,1]
	v_pk_fma_f32 v[84:85], v[84:85], v[138:139], v[88:89] op_sel:[0,1,0] neg_lo:[0,0,1] neg_hi:[0,0,1]
	v_pk_fma_f32 v[88:89], v[76:77], v[96:97], v[100:101]
	v_pk_fma_f32 v[100:101], v[76:77], v[116:117], v[84:85]
	v_pk_mul_f32 v[76:77], v[90:91], v[108:109] op_sel_hi:[1,0]
	v_pk_mul_f32 v[84:85], v[90:91], v[108:109] op_sel:[0,1]
	v_pk_fma_f32 v[76:77], v[86:87], v[138:139], v[76:77] op_sel_hi:[1,0,1] neg_lo:[0,0,1] neg_hi:[0,0,1]
	v_pk_fma_f32 v[84:85], v[86:87], v[138:139], v[84:85] op_sel:[0,1,0] neg_lo:[0,0,1] neg_hi:[0,0,1]
	v_pk_fma_f32 v[90:91], v[78:79], v[98:99], v[76:77]
	v_pk_mul_f32 v[76:77], v[64:65], v[108:109] op_sel_hi:[1,0]
	v_pk_mul_f32 v[64:65], v[64:65], v[108:109] op_sel:[0,1]
	v_pk_fma_f32 v[102:103], v[78:79], v[118:119], v[84:85]
	v_pk_fma_f32 v[76:77], v[52:53], v[138:139], v[76:77] op_sel_hi:[1,0,1] neg_lo:[0,0,1] neg_hi:[0,0,1]
	v_pk_fma_f32 v[52:53], v[52:53], v[138:139], v[64:65] op_sel:[0,1,0] neg_lo:[0,0,1] neg_hi:[0,0,1]
	v_pk_fma_f32 v[130:131], v[44:45], v[144:145], v[76:77]
	v_pk_fma_f32 v[142:143], v[44:45], v[60:61], v[52:53]
	v_pk_mul_f32 v[44:45], v[66:67], v[108:109] op_sel_hi:[1,0]
	v_pk_mul_f32 v[52:53], v[66:67], v[108:109] op_sel:[0,1]
	s_waitcnt lgkmcnt(0)
	v_pk_mul_f32 v[148:149], v[126:127], v[90:91]
	v_pk_mul_f32 v[126:127], v[126:127], v[102:103]
	v_pk_fma_f32 v[44:45], v[54:55], v[138:139], v[44:45] op_sel_hi:[1,0,1] neg_lo:[0,0,1] neg_hi:[0,0,1]
	v_pk_fma_f32 v[52:53], v[54:55], v[138:139], v[52:53] op_sel:[0,1,0] neg_lo:[0,0,1] neg_hi:[0,0,1]
	v_pk_fma_f32 v[148:149], v[124:125], v[88:89], v[148:149]
	v_pk_fma_f32 v[124:125], v[124:125], v[100:101], v[126:127]
	v_pk_mul_f32 v[126:127], v[114:115], v[90:91]
	v_pk_mul_f32 v[114:115], v[114:115], v[102:103]
	v_pk_fma_f32 v[144:145], v[46:47], v[146:147], v[44:45]
	v_pk_fma_f32 v[146:147], v[46:47], v[62:63], v[52:53]
	v_pk_fma_f32 v[126:127], v[112:113], v[88:89], v[126:127]
	v_pk_fma_f32 v[112:113], v[112:113], v[100:101], v[114:115]
	v_pk_fma_f32 v[114:115], v[92:93], v[130:131], v[148:149]
	v_pk_fma_f32 v[92:93], v[92:93], v[142:143], v[124:125]
	ds_read_b128 v[96:99], v163 offset:6288
	ds_read_b128 v[64:67], v163 offset:6528
	ds_read_b128 v[44:47], v163 offset:6544
	ds_read_b128 v[76:79], v163 offset:6784
	ds_read_b128 v[52:55], v163 offset:6800
	ds_read_b128 v[84:87], v163 offset:7040
	ds_read_b128 v[60:63], v163 offset:7056
	ds_read_b128 v[116:119], v163 offset:7296
	ds_read_b128 v[108:111], v163 offset:7312
	ds_read_b64 v[128:129], v164 offset:7552
	ds_read_b128 v[120:123], v163 offset:6272
	ds_read_b64 v[138:139], v162 offset:7808
	v_pk_fma_f32 v[124:125], v[104:105], v[130:131], v[126:127]
	v_pk_fma_f32 v[104:105], v[104:105], v[142:143], v[112:113]
	v_pk_fma_f32 v[112:113], v[94:95], v[144:145], v[114:115]
	v_pk_fma_f32 v[92:93], v[94:95], v[146:147], v[92:93]
	v_pk_fma_f32 v[94:95], v[106:107], v[144:145], v[124:125]
	v_pk_fma_f32 v[106:107], v[106:107], v[146:147], v[104:105]
	v_add_f32_e32 v93, v92, v93
	v_add_f32_e32 v92, v112, v113
	s_nop 1
	v_add_f32_dpp v92, v92, v92 quad_perm:[1,0,3,2] row_mask:0xf bank_mask:0xf bound_ctrl:1
	v_add_f32_dpp v93, v93, v93 quad_perm:[1,0,3,2] row_mask:0xf bank_mask:0xf bound_ctrl:1
	s_nop 1
	v_add_f32_dpp v92, v92, v92 quad_perm:[2,3,0,1] row_mask:0xf bank_mask:0xf bound_ctrl:1
	v_add_f32_dpp v93, v93, v93 quad_perm:[2,3,0,1] row_mask:0xf bank_mask:0xf bound_ctrl:1
	s_nop 1
	v_mov_b32_dpp v104, v92 row_half_mirror row_mask:0xf bank_mask:0xf bound_ctrl:1
	v_mov_b32_dpp v105, v93 row_half_mirror row_mask:0xf bank_mask:0xf bound_ctrl:1
	v_pk_add_f32 v[104:105], v[92:93], v[104:105]
	v_add_f32_e32 v92, v94, v95
	v_add_f32_e32 v93, v106, v107
	s_nop 1
	v_add_f32_dpp v92, v92, v92 quad_perm:[1,0,3,2] row_mask:0xf bank_mask:0xf bound_ctrl:1
	v_add_f32_dpp v93, v93, v93 quad_perm:[1,0,3,2] row_mask:0xf bank_mask:0xf bound_ctrl:1
	s_nop 1
	v_add_f32_dpp v92, v92, v92 quad_perm:[2,3,0,1] row_mask:0xf bank_mask:0xf bound_ctrl:1
	v_add_f32_dpp v93, v93, v93 quad_perm:[2,3,0,1] row_mask:0xf bank_mask:0xf bound_ctrl:1
	s_nop 1
	v_mov_b32_dpp v94, v92 row_half_mirror row_mask:0xf bank_mask:0xf bound_ctrl:1
	v_mov_b32_dpp v95, v93 row_half_mirror row_mask:0xf bank_mask:0xf bound_ctrl:1
	s_and_saveexec_b64 s[30:31], s[8:9]
	s_cbranch_execz .LBB0_785
	v_pk_add_f32 v[92:93], v[92:93], v[94:95]
	v_readlane_b32 s60, v253, 58
	v_pk_fma_f32 v[92:93], v[136:137], v[140:141], v[92:93] op_sel:[0,1,0]
	v_readlane_b32 s61, v253, 59
	v_pk_fma_f32 v[92:93], v[140:141], v[104:105], v[92:93] op_sel_hi:[0,1,1] neg_lo:[1,0,0] neg_hi:[1,0,0]
	s_nop 0
	v_lshl_add_u64 v[94:95], v[134:135], 0, s[60:61]
	flat_store_dwordx2 v[94:95], v[92:93]
.LBB0_785:
	s_or_b64 exec, exec, s[30:31]
	v_pk_mul_f32 v[92:93], v[80:81], v[104:105] op_sel_hi:[1,0]
	v_pk_mul_f32 v[80:81], v[80:81], v[104:105] op_sel:[0,1]
	v_pk_fma_f32 v[92:93], v[72:73], v[136:137], v[92:93] op_sel_hi:[1,0,1] neg_lo:[0,0,1] neg_hi:[0,0,1]
	v_pk_fma_f32 v[80:81], v[72:73], v[136:137], v[80:81] op_sel:[0,1,0] neg_lo:[0,0,1] neg_hi:[0,0,1]
	v_pk_fma_f32 v[72:73], v[68:69], v[88:89], v[92:93]
	v_pk_fma_f32 v[92:93], v[68:69], v[100:101], v[80:81]
	v_pk_mul_f32 v[68:69], v[82:83], v[104:105] op_sel_hi:[1,0]
	v_pk_mul_f32 v[80:81], v[82:83], v[104:105] op_sel:[0,1]
	v_pk_fma_f32 v[68:69], v[74:75], v[136:137], v[68:69] op_sel_hi:[1,0,1] neg_lo:[0,0,1] neg_hi:[0,0,1]
	v_pk_fma_f32 v[80:81], v[74:75], v[136:137], v[80:81] op_sel:[0,1,0] neg_lo:[0,0,1] neg_hi:[0,0,1]
	v_pk_fma_f32 v[74:75], v[70:71], v[90:91], v[68:69]
	v_pk_mul_f32 v[68:69], v[56:57], v[104:105] op_sel_hi:[1,0]
	v_pk_mul_f32 v[56:57], v[56:57], v[104:105] op_sel:[0,1]
	v_pk_fma_f32 v[94:95], v[70:71], v[102:103], v[80:81]
	v_pk_fma_f32 v[68:69], v[48:49], v[136:137], v[68:69] op_sel_hi:[1,0,1] neg_lo:[0,0,1] neg_hi:[0,0,1]
	v_pk_fma_f32 v[48:49], v[48:49], v[136:137], v[56:57] op_sel:[0,1,0] neg_lo:[0,0,1] neg_hi:[0,0,1]
	v_pk_fma_f32 v[140:141], v[40:41], v[130:131], v[68:69]
	v_pk_fma_f32 v[142:143], v[40:41], v[142:143], v[48:49]
	v_pk_mul_f32 v[40:41], v[58:59], v[104:105] op_sel_hi:[1,0]
	v_pk_mul_f32 v[48:49], v[58:59], v[104:105] op_sel:[0,1]
	s_waitcnt lgkmcnt(0)
	v_pk_mul_f32 v[148:149], v[122:123], v[74:75]
	v_pk_mul_f32 v[122:123], v[122:123], v[94:95]
	v_pk_fma_f32 v[40:41], v[50:51], v[136:137], v[40:41] op_sel_hi:[1,0,1] neg_lo:[0,0,1] neg_hi:[0,0,1]
	v_pk_fma_f32 v[48:49], v[50:51], v[136:137], v[48:49] op_sel:[0,1,0] neg_lo:[0,0,1] neg_hi:[0,0,1]
	v_pk_fma_f32 v[148:149], v[120:121], v[72:73], v[148:149]
	v_pk_fma_f32 v[120:121], v[120:121], v[92:93], v[122:123]
	v_pk_mul_f32 v[122:123], v[118:119], v[74:75]
	v_pk_mul_f32 v[118:119], v[118:119], v[94:95]
	v_pk_fma_f32 v[144:145], v[42:43], v[144:145], v[40:41]
	v_pk_fma_f32 v[146:147], v[42:43], v[146:147], v[48:49]
	v_pk_fma_f32 v[122:123], v[116:117], v[72:73], v[122:123]
	v_pk_fma_f32 v[116:117], v[116:117], v[92:93], v[118:119]
	v_pk_fma_f32 v[118:119], v[96:97], v[140:141], v[148:149]
	v_pk_fma_f32 v[96:97], v[96:97], v[142:143], v[120:121]
	ds_read_b128 v[100:103], v163 offset:7856
	ds_read_b128 v[68:71], v163 offset:8096
	ds_read_b128 v[40:43], v163 offset:8112
	ds_read_b128 v[80:83], v163 offset:8352
	ds_read_b128 v[48:51], v163 offset:8368
	ds_read_b128 v[88:91], v163 offset:8608
	ds_read_b128 v[56:59], v163 offset:8624
	ds_read_b128 v[112:115], v163 offset:8864
	ds_read_b128 v[104:107], v163 offset:8880
	ds_read_b64 v[130:131], v164 offset:9120
	ds_read_b128 v[124:127], v163 offset:7840
	ds_read_b64 v[136:137], v162 offset:9376
	v_pk_fma_f32 v[120:121], v[108:109], v[140:141], v[122:123]
	v_pk_fma_f32 v[108:109], v[108:109], v[142:143], v[116:117]
	v_pk_fma_f32 v[116:117], v[98:99], v[144:145], v[118:119]
	v_pk_fma_f32 v[96:97], v[98:99], v[146:147], v[96:97]
	v_pk_fma_f32 v[98:99], v[110:111], v[144:145], v[120:121]
	v_pk_fma_f32 v[108:109], v[110:111], v[146:147], v[108:109]
	v_add_f32_e32 v97, v96, v97
	v_add_f32_e32 v96, v116, v117
	s_nop 1
	v_add_f32_dpp v96, v96, v96 quad_perm:[1,0,3,2] row_mask:0xf bank_mask:0xf bound_ctrl:1
	v_add_f32_dpp v97, v97, v97 quad_perm:[1,0,3,2] row_mask:0xf bank_mask:0xf bound_ctrl:1
	s_nop 1
	v_add_f32_dpp v96, v96, v96 quad_perm:[2,3,0,1] row_mask:0xf bank_mask:0xf bound_ctrl:1
	v_add_f32_dpp v97, v97, v97 quad_perm:[2,3,0,1] row_mask:0xf bank_mask:0xf bound_ctrl:1
	s_nop 1
	v_add_f32_dpp v96, v96, v96 row_half_mirror row_mask:0xf bank_mask:0xf bound_ctrl:1
	v_add_f32_dpp v97, v97, v97 row_half_mirror row_mask:0xf bank_mask:0xf bound_ctrl:1
	v_add_f32_e32 v98, v98, v99
	v_add_f32_e32 v99, v108, v109
	s_nop 1
	v_add_f32_dpp v98, v98, v98 quad_perm:[1,0,3,2] row_mask:0xf bank_mask:0xf bound_ctrl:1
	v_add_f32_dpp v99, v99, v99 quad_perm:[1,0,3,2] row_mask:0xf bank_mask:0xf bound_ctrl:1
	s_nop 1
	v_add_f32_dpp v98, v98, v98 quad_perm:[2,3,0,1] row_mask:0xf bank_mask:0xf bound_ctrl:1
	v_add_f32_dpp v99, v99, v99 quad_perm:[2,3,0,1] row_mask:0xf bank_mask:0xf bound_ctrl:1
	s_nop 1
	v_mov_b32_dpp v108, v98 row_half_mirror row_mask:0xf bank_mask:0xf bound_ctrl:1
	v_mov_b32_dpp v109, v99 row_half_mirror row_mask:0xf bank_mask:0xf bound_ctrl:1
	s_and_saveexec_b64 s[30:31], s[8:9]
	s_cbranch_execz .LBB0_787
	v_pk_add_f32 v[98:99], v[98:99], v[108:109]
	v_readlane_b32 s60, v253, 4
	v_pk_fma_f32 v[98:99], v[128:129], v[138:139], v[98:99] op_sel:[0,1,0]
	v_readlane_b32 s61, v253, 5
	v_pk_fma_f32 v[98:99], v[138:139], v[96:97], v[98:99] op_sel_hi:[0,1,1] neg_lo:[1,0,0] neg_hi:[1,0,0]
	s_nop 0
	v_lshl_add_u64 v[108:109], v[134:135], 0, s[60:61]
	flat_store_dwordx2 v[108:109], v[98:99]
.LBB0_787:
	s_or_b64 exec, exec, s[30:31]
	v_pk_mul_f32 v[98:99], v[84:85], v[96:97] op_sel_hi:[1,0]
	v_pk_mul_f32 v[84:85], v[84:85], v[96:97] op_sel:[0,1]
	v_pk_fma_f32 v[98:99], v[76:77], v[128:129], v[98:99] op_sel_hi:[1,0,1] neg_lo:[0,0,1] neg_hi:[0,0,1]
	v_pk_fma_f32 v[84:85], v[76:77], v[128:129], v[84:85] op_sel:[0,1,0] neg_lo:[0,0,1] neg_hi:[0,0,1]
	v_pk_fma_f32 v[76:77], v[64:65], v[72:73], v[98:99]
	v_pk_mul_f32 v[72:73], v[86:87], v[96:97] op_sel_hi:[1,0]
	v_pk_fma_f32 v[64:65], v[64:65], v[92:93], v[84:85]
	v_pk_fma_f32 v[72:73], v[78:79], v[128:129], v[72:73] op_sel_hi:[1,0,1] neg_lo:[0,0,1] neg_hi:[0,0,1]
	v_pk_mul_f32 v[84:85], v[86:87], v[96:97] op_sel:[0,1]
	s_nop 0
	v_pk_fma_f32 v[84:85], v[78:79], v[128:129], v[84:85] op_sel:[0,1,0] neg_lo:[0,0,1] neg_hi:[0,0,1]
	v_pk_fma_f32 v[78:79], v[66:67], v[74:75], v[72:73]
	v_pk_mul_f32 v[72:73], v[60:61], v[96:97] op_sel_hi:[1,0]
	v_pk_mul_f32 v[60:61], v[60:61], v[96:97] op_sel:[0,1]
	v_pk_fma_f32 v[66:67], v[66:67], v[94:95], v[84:85]
	v_pk_fma_f32 v[72:73], v[52:53], v[128:129], v[72:73] op_sel_hi:[1,0,1] neg_lo:[0,0,1] neg_hi:[0,0,1]
	v_pk_fma_f32 v[52:53], v[52:53], v[128:129], v[60:61] op_sel:[0,1,0] neg_lo:[0,0,1] neg_hi:[0,0,1]
	v_pk_fma_f32 v[140:141], v[44:45], v[140:141], v[72:73]
	v_pk_fma_f32 v[142:143], v[44:45], v[142:143], v[52:53]
	v_pk_mul_f32 v[44:45], v[62:63], v[96:97] op_sel_hi:[1,0]
	v_pk_mul_f32 v[52:53], v[62:63], v[96:97] op_sel:[0,1]
	s_waitcnt lgkmcnt(0)
	v_pk_mul_f32 v[148:149], v[126:127], v[78:79]
	v_pk_mul_f32 v[126:127], v[126:127], v[66:67]
	v_pk_fma_f32 v[44:45], v[54:55], v[128:129], v[44:45] op_sel_hi:[1,0,1] neg_lo:[0,0,1] neg_hi:[0,0,1]
	v_pk_fma_f32 v[52:53], v[54:55], v[128:129], v[52:53] op_sel:[0,1,0] neg_lo:[0,0,1] neg_hi:[0,0,1]
	v_pk_fma_f32 v[148:149], v[124:125], v[76:77], v[148:149]
	v_pk_fma_f32 v[124:125], v[124:125], v[64:65], v[126:127]
	v_pk_mul_f32 v[126:127], v[114:115], v[78:79]
	v_pk_mul_f32 v[114:115], v[114:115], v[66:67]
	v_pk_fma_f32 v[144:145], v[46:47], v[144:145], v[44:45]
	v_pk_fma_f32 v[146:147], v[46:47], v[146:147], v[52:53]
	v_pk_fma_f32 v[126:127], v[112:113], v[76:77], v[126:127]
	v_pk_fma_f32 v[112:113], v[112:113], v[64:65], v[114:115]
	v_pk_fma_f32 v[114:115], v[100:101], v[140:141], v[148:149]
	v_pk_fma_f32 v[100:101], v[100:101], v[142:143], v[124:125]
	ds_read_b128 v[96:99], v163 offset:9424
	ds_read_b128 v[72:75], v163 offset:9664
	ds_read_b128 v[44:47], v163 offset:9680
	ds_read_b128 v[84:87], v163 offset:9920
	ds_read_b128 v[52:55], v163 offset:9936
	ds_read_b128 v[92:95], v163 offset:10176
	ds_read_b128 v[60:63], v163 offset:10192
	ds_read_b128 v[116:119], v163 offset:10432
	ds_read_b128 v[108:111], v163 offset:10448
	ds_read_b64 v[128:129], v164 offset:10688
	ds_read_b128 v[120:123], v163 offset:9408
	ds_read_b64 v[138:139], v162 offset:10944
	v_pk_fma_f32 v[124:125], v[104:105], v[140:141], v[126:127]
	v_pk_fma_f32 v[104:105], v[104:105], v[142:143], v[112:113]
	v_pk_fma_f32 v[112:113], v[102:103], v[144:145], v[114:115]
	v_pk_fma_f32 v[100:101], v[102:103], v[146:147], v[100:101]
	v_pk_fma_f32 v[102:103], v[106:107], v[144:145], v[124:125]
	v_pk_fma_f32 v[104:105], v[106:107], v[146:147], v[104:105]
	v_add_f32_e32 v101, v100, v101
	v_add_f32_e32 v100, v112, v113
	s_nop 1
	v_add_f32_dpp v100, v100, v100 quad_perm:[1,0,3,2] row_mask:0xf bank_mask:0xf bound_ctrl:1
	v_add_f32_dpp v101, v101, v101 quad_perm:[1,0,3,2] row_mask:0xf bank_mask:0xf bound_ctrl:1
	s_nop 1
	v_add_f32_dpp v100, v100, v100 quad_perm:[2,3,0,1] row_mask:0xf bank_mask:0xf bound_ctrl:1
	v_add_f32_dpp v101, v101, v101 quad_perm:[2,3,0,1] row_mask:0xf bank_mask:0xf bound_ctrl:1
	s_nop 1
	v_add_f32_dpp v100, v100, v100 row_half_mirror row_mask:0xf bank_mask:0xf bound_ctrl:1
	v_add_f32_dpp v101, v101, v101 row_half_mirror row_mask:0xf bank_mask:0xf bound_ctrl:1
	v_add_f32_e32 v102, v102, v103
	v_add_f32_e32 v103, v104, v105
	s_nop 1
	v_add_f32_dpp v102, v102, v102 quad_perm:[1,0,3,2] row_mask:0xf bank_mask:0xf bound_ctrl:1
	v_add_f32_dpp v103, v103, v103 quad_perm:[1,0,3,2] row_mask:0xf bank_mask:0xf bound_ctrl:1
	s_nop 1
	v_add_f32_dpp v102, v102, v102 quad_perm:[2,3,0,1] row_mask:0xf bank_mask:0xf bound_ctrl:1
	v_add_f32_dpp v103, v103, v103 quad_perm:[2,3,0,1] row_mask:0xf bank_mask:0xf bound_ctrl:1
	s_nop 1
	v_mov_b32_dpp v104, v102 row_half_mirror row_mask:0xf bank_mask:0xf bound_ctrl:1
	v_mov_b32_dpp v105, v103 row_half_mirror row_mask:0xf bank_mask:0xf bound_ctrl:1
	s_and_saveexec_b64 s[30:31], s[8:9]
	s_cbranch_execz .LBB0_789
	v_pk_add_f32 v[102:103], v[102:103], v[104:105]
	v_readlane_b32 s60, v253, 60
	v_pk_fma_f32 v[102:103], v[130:131], v[136:137], v[102:103] op_sel:[0,1,0]
	v_readlane_b32 s61, v253, 61
	v_pk_fma_f32 v[102:103], v[136:137], v[100:101], v[102:103] op_sel_hi:[0,1,1] neg_lo:[1,0,0] neg_hi:[1,0,0]
	s_nop 0
	v_lshl_add_u64 v[104:105], v[134:135], 0, s[60:61]
	flat_store_dwordx2 v[104:105], v[102:103]
.LBB0_789:
	s_or_b64 exec, exec, s[30:31]
	v_pk_mul_f32 v[102:103], v[88:89], v[100:101] op_sel_hi:[1,0]
	v_pk_mul_f32 v[88:89], v[88:89], v[100:101] op_sel:[0,1]
	v_pk_fma_f32 v[102:103], v[80:81], v[130:131], v[102:103] op_sel_hi:[1,0,1] neg_lo:[0,0,1] neg_hi:[0,0,1]
	v_pk_fma_f32 v[80:81], v[80:81], v[130:131], v[88:89] op_sel:[0,1,0] neg_lo:[0,0,1] neg_hi:[0,0,1]
	v_pk_fma_f32 v[148:149], v[68:69], v[76:77], v[102:103]
	v_pk_fma_f32 v[68:69], v[68:69], v[64:65], v[80:81]
	v_pk_mul_f32 v[64:65], v[90:91], v[100:101] op_sel_hi:[1,0]
	v_pk_mul_f32 v[76:77], v[90:91], v[100:101] op_sel:[0,1]
	v_pk_fma_f32 v[64:65], v[82:83], v[130:131], v[64:65] op_sel_hi:[1,0,1] neg_lo:[0,0,1] neg_hi:[0,0,1]
	v_pk_fma_f32 v[76:77], v[82:83], v[130:131], v[76:77] op_sel:[0,1,0] neg_lo:[0,0,1] neg_hi:[0,0,1]
	v_pk_fma_f32 v[150:151], v[70:71], v[78:79], v[64:65]
	v_pk_mul_f32 v[64:65], v[56:57], v[100:101] op_sel_hi:[1,0]
	v_pk_mul_f32 v[56:57], v[56:57], v[100:101] op_sel:[0,1]
	v_pk_fma_f32 v[64:65], v[48:49], v[130:131], v[64:65] op_sel_hi:[1,0,1] neg_lo:[0,0,1] neg_hi:[0,0,1]
	v_pk_fma_f32 v[48:49], v[48:49], v[130:131], v[56:57] op_sel:[0,1,0] neg_lo:[0,0,1] neg_hi:[0,0,1]
	v_pk_fma_f32 v[140:141], v[40:41], v[140:141], v[64:65]
	v_pk_fma_f32 v[40:41], v[40:41], v[142:143], v[48:49]
	v_pk_mul_f32 v[48:49], v[58:59], v[100:101] op_sel_hi:[1,0]
	v_pk_fma_f32 v[70:71], v[70:71], v[66:67], v[76:77]
	v_pk_fma_f32 v[48:49], v[50:51], v[130:131], v[48:49] op_sel_hi:[1,0,1] neg_lo:[0,0,1] neg_hi:[0,0,1]
	v_pk_mul_f32 v[56:57], v[58:59], v[100:101] op_sel:[0,1]
	v_pk_fma_f32 v[142:143], v[42:43], v[144:145], v[48:49]
	s_waitcnt lgkmcnt(0)
	v_pk_mul_f32 v[144:145], v[122:123], v[150:151]
	v_pk_mul_f32 v[122:123], v[122:123], v[70:71]
	v_pk_fma_f32 v[50:51], v[50:51], v[130:131], v[56:57] op_sel:[0,1,0] neg_lo:[0,0,1] neg_hi:[0,0,1]
	v_pk_fma_f32 v[144:145], v[120:121], v[148:149], v[144:145]
	v_pk_fma_f32 v[120:121], v[120:121], v[68:69], v[122:123]
	v_pk_mul_f32 v[122:123], v[118:119], v[150:151]
	v_pk_mul_f32 v[118:119], v[118:119], v[70:71]
	v_pk_fma_f32 v[42:43], v[42:43], v[146:147], v[50:51]
	v_pk_fma_f32 v[122:123], v[116:117], v[148:149], v[122:123]
	v_pk_fma_f32 v[116:117], v[116:117], v[68:69], v[118:119]
	v_pk_fma_f32 v[118:119], v[96:97], v[140:141], v[144:145]
	v_pk_fma_f32 v[96:97], v[96:97], v[40:41], v[120:121]
	ds_read_b128 v[100:103], v163 offset:10992
	ds_read_b128 v[76:79], v163 offset:11232
	ds_read_b128 v[48:51], v163 offset:11248
	ds_read_b128 v[80:83], v163 offset:11488
	ds_read_b128 v[56:59], v163 offset:11504
	ds_read_b128 v[88:91], v163 offset:11744
	ds_read_b128 v[64:67], v163 offset:11760
	ds_read_b128 v[112:115], v163 offset:12000
	ds_read_b128 v[104:107], v163 offset:12016
	ds_read_b64 v[130:131], v164 offset:12256
	ds_read_b128 v[124:127], v163 offset:10976
	ds_read_b64 v[136:137], v162 offset:12512
	v_pk_fma_f32 v[120:121], v[108:109], v[140:141], v[122:123]
	v_pk_fma_f32 v[108:109], v[108:109], v[40:41], v[116:117]
	v_pk_fma_f32 v[116:117], v[98:99], v[142:143], v[118:119]
	v_pk_fma_f32 v[96:97], v[98:99], v[42:43], v[96:97]
	v_pk_fma_f32 v[98:99], v[110:111], v[142:143], v[120:121]
	v_pk_fma_f32 v[110:111], v[110:111], v[42:43], v[108:109]
	v_add_f32_e32 v97, v96, v97
	v_add_f32_e32 v96, v116, v117
	s_nop 1
	v_add_f32_dpp v96, v96, v96 quad_perm:[1,0,3,2] row_mask:0xf bank_mask:0xf bound_ctrl:1
	v_add_f32_dpp v97, v97, v97 quad_perm:[1,0,3,2] row_mask:0xf bank_mask:0xf bound_ctrl:1
	s_nop 1
	v_add_f32_dpp v96, v96, v96 quad_perm:[2,3,0,1] row_mask:0xf bank_mask:0xf bound_ctrl:1
	v_add_f32_dpp v97, v97, v97 quad_perm:[2,3,0,1] row_mask:0xf bank_mask:0xf bound_ctrl:1
	s_nop 1
	v_mov_b32_dpp v108, v96 row_half_mirror row_mask:0xf bank_mask:0xf bound_ctrl:1
	v_mov_b32_dpp v109, v97 row_half_mirror row_mask:0xf bank_mask:0xf bound_ctrl:1
	v_pk_add_f32 v[108:109], v[96:97], v[108:109]
	v_add_f32_e32 v96, v98, v99
	v_add_f32_e32 v97, v110, v111
	s_nop 1
	v_add_f32_dpp v96, v96, v96 quad_perm:[1,0,3,2] row_mask:0xf bank_mask:0xf bound_ctrl:1
	v_add_f32_dpp v97, v97, v97 quad_perm:[1,0,3,2] row_mask:0xf bank_mask:0xf bound_ctrl:1
	s_nop 1
	v_add_f32_dpp v96, v96, v96 quad_perm:[2,3,0,1] row_mask:0xf bank_mask:0xf bound_ctrl:1
	v_add_f32_dpp v97, v97, v97 quad_perm:[2,3,0,1] row_mask:0xf bank_mask:0xf bound_ctrl:1
	s_nop 1
	v_mov_b32_dpp v98, v96 row_half_mirror row_mask:0xf bank_mask:0xf bound_ctrl:1
	v_mov_b32_dpp v99, v97 row_half_mirror row_mask:0xf bank_mask:0xf bound_ctrl:1
	s_and_saveexec_b64 s[30:31], s[8:9]
	s_cbranch_execz .LBB0_791
	v_pk_add_f32 v[96:97], v[96:97], v[98:99]
	v_lshl_add_u64 v[98:99], v[134:135], 0, s[90:91]
	v_pk_fma_f32 v[96:97], v[128:129], v[138:139], v[96:97] op_sel:[0,1,0]
	s_nop 0
	v_pk_fma_f32 v[96:97], v[138:139], v[108:109], v[96:97] op_sel_hi:[0,1,1] neg_lo:[1,0,0] neg_hi:[1,0,0]
	flat_store_dwordx2 v[98:99], v[96:97]
.LBB0_791:
	s_or_b64 exec, exec, s[30:31]
	v_pk_mul_f32 v[96:97], v[92:93], v[108:109] op_sel_hi:[1,0]
	v_pk_mul_f32 v[92:93], v[92:93], v[108:109] op_sel:[0,1]
	v_pk_fma_f32 v[96:97], v[84:85], v[128:129], v[96:97] op_sel_hi:[1,0,1] neg_lo:[0,0,1] neg_hi:[0,0,1]
	v_pk_fma_f32 v[84:85], v[84:85], v[128:129], v[92:93] op_sel:[0,1,0] neg_lo:[0,0,1] neg_hi:[0,0,1]
	v_pk_fma_f32 v[96:97], v[72:73], v[148:149], v[96:97]
	v_pk_fma_f32 v[98:99], v[72:73], v[68:69], v[84:85]
	v_pk_mul_f32 v[68:69], v[94:95], v[108:109] op_sel_hi:[1,0]
	v_pk_mul_f32 v[72:73], v[94:95], v[108:109] op_sel:[0,1]
	v_pk_fma_f32 v[68:69], v[86:87], v[128:129], v[68:69] op_sel_hi:[1,0,1] neg_lo:[0,0,1] neg_hi:[0,0,1]
	v_pk_fma_f32 v[72:73], v[86:87], v[128:129], v[72:73] op_sel:[0,1,0] neg_lo:[0,0,1] neg_hi:[0,0,1]
	v_pk_fma_f32 v[144:145], v[74:75], v[150:151], v[68:69]
	v_pk_mul_f32 v[68:69], v[60:61], v[108:109] op_sel_hi:[1,0]
	v_pk_mul_f32 v[60:61], v[60:61], v[108:109] op_sel:[0,1]
	v_pk_fma_f32 v[146:147], v[74:75], v[70:71], v[72:73]
	v_pk_fma_f32 v[68:69], v[52:53], v[128:129], v[68:69] op_sel_hi:[1,0,1] neg_lo:[0,0,1] neg_hi:[0,0,1]
	v_pk_fma_f32 v[52:53], v[52:53], v[128:129], v[60:61] op_sel:[0,1,0] neg_lo:[0,0,1] neg_hi:[0,0,1]
	v_pk_fma_f32 v[148:149], v[44:45], v[140:141], v[68:69]
	v_pk_fma_f32 v[44:45], v[44:45], v[40:41], v[52:53]
	v_pk_mul_f32 v[40:41], v[62:63], v[108:109] op_sel_hi:[1,0]
	v_pk_mul_f32 v[52:53], v[62:63], v[108:109] op_sel:[0,1]
	s_waitcnt lgkmcnt(0)
	v_pk_mul_f32 v[140:141], v[126:127], v[144:145]
	v_pk_mul_f32 v[126:127], v[126:127], v[146:147]
	v_pk_fma_f32 v[40:41], v[54:55], v[128:129], v[40:41] op_sel_hi:[1,0,1] neg_lo:[0,0,1] neg_hi:[0,0,1]
	v_pk_fma_f32 v[52:53], v[54:55], v[128:129], v[52:53] op_sel:[0,1,0] neg_lo:[0,0,1] neg_hi:[0,0,1]
	v_pk_fma_f32 v[140:141], v[124:125], v[96:97], v[140:141]
	v_pk_fma_f32 v[124:125], v[124:125], v[98:99], v[126:127]
	v_pk_mul_f32 v[126:127], v[114:115], v[144:145]
	v_pk_mul_f32 v[114:115], v[114:115], v[146:147]
	v_pk_fma_f32 v[150:151], v[46:47], v[142:143], v[40:41]
	v_pk_fma_f32 v[46:47], v[46:47], v[42:43], v[52:53]
	v_pk_fma_f32 v[126:127], v[112:113], v[96:97], v[126:127]
	v_pk_fma_f32 v[112:113], v[112:113], v[98:99], v[114:115]
	v_pk_fma_f32 v[114:115], v[100:101], v[148:149], v[140:141]
	v_pk_fma_f32 v[100:101], v[100:101], v[44:45], v[124:125]
	ds_read_b128 v[92:95], v163 offset:12560
	ds_read_b128 v[68:71], v163 offset:12800
	ds_read_b128 v[40:43], v163 offset:12816
	ds_read_b128 v[72:75], v163 offset:13056
	ds_read_b128 v[52:55], v163 offset:13072
	ds_read_b128 v[84:87], v163 offset:13312
	ds_read_b128 v[60:63], v163 offset:13328
	ds_read_b128 v[116:119], v163 offset:13568
	ds_read_b128 v[108:111], v163 offset:13584
	ds_read_b64 v[128:129], v164 offset:13824
	ds_read_b128 v[120:123], v163 offset:12544
	ds_read_b64 v[138:139], v162 offset:14080
	v_pk_fma_f32 v[124:125], v[104:105], v[148:149], v[126:127]
	v_pk_fma_f32 v[104:105], v[104:105], v[44:45], v[112:113]
	v_pk_fma_f32 v[112:113], v[102:103], v[150:151], v[114:115]
	v_pk_fma_f32 v[100:101], v[102:103], v[46:47], v[100:101]
	v_pk_fma_f32 v[102:103], v[106:107], v[150:151], v[124:125]
	v_pk_fma_f32 v[106:107], v[106:107], v[46:47], v[104:105]
	v_add_f32_e32 v101, v100, v101
	v_add_f32_e32 v100, v112, v113
	s_nop 1
	v_add_f32_dpp v100, v100, v100 quad_perm:[1,0,3,2] row_mask:0xf bank_mask:0xf bound_ctrl:1
	v_add_f32_dpp v101, v101, v101 quad_perm:[1,0,3,2] row_mask:0xf bank_mask:0xf bound_ctrl:1
	s_nop 1
	v_add_f32_dpp v100, v100, v100 quad_perm:[2,3,0,1] row_mask:0xf bank_mask:0xf bound_ctrl:1
	v_add_f32_dpp v101, v101, v101 quad_perm:[2,3,0,1] row_mask:0xf bank_mask:0xf bound_ctrl:1
	s_nop 1
	v_mov_b32_dpp v104, v100 row_half_mirror row_mask:0xf bank_mask:0xf bound_ctrl:1
	v_mov_b32_dpp v105, v101 row_half_mirror row_mask:0xf bank_mask:0xf bound_ctrl:1
	v_pk_add_f32 v[104:105], v[100:101], v[104:105]
	v_add_f32_e32 v100, v102, v103
	v_add_f32_e32 v101, v106, v107
	s_nop 1
	v_add_f32_dpp v100, v100, v100 quad_perm:[1,0,3,2] row_mask:0xf bank_mask:0xf bound_ctrl:1
	v_add_f32_dpp v101, v101, v101 quad_perm:[1,0,3,2] row_mask:0xf bank_mask:0xf bound_ctrl:1
	s_nop 1
	v_add_f32_dpp v100, v100, v100 quad_perm:[2,3,0,1] row_mask:0xf bank_mask:0xf bound_ctrl:1
	v_add_f32_dpp v101, v101, v101 quad_perm:[2,3,0,1] row_mask:0xf bank_mask:0xf bound_ctrl:1
	s_nop 1
	v_mov_b32_dpp v102, v100 row_half_mirror row_mask:0xf bank_mask:0xf bound_ctrl:1
	v_mov_b32_dpp v103, v101 row_half_mirror row_mask:0xf bank_mask:0xf bound_ctrl:1
	s_and_saveexec_b64 s[30:31], s[8:9]
	s_cbranch_execz .LBB0_793
	v_pk_add_f32 v[100:101], v[100:101], v[102:103]
	v_lshl_add_u64 v[102:103], v[134:135], 0, s[40:41]
	v_pk_fma_f32 v[100:101], v[130:131], v[136:137], v[100:101] op_sel:[0,1,0]
	s_nop 0
	v_pk_fma_f32 v[100:101], v[136:137], v[104:105], v[100:101] op_sel_hi:[0,1,1] neg_lo:[1,0,0] neg_hi:[1,0,0]
	flat_store_dwordx2 v[102:103], v[100:101]
.LBB0_793:
	s_or_b64 exec, exec, s[30:31]
	v_pk_mul_f32 v[100:101], v[88:89], v[104:105] op_sel_hi:[1,0]
	v_pk_mul_f32 v[88:89], v[88:89], v[104:105] op_sel:[0,1]
	v_pk_fma_f32 v[100:101], v[80:81], v[130:131], v[100:101] op_sel_hi:[1,0,1] neg_lo:[0,0,1] neg_hi:[0,0,1]
	v_pk_fma_f32 v[80:81], v[80:81], v[130:131], v[88:89] op_sel:[0,1,0] neg_lo:[0,0,1] neg_hi:[0,0,1]
	v_pk_fma_f32 v[100:101], v[76:77], v[96:97], v[100:101]
	v_pk_fma_f32 v[102:103], v[76:77], v[98:99], v[80:81]
	v_pk_mul_f32 v[76:77], v[90:91], v[104:105] op_sel_hi:[1,0]
	v_pk_mul_f32 v[80:81], v[90:91], v[104:105] op_sel:[0,1]
	v_pk_fma_f32 v[76:77], v[82:83], v[130:131], v[76:77] op_sel_hi:[1,0,1] neg_lo:[0,0,1] neg_hi:[0,0,1]
	v_pk_fma_f32 v[80:81], v[82:83], v[130:131], v[80:81] op_sel:[0,1,0] neg_lo:[0,0,1] neg_hi:[0,0,1]
	v_pk_fma_f32 v[136:137], v[78:79], v[144:145], v[76:77]
	v_pk_mul_f32 v[76:77], v[64:65], v[104:105] op_sel_hi:[1,0]
	v_pk_mul_f32 v[64:65], v[64:65], v[104:105] op_sel:[0,1]
	v_pk_fma_f32 v[140:141], v[78:79], v[146:147], v[80:81]
	v_pk_fma_f32 v[76:77], v[56:57], v[130:131], v[76:77] op_sel_hi:[1,0,1] neg_lo:[0,0,1] neg_hi:[0,0,1]
	v_pk_fma_f32 v[56:57], v[56:57], v[130:131], v[64:65] op_sel:[0,1,0] neg_lo:[0,0,1] neg_hi:[0,0,1]
	v_pk_fma_f32 v[142:143], v[48:49], v[148:149], v[76:77]
	v_pk_fma_f32 v[144:145], v[48:49], v[44:45], v[56:57]
	v_pk_mul_f32 v[44:45], v[66:67], v[104:105] op_sel_hi:[1,0]
	v_pk_mul_f32 v[48:49], v[66:67], v[104:105] op_sel:[0,1]
	s_waitcnt lgkmcnt(0)
	v_pk_mul_f32 v[148:149], v[122:123], v[136:137]
	v_pk_mul_f32 v[122:123], v[122:123], v[140:141]
	v_pk_fma_f32 v[44:45], v[58:59], v[130:131], v[44:45] op_sel_hi:[1,0,1] neg_lo:[0,0,1] neg_hi:[0,0,1]
	v_pk_fma_f32 v[48:49], v[58:59], v[130:131], v[48:49] op_sel:[0,1,0] neg_lo:[0,0,1] neg_hi:[0,0,1]
	v_pk_fma_f32 v[148:149], v[120:121], v[100:101], v[148:149]
	v_pk_fma_f32 v[120:121], v[120:121], v[102:103], v[122:123]
	v_pk_mul_f32 v[122:123], v[118:119], v[136:137]
	v_pk_mul_f32 v[118:119], v[118:119], v[140:141]
	v_pk_fma_f32 v[130:131], v[50:51], v[150:151], v[44:45]
	v_pk_fma_f32 v[146:147], v[50:51], v[46:47], v[48:49]
	v_pk_fma_f32 v[122:123], v[116:117], v[100:101], v[122:123]
	v_pk_fma_f32 v[116:117], v[116:117], v[102:103], v[118:119]
	v_pk_fma_f32 v[118:119], v[92:93], v[142:143], v[148:149]
	v_pk_fma_f32 v[92:93], v[92:93], v[144:145], v[120:121]
	ds_read_b128 v[88:91], v163 offset:14128
	ds_read_b128 v[64:67], v163 offset:14368
	ds_read_b128 v[44:47], v163 offset:14384
	ds_read_b128 v[76:79], v163 offset:14624
	ds_read_b128 v[48:51], v163 offset:14640
	ds_read_b128 v[80:83], v163 offset:14880
	ds_read_b128 v[56:59], v163 offset:14896
	ds_read_b128 v[104:107], v163 offset:15136
	ds_read_b128 v[96:99], v163 offset:15152
	ds_read_b64 v[124:125], v164 offset:15392
	ds_read_b128 v[112:115], v163 offset:14112
	ds_read_b64 v[126:127], v162 offset:15648
	v_pk_fma_f32 v[120:121], v[108:109], v[142:143], v[122:123]
	v_pk_fma_f32 v[108:109], v[108:109], v[144:145], v[116:117]
	v_pk_fma_f32 v[116:117], v[94:95], v[130:131], v[118:119]
	v_pk_fma_f32 v[92:93], v[94:95], v[146:147], v[92:93]
	v_pk_fma_f32 v[94:95], v[110:111], v[130:131], v[120:121]
	v_pk_fma_f32 v[108:109], v[110:111], v[146:147], v[108:109]
	v_add_f32_e32 v93, v92, v93
	v_add_f32_e32 v92, v116, v117
	s_nop 1
	v_add_f32_dpp v92, v92, v92 quad_perm:[1,0,3,2] row_mask:0xf bank_mask:0xf bound_ctrl:1
	v_add_f32_dpp v93, v93, v93 quad_perm:[1,0,3,2] row_mask:0xf bank_mask:0xf bound_ctrl:1
	s_nop 1
	v_add_f32_dpp v92, v92, v92 quad_perm:[2,3,0,1] row_mask:0xf bank_mask:0xf bound_ctrl:1
	v_add_f32_dpp v93, v93, v93 quad_perm:[2,3,0,1] row_mask:0xf bank_mask:0xf bound_ctrl:1
	s_nop 1
	v_add_f32_dpp v92, v92, v92 row_half_mirror row_mask:0xf bank_mask:0xf bound_ctrl:1
	v_add_f32_dpp v93, v93, v93 row_half_mirror row_mask:0xf bank_mask:0xf bound_ctrl:1
	v_add_f32_e32 v94, v94, v95
	v_add_f32_e32 v95, v108, v109
	s_nop 1
	v_add_f32_dpp v94, v94, v94 quad_perm:[1,0,3,2] row_mask:0xf bank_mask:0xf bound_ctrl:1
	v_add_f32_dpp v95, v95, v95 quad_perm:[1,0,3,2] row_mask:0xf bank_mask:0xf bound_ctrl:1
	s_nop 1
	v_add_f32_dpp v94, v94, v94 quad_perm:[2,3,0,1] row_mask:0xf bank_mask:0xf bound_ctrl:1
	v_add_f32_dpp v95, v95, v95 quad_perm:[2,3,0,1] row_mask:0xf bank_mask:0xf bound_ctrl:1
	s_nop 1
	v_mov_b32_dpp v108, v94 row_half_mirror row_mask:0xf bank_mask:0xf bound_ctrl:1
	v_mov_b32_dpp v109, v95 row_half_mirror row_mask:0xf bank_mask:0xf bound_ctrl:1
	s_and_saveexec_b64 s[30:31], s[8:9]
	s_cbranch_execz .LBB0_795
	v_pk_add_f32 v[94:95], v[94:95], v[108:109]
	v_readlane_b32 s60, v253, 6
	v_pk_fma_f32 v[94:95], v[128:129], v[138:139], v[94:95] op_sel:[0,1,0]
	v_readlane_b32 s61, v253, 7
	v_pk_fma_f32 v[94:95], v[138:139], v[92:93], v[94:95] op_sel_hi:[0,1,1] neg_lo:[1,0,0] neg_hi:[1,0,0]
	s_nop 0
	v_lshl_add_u64 v[108:109], v[134:135], 0, s[60:61]
	flat_store_dwordx2 v[108:109], v[94:95]
.LBB0_795:
	s_or_b64 exec, exec, s[30:31]
	v_pk_mul_f32 v[94:95], v[84:85], v[92:93] op_sel_hi:[1,0]
	v_pk_mul_f32 v[84:85], v[84:85], v[92:93] op_sel:[0,1]
	v_pk_fma_f32 v[94:95], v[72:73], v[128:129], v[94:95] op_sel_hi:[1,0,1] neg_lo:[0,0,1] neg_hi:[0,0,1]
	v_pk_fma_f32 v[72:73], v[72:73], v[128:129], v[84:85] op_sel:[0,1,0] neg_lo:[0,0,1] neg_hi:[0,0,1]
	v_pk_fma_f32 v[122:123], v[68:69], v[100:101], v[94:95]
	v_pk_fma_f32 v[138:139], v[68:69], v[102:103], v[72:73]
	v_pk_mul_f32 v[68:69], v[86:87], v[92:93] op_sel_hi:[1,0]
	v_pk_mul_f32 v[72:73], v[86:87], v[92:93] op_sel:[0,1]
	v_pk_fma_f32 v[68:69], v[74:75], v[128:129], v[68:69] op_sel_hi:[1,0,1] neg_lo:[0,0,1] neg_hi:[0,0,1]
	v_pk_fma_f32 v[72:73], v[74:75], v[128:129], v[72:73] op_sel:[0,1,0] neg_lo:[0,0,1] neg_hi:[0,0,1]
	v_pk_fma_f32 v[136:137], v[70:71], v[136:137], v[68:69]
	v_pk_mul_f32 v[68:69], v[60:61], v[92:93] op_sel_hi:[1,0]
	v_pk_mul_f32 v[60:61], v[60:61], v[92:93] op_sel:[0,1]
	v_pk_fma_f32 v[140:141], v[70:71], v[140:141], v[72:73]
	v_pk_fma_f32 v[68:69], v[52:53], v[128:129], v[68:69] op_sel_hi:[1,0,1] neg_lo:[0,0,1] neg_hi:[0,0,1]
	v_pk_fma_f32 v[52:53], v[52:53], v[128:129], v[60:61] op_sel:[0,1,0] neg_lo:[0,0,1] neg_hi:[0,0,1]
	v_pk_fma_f32 v[142:143], v[40:41], v[142:143], v[68:69]
	v_pk_fma_f32 v[144:145], v[40:41], v[144:145], v[52:53]
	v_pk_mul_f32 v[40:41], v[62:63], v[92:93] op_sel_hi:[1,0]
	v_pk_mul_f32 v[52:53], v[62:63], v[92:93] op_sel:[0,1]
	s_waitcnt lgkmcnt(0)
	v_pk_mul_f32 v[148:149], v[114:115], v[136:137]
	v_pk_mul_f32 v[114:115], v[114:115], v[140:141]
	v_pk_fma_f32 v[40:41], v[54:55], v[128:129], v[40:41] op_sel_hi:[1,0,1] neg_lo:[0,0,1] neg_hi:[0,0,1]
	v_pk_fma_f32 v[52:53], v[54:55], v[128:129], v[52:53] op_sel:[0,1,0] neg_lo:[0,0,1] neg_hi:[0,0,1]
	v_pk_fma_f32 v[148:149], v[112:113], v[122:123], v[148:149]
	v_pk_fma_f32 v[112:113], v[112:113], v[138:139], v[114:115]
	v_pk_mul_f32 v[114:115], v[106:107], v[136:137]
	v_pk_mul_f32 v[106:107], v[106:107], v[140:141]
	v_pk_fma_f32 v[130:131], v[42:43], v[130:131], v[40:41]
	v_pk_fma_f32 v[146:147], v[42:43], v[146:147], v[52:53]
	v_pk_fma_f32 v[114:115], v[104:105], v[122:123], v[114:115]
	v_pk_fma_f32 v[104:105], v[104:105], v[138:139], v[106:107]
	v_pk_fma_f32 v[106:107], v[88:89], v[142:143], v[148:149]
	v_pk_fma_f32 v[88:89], v[88:89], v[144:145], v[112:113]
	ds_read_b128 v[92:95], v163 offset:15696
	ds_read_b128 v[68:71], v163 offset:15936
	ds_read_b128 v[40:43], v163 offset:15952
	ds_read_b128 v[72:75], v163 offset:16192
	ds_read_b128 v[52:55], v163 offset:16208
	ds_read_b128 v[84:87], v163 offset:16448
	ds_read_b128 v[60:63], v163 offset:16464
	ds_read_b128 v[108:111], v163 offset:16704
	ds_read_b128 v[100:103], v163 offset:16720
	ds_read_b64 v[120:121], v164 offset:16960
	ds_read_b128 v[116:119], v163 offset:15680
	ds_read_b64 v[128:129], v162 offset:17216
	v_pk_fma_f32 v[112:113], v[96:97], v[142:143], v[114:115]
	v_pk_fma_f32 v[96:97], v[96:97], v[144:145], v[104:105]
	v_pk_fma_f32 v[104:105], v[90:91], v[130:131], v[106:107]
	v_pk_fma_f32 v[88:89], v[90:91], v[146:147], v[88:89]
	v_pk_fma_f32 v[90:91], v[98:99], v[130:131], v[112:113]
	v_pk_fma_f32 v[96:97], v[98:99], v[146:147], v[96:97]
	v_add_f32_e32 v89, v88, v89
	v_add_f32_e32 v88, v104, v105
	s_nop 1
	v_add_f32_dpp v88, v88, v88 quad_perm:[1,0,3,2] row_mask:0xf bank_mask:0xf bound_ctrl:1
	v_add_f32_dpp v89, v89, v89 quad_perm:[1,0,3,2] row_mask:0xf bank_mask:0xf bound_ctrl:1
	s_nop 1
	v_add_f32_dpp v88, v88, v88 quad_perm:[2,3,0,1] row_mask:0xf bank_mask:0xf bound_ctrl:1
	v_add_f32_dpp v89, v89, v89 quad_perm:[2,3,0,1] row_mask:0xf bank_mask:0xf bound_ctrl:1
	s_nop 1
	v_add_f32_dpp v88, v88, v88 row_half_mirror row_mask:0xf bank_mask:0xf bound_ctrl:1
	v_add_f32_dpp v89, v89, v89 row_half_mirror row_mask:0xf bank_mask:0xf bound_ctrl:1
	v_add_f32_e32 v90, v90, v91
	v_add_f32_e32 v91, v96, v97
	s_nop 1
	v_add_f32_dpp v90, v90, v90 quad_perm:[1,0,3,2] row_mask:0xf bank_mask:0xf bound_ctrl:1
	v_add_f32_dpp v91, v91, v91 quad_perm:[1,0,3,2] row_mask:0xf bank_mask:0xf bound_ctrl:1
	s_nop 1
	v_add_f32_dpp v90, v90, v90 quad_perm:[2,3,0,1] row_mask:0xf bank_mask:0xf bound_ctrl:1
	v_add_f32_dpp v91, v91, v91 quad_perm:[2,3,0,1] row_mask:0xf bank_mask:0xf bound_ctrl:1
	s_nop 1
	v_mov_b32_dpp v96, v90 row_half_mirror row_mask:0xf bank_mask:0xf bound_ctrl:1
	v_mov_b32_dpp v97, v91 row_half_mirror row_mask:0xf bank_mask:0xf bound_ctrl:1
	s_and_saveexec_b64 s[30:31], s[8:9]
	s_cbranch_execz .LBB0_797
	v_pk_add_f32 v[90:91], v[90:91], v[96:97]
	v_lshl_add_u64 v[96:97], v[134:135], 0, s[42:43]
	v_pk_fma_f32 v[90:91], v[124:125], v[126:127], v[90:91] op_sel:[0,1,0]
	s_nop 0
	v_pk_fma_f32 v[90:91], v[126:127], v[88:89], v[90:91] op_sel_hi:[0,1,1] neg_lo:[1,0,0] neg_hi:[1,0,0]
	flat_store_dwordx2 v[96:97], v[90:91]
.LBB0_797:
	s_or_b64 exec, exec, s[30:31]
	v_pk_mul_f32 v[90:91], v[80:81], v[88:89] op_sel_hi:[1,0]
	v_pk_mul_f32 v[80:81], v[80:81], v[88:89] op_sel:[0,1]
	v_pk_fma_f32 v[90:91], v[76:77], v[124:125], v[90:91] op_sel_hi:[1,0,1] neg_lo:[0,0,1] neg_hi:[0,0,1]
	v_pk_fma_f32 v[76:77], v[76:77], v[124:125], v[80:81] op_sel:[0,1,0] neg_lo:[0,0,1] neg_hi:[0,0,1]
	v_pk_fma_f32 v[126:127], v[64:65], v[122:123], v[90:91]
	v_pk_fma_f32 v[138:139], v[64:65], v[138:139], v[76:77]
	v_pk_mul_f32 v[64:65], v[82:83], v[88:89] op_sel_hi:[1,0]
	v_pk_mul_f32 v[76:77], v[82:83], v[88:89] op_sel:[0,1]
	v_pk_fma_f32 v[64:65], v[78:79], v[124:125], v[64:65] op_sel_hi:[1,0,1] neg_lo:[0,0,1] neg_hi:[0,0,1]
	v_pk_fma_f32 v[76:77], v[78:79], v[124:125], v[76:77] op_sel:[0,1,0] neg_lo:[0,0,1] neg_hi:[0,0,1]
	v_pk_fma_f32 v[136:137], v[66:67], v[136:137], v[64:65]
	v_pk_mul_f32 v[64:65], v[56:57], v[88:89] op_sel_hi:[1,0]
	v_pk_mul_f32 v[56:57], v[56:57], v[88:89] op_sel:[0,1]
	v_pk_fma_f32 v[140:141], v[66:67], v[140:141], v[76:77]
	v_pk_fma_f32 v[64:65], v[48:49], v[124:125], v[64:65] op_sel_hi:[1,0,1] neg_lo:[0,0,1] neg_hi:[0,0,1]
	v_pk_fma_f32 v[48:49], v[48:49], v[124:125], v[56:57] op_sel:[0,1,0] neg_lo:[0,0,1] neg_hi:[0,0,1]
	v_pk_fma_f32 v[142:143], v[44:45], v[142:143], v[64:65]
	v_pk_fma_f32 v[144:145], v[44:45], v[144:145], v[48:49]
	v_pk_mul_f32 v[44:45], v[58:59], v[88:89] op_sel_hi:[1,0]
	v_pk_mul_f32 v[48:49], v[58:59], v[88:89] op_sel:[0,1]
	s_waitcnt lgkmcnt(0)
	v_pk_mul_f32 v[148:149], v[118:119], v[136:137]
	v_pk_mul_f32 v[118:119], v[118:119], v[140:141]
	v_pk_fma_f32 v[44:45], v[50:51], v[124:125], v[44:45] op_sel_hi:[1,0,1] neg_lo:[0,0,1] neg_hi:[0,0,1]
	v_pk_fma_f32 v[48:49], v[50:51], v[124:125], v[48:49] op_sel:[0,1,0] neg_lo:[0,0,1] neg_hi:[0,0,1]
	v_pk_fma_f32 v[148:149], v[116:117], v[126:127], v[148:149]
	v_pk_fma_f32 v[116:117], v[116:117], v[138:139], v[118:119]
	v_pk_mul_f32 v[118:119], v[110:111], v[136:137]
	v_pk_mul_f32 v[110:111], v[110:111], v[140:141]
	v_pk_fma_f32 v[130:131], v[46:47], v[130:131], v[44:45]
	v_pk_fma_f32 v[146:147], v[46:47], v[146:147], v[48:49]
	v_pk_fma_f32 v[118:119], v[108:109], v[126:127], v[118:119]
	v_pk_fma_f32 v[108:109], v[108:109], v[138:139], v[110:111]
	v_pk_fma_f32 v[110:111], v[92:93], v[142:143], v[148:149]
	v_pk_fma_f32 v[92:93], v[92:93], v[144:145], v[116:117]
	ds_read_b128 v[88:91], v163 offset:17264
	ds_read_b128 v[64:67], v163 offset:17504
	ds_read_b128 v[44:47], v163 offset:17520
	ds_read_b128 v[76:79], v163 offset:17760
	ds_read_b128 v[48:51], v163 offset:17776
	ds_read_b128 v[80:83], v163 offset:18016
	ds_read_b128 v[56:59], v163 offset:18032
	ds_read_b128 v[104:107], v163 offset:18272
	ds_read_b128 v[96:99], v163 offset:18288
	ds_read_b64 v[122:123], v164 offset:18528
	ds_read_b128 v[112:115], v163 offset:17248
	ds_read_b64 v[124:125], v162 offset:18784
	v_pk_fma_f32 v[116:117], v[100:101], v[142:143], v[118:119]
	v_pk_fma_f32 v[100:101], v[100:101], v[144:145], v[108:109]
	v_pk_fma_f32 v[108:109], v[94:95], v[130:131], v[110:111]
	v_pk_fma_f32 v[92:93], v[94:95], v[146:147], v[92:93]
	v_pk_fma_f32 v[94:95], v[102:103], v[130:131], v[116:117]
	v_pk_fma_f32 v[100:101], v[102:103], v[146:147], v[100:101]
	v_add_f32_e32 v93, v92, v93
	v_add_f32_e32 v92, v108, v109
	s_nop 1
	v_add_f32_dpp v92, v92, v92 quad_perm:[1,0,3,2] row_mask:0xf bank_mask:0xf bound_ctrl:1
	v_add_f32_dpp v93, v93, v93 quad_perm:[1,0,3,2] row_mask:0xf bank_mask:0xf bound_ctrl:1
	s_nop 1
	v_add_f32_dpp v92, v92, v92 quad_perm:[2,3,0,1] row_mask:0xf bank_mask:0xf bound_ctrl:1
	v_add_f32_dpp v93, v93, v93 quad_perm:[2,3,0,1] row_mask:0xf bank_mask:0xf bound_ctrl:1
	s_nop 1
	v_add_f32_dpp v92, v92, v92 row_half_mirror row_mask:0xf bank_mask:0xf bound_ctrl:1
	v_add_f32_dpp v93, v93, v93 row_half_mirror row_mask:0xf bank_mask:0xf bound_ctrl:1
	v_add_f32_e32 v94, v94, v95
	v_add_f32_e32 v95, v100, v101
	s_nop 1
	v_add_f32_dpp v94, v94, v94 quad_perm:[1,0,3,2] row_mask:0xf bank_mask:0xf bound_ctrl:1
	v_add_f32_dpp v95, v95, v95 quad_perm:[1,0,3,2] row_mask:0xf bank_mask:0xf bound_ctrl:1
	s_nop 1
	v_add_f32_dpp v94, v94, v94 quad_perm:[2,3,0,1] row_mask:0xf bank_mask:0xf bound_ctrl:1
	v_add_f32_dpp v95, v95, v95 quad_perm:[2,3,0,1] row_mask:0xf bank_mask:0xf bound_ctrl:1
	s_nop 1
	v_mov_b32_dpp v100, v94 row_half_mirror row_mask:0xf bank_mask:0xf bound_ctrl:1
	v_mov_b32_dpp v101, v95 row_half_mirror row_mask:0xf bank_mask:0xf bound_ctrl:1
	s_and_saveexec_b64 s[30:31], s[8:9]
	s_cbranch_execz .LBB0_799
	v_pk_add_f32 v[94:95], v[94:95], v[100:101]
	v_lshl_add_u64 v[100:101], v[134:135], 0, s[44:45]
	v_pk_fma_f32 v[94:95], v[120:121], v[128:129], v[94:95] op_sel:[0,1,0]
	s_nop 0
	v_pk_fma_f32 v[94:95], v[128:129], v[92:93], v[94:95] op_sel_hi:[0,1,1] neg_lo:[1,0,0] neg_hi:[1,0,0]
	flat_store_dwordx2 v[100:101], v[94:95]
.LBB0_799:
	s_or_b64 exec, exec, s[30:31]
	v_pk_mul_f32 v[94:95], v[84:85], v[92:93] op_sel_hi:[1,0]
	v_pk_mul_f32 v[84:85], v[84:85], v[92:93] op_sel:[0,1]
	v_pk_fma_f32 v[94:95], v[72:73], v[120:121], v[94:95] op_sel_hi:[1,0,1] neg_lo:[0,0,1] neg_hi:[0,0,1]
	v_pk_fma_f32 v[72:73], v[72:73], v[120:121], v[84:85] op_sel:[0,1,0] neg_lo:[0,0,1] neg_hi:[0,0,1]
	v_pk_fma_f32 v[128:129], v[68:69], v[126:127], v[94:95]
	v_pk_fma_f32 v[138:139], v[68:69], v[138:139], v[72:73]
	v_pk_mul_f32 v[68:69], v[86:87], v[92:93] op_sel_hi:[1,0]
	v_pk_mul_f32 v[72:73], v[86:87], v[92:93] op_sel:[0,1]
	v_pk_fma_f32 v[68:69], v[74:75], v[120:121], v[68:69] op_sel_hi:[1,0,1] neg_lo:[0,0,1] neg_hi:[0,0,1]
	v_pk_fma_f32 v[72:73], v[74:75], v[120:121], v[72:73] op_sel:[0,1,0] neg_lo:[0,0,1] neg_hi:[0,0,1]
	v_pk_fma_f32 v[136:137], v[70:71], v[136:137], v[68:69]
	v_pk_mul_f32 v[68:69], v[60:61], v[92:93] op_sel_hi:[1,0]
	v_pk_mul_f32 v[60:61], v[60:61], v[92:93] op_sel:[0,1]
	v_pk_fma_f32 v[140:141], v[70:71], v[140:141], v[72:73]
	v_pk_fma_f32 v[68:69], v[52:53], v[120:121], v[68:69] op_sel_hi:[1,0,1] neg_lo:[0,0,1] neg_hi:[0,0,1]
	v_pk_fma_f32 v[52:53], v[52:53], v[120:121], v[60:61] op_sel:[0,1,0] neg_lo:[0,0,1] neg_hi:[0,0,1]
	v_pk_fma_f32 v[142:143], v[40:41], v[142:143], v[68:69]
	v_pk_fma_f32 v[144:145], v[40:41], v[144:145], v[52:53]
	v_pk_mul_f32 v[40:41], v[62:63], v[92:93] op_sel_hi:[1,0]
	v_pk_mul_f32 v[52:53], v[62:63], v[92:93] op_sel:[0,1]
	s_waitcnt lgkmcnt(0)
	v_pk_mul_f32 v[148:149], v[114:115], v[136:137]
	v_pk_mul_f32 v[114:115], v[114:115], v[140:141]
	v_pk_fma_f32 v[40:41], v[54:55], v[120:121], v[40:41] op_sel_hi:[1,0,1] neg_lo:[0,0,1] neg_hi:[0,0,1]
	v_pk_fma_f32 v[52:53], v[54:55], v[120:121], v[52:53] op_sel:[0,1,0] neg_lo:[0,0,1] neg_hi:[0,0,1]
	v_pk_fma_f32 v[148:149], v[112:113], v[128:129], v[148:149]
	v_pk_fma_f32 v[112:113], v[112:113], v[138:139], v[114:115]
	v_pk_mul_f32 v[114:115], v[106:107], v[136:137]
	v_pk_mul_f32 v[106:107], v[106:107], v[140:141]
	v_pk_fma_f32 v[130:131], v[42:43], v[130:131], v[40:41]
	v_pk_fma_f32 v[146:147], v[42:43], v[146:147], v[52:53]
	v_pk_fma_f32 v[114:115], v[104:105], v[128:129], v[114:115]
	v_pk_fma_f32 v[104:105], v[104:105], v[138:139], v[106:107]
	v_pk_fma_f32 v[106:107], v[88:89], v[142:143], v[148:149]
	v_pk_fma_f32 v[88:89], v[88:89], v[144:145], v[112:113]
	ds_read_b128 v[92:95], v163 offset:18832
	ds_read_b128 v[68:71], v163 offset:19072
	ds_read_b128 v[40:43], v163 offset:19088
	ds_read_b128 v[72:75], v163 offset:19328
	ds_read_b128 v[52:55], v163 offset:19344
	ds_read_b128 v[84:87], v163 offset:19584
	ds_read_b128 v[60:63], v163 offset:19600
	ds_read_b128 v[108:111], v163 offset:19840
	ds_read_b128 v[100:103], v163 offset:19856
	ds_read_b64 v[120:121], v164 offset:20096
	ds_read_b128 v[116:119], v163 offset:18816
	ds_read_b64 v[126:127], v162 offset:20352
	v_pk_fma_f32 v[112:113], v[96:97], v[142:143], v[114:115]
	v_pk_fma_f32 v[96:97], v[96:97], v[144:145], v[104:105]
	v_pk_fma_f32 v[104:105], v[90:91], v[130:131], v[106:107]
	v_pk_fma_f32 v[88:89], v[90:91], v[146:147], v[88:89]
	v_pk_fma_f32 v[90:91], v[98:99], v[130:131], v[112:113]
	v_pk_fma_f32 v[96:97], v[98:99], v[146:147], v[96:97]
	v_add_f32_e32 v89, v88, v89
	v_add_f32_e32 v88, v104, v105
	s_nop 1
	v_add_f32_dpp v88, v88, v88 quad_perm:[1,0,3,2] row_mask:0xf bank_mask:0xf bound_ctrl:1
	v_add_f32_dpp v89, v89, v89 quad_perm:[1,0,3,2] row_mask:0xf bank_mask:0xf bound_ctrl:1
	s_nop 1
	v_add_f32_dpp v88, v88, v88 quad_perm:[2,3,0,1] row_mask:0xf bank_mask:0xf bound_ctrl:1
	v_add_f32_dpp v89, v89, v89 quad_perm:[2,3,0,1] row_mask:0xf bank_mask:0xf bound_ctrl:1
	s_nop 1
	v_add_f32_dpp v88, v88, v88 row_half_mirror row_mask:0xf bank_mask:0xf bound_ctrl:1
	v_add_f32_dpp v89, v89, v89 row_half_mirror row_mask:0xf bank_mask:0xf bound_ctrl:1
	v_add_f32_e32 v90, v90, v91
	v_add_f32_e32 v91, v96, v97
	s_nop 1
	v_add_f32_dpp v90, v90, v90 quad_perm:[1,0,3,2] row_mask:0xf bank_mask:0xf bound_ctrl:1
	v_add_f32_dpp v91, v91, v91 quad_perm:[1,0,3,2] row_mask:0xf bank_mask:0xf bound_ctrl:1
	s_nop 1
	v_add_f32_dpp v90, v90, v90 quad_perm:[2,3,0,1] row_mask:0xf bank_mask:0xf bound_ctrl:1
	v_add_f32_dpp v91, v91, v91 quad_perm:[2,3,0,1] row_mask:0xf bank_mask:0xf bound_ctrl:1
	s_nop 1
	v_mov_b32_dpp v96, v90 row_half_mirror row_mask:0xf bank_mask:0xf bound_ctrl:1
	v_mov_b32_dpp v97, v91 row_half_mirror row_mask:0xf bank_mask:0xf bound_ctrl:1
	s_and_saveexec_b64 s[30:31], s[8:9]
	s_cbranch_execz .LBB0_801
	v_pk_add_f32 v[90:91], v[90:91], v[96:97]
	v_lshl_add_u64 v[96:97], v[134:135], 0, s[46:47]
	v_pk_fma_f32 v[90:91], v[122:123], v[124:125], v[90:91] op_sel:[0,1,0]
	s_nop 0
	v_pk_fma_f32 v[90:91], v[124:125], v[88:89], v[90:91] op_sel_hi:[0,1,1] neg_lo:[1,0,0] neg_hi:[1,0,0]
	flat_store_dwordx2 v[96:97], v[90:91]
.LBB0_801:
	s_or_b64 exec, exec, s[30:31]
	v_pk_mul_f32 v[90:91], v[80:81], v[88:89] op_sel_hi:[1,0]
	v_pk_mul_f32 v[80:81], v[80:81], v[88:89] op_sel:[0,1]
	v_pk_fma_f32 v[90:91], v[76:77], v[122:123], v[90:91] op_sel_hi:[1,0,1] neg_lo:[0,0,1] neg_hi:[0,0,1]
	v_pk_fma_f32 v[76:77], v[76:77], v[122:123], v[80:81] op_sel:[0,1,0] neg_lo:[0,0,1] neg_hi:[0,0,1]
	v_pk_fma_f32 v[128:129], v[64:65], v[128:129], v[90:91]
	v_pk_fma_f32 v[138:139], v[64:65], v[138:139], v[76:77]
	v_pk_mul_f32 v[64:65], v[82:83], v[88:89] op_sel_hi:[1,0]
	v_pk_mul_f32 v[76:77], v[82:83], v[88:89] op_sel:[0,1]
	v_pk_fma_f32 v[64:65], v[78:79], v[122:123], v[64:65] op_sel_hi:[1,0,1] neg_lo:[0,0,1] neg_hi:[0,0,1]
	v_pk_fma_f32 v[76:77], v[78:79], v[122:123], v[76:77] op_sel:[0,1,0] neg_lo:[0,0,1] neg_hi:[0,0,1]
	v_pk_fma_f32 v[136:137], v[66:67], v[136:137], v[64:65]
	v_pk_mul_f32 v[64:65], v[56:57], v[88:89] op_sel_hi:[1,0]
	v_pk_mul_f32 v[56:57], v[56:57], v[88:89] op_sel:[0,1]
	v_pk_fma_f32 v[140:141], v[66:67], v[140:141], v[76:77]
	v_pk_fma_f32 v[64:65], v[48:49], v[122:123], v[64:65] op_sel_hi:[1,0,1] neg_lo:[0,0,1] neg_hi:[0,0,1]
	v_pk_fma_f32 v[48:49], v[48:49], v[122:123], v[56:57] op_sel:[0,1,0] neg_lo:[0,0,1] neg_hi:[0,0,1]
	v_pk_fma_f32 v[142:143], v[44:45], v[142:143], v[64:65]
	v_pk_fma_f32 v[144:145], v[44:45], v[144:145], v[48:49]
	v_pk_mul_f32 v[44:45], v[58:59], v[88:89] op_sel_hi:[1,0]
	v_pk_mul_f32 v[48:49], v[58:59], v[88:89] op_sel:[0,1]
	s_waitcnt lgkmcnt(0)
	v_pk_mul_f32 v[148:149], v[118:119], v[136:137]
	v_pk_mul_f32 v[118:119], v[118:119], v[140:141]
	v_pk_fma_f32 v[44:45], v[50:51], v[122:123], v[44:45] op_sel_hi:[1,0,1] neg_lo:[0,0,1] neg_hi:[0,0,1]
	v_pk_fma_f32 v[48:49], v[50:51], v[122:123], v[48:49] op_sel:[0,1,0] neg_lo:[0,0,1] neg_hi:[0,0,1]
	v_pk_fma_f32 v[148:149], v[116:117], v[128:129], v[148:149]
	v_pk_fma_f32 v[116:117], v[116:117], v[138:139], v[118:119]
	v_pk_mul_f32 v[118:119], v[110:111], v[136:137]
	v_pk_mul_f32 v[110:111], v[110:111], v[140:141]
	v_pk_fma_f32 v[130:131], v[46:47], v[130:131], v[44:45]
	v_pk_fma_f32 v[146:147], v[46:47], v[146:147], v[48:49]
	v_pk_fma_f32 v[118:119], v[108:109], v[128:129], v[118:119]
	v_pk_fma_f32 v[108:109], v[108:109], v[138:139], v[110:111]
	v_pk_fma_f32 v[110:111], v[92:93], v[142:143], v[148:149]
	v_pk_fma_f32 v[92:93], v[92:93], v[144:145], v[116:117]
	ds_read_b128 v[88:91], v163 offset:20400
	ds_read_b128 v[64:67], v163 offset:20640
	ds_read_b128 v[44:47], v163 offset:20656
	ds_read_b128 v[76:79], v163 offset:20896
	ds_read_b128 v[48:51], v163 offset:20912
	ds_read_b128 v[80:83], v163 offset:21152
	ds_read_b128 v[56:59], v163 offset:21168
	ds_read_b128 v[104:107], v163 offset:21408
	ds_read_b128 v[96:99], v163 offset:21424
	ds_read_b64 v[122:123], v164 offset:21664
	ds_read_b128 v[112:115], v163 offset:20384
	ds_read_b64 v[124:125], v162 offset:21920
	v_pk_fma_f32 v[116:117], v[100:101], v[142:143], v[118:119]
	v_pk_fma_f32 v[100:101], v[100:101], v[144:145], v[108:109]
	v_pk_fma_f32 v[108:109], v[94:95], v[130:131], v[110:111]
	v_pk_fma_f32 v[92:93], v[94:95], v[146:147], v[92:93]
	v_pk_fma_f32 v[94:95], v[102:103], v[130:131], v[116:117]
	v_pk_fma_f32 v[100:101], v[102:103], v[146:147], v[100:101]
	v_add_f32_e32 v93, v92, v93
	v_add_f32_e32 v92, v108, v109
	s_nop 1
	v_add_f32_dpp v92, v92, v92 quad_perm:[1,0,3,2] row_mask:0xf bank_mask:0xf bound_ctrl:1
	v_add_f32_dpp v93, v93, v93 quad_perm:[1,0,3,2] row_mask:0xf bank_mask:0xf bound_ctrl:1
	s_nop 1
	v_add_f32_dpp v92, v92, v92 quad_perm:[2,3,0,1] row_mask:0xf bank_mask:0xf bound_ctrl:1
	v_add_f32_dpp v93, v93, v93 quad_perm:[2,3,0,1] row_mask:0xf bank_mask:0xf bound_ctrl:1
	s_nop 1
	v_add_f32_dpp v92, v92, v92 row_half_mirror row_mask:0xf bank_mask:0xf bound_ctrl:1
	v_add_f32_dpp v93, v93, v93 row_half_mirror row_mask:0xf bank_mask:0xf bound_ctrl:1
	v_add_f32_e32 v94, v94, v95
	v_add_f32_e32 v95, v100, v101
	s_nop 1
	v_add_f32_dpp v94, v94, v94 quad_perm:[1,0,3,2] row_mask:0xf bank_mask:0xf bound_ctrl:1
	v_add_f32_dpp v95, v95, v95 quad_perm:[1,0,3,2] row_mask:0xf bank_mask:0xf bound_ctrl:1
	s_nop 1
	v_add_f32_dpp v94, v94, v94 quad_perm:[2,3,0,1] row_mask:0xf bank_mask:0xf bound_ctrl:1
	v_add_f32_dpp v95, v95, v95 quad_perm:[2,3,0,1] row_mask:0xf bank_mask:0xf bound_ctrl:1
	s_nop 1
	v_mov_b32_dpp v100, v94 row_half_mirror row_mask:0xf bank_mask:0xf bound_ctrl:1
	v_mov_b32_dpp v101, v95 row_half_mirror row_mask:0xf bank_mask:0xf bound_ctrl:1
	s_and_saveexec_b64 s[30:31], s[8:9]
	s_cbranch_execz .LBB0_803
	v_pk_add_f32 v[94:95], v[94:95], v[100:101]
	v_lshl_add_u64 v[100:101], v[134:135], 0, s[48:49]
	v_pk_fma_f32 v[94:95], v[120:121], v[126:127], v[94:95] op_sel:[0,1,0]
	s_nop 0
	v_pk_fma_f32 v[94:95], v[126:127], v[92:93], v[94:95] op_sel_hi:[0,1,1] neg_lo:[1,0,0] neg_hi:[1,0,0]
	flat_store_dwordx2 v[100:101], v[94:95]
.LBB0_803:
	s_or_b64 exec, exec, s[30:31]
	v_pk_mul_f32 v[94:95], v[84:85], v[92:93] op_sel_hi:[1,0]
	v_pk_mul_f32 v[84:85], v[84:85], v[92:93] op_sel:[0,1]
	v_pk_fma_f32 v[94:95], v[72:73], v[120:121], v[94:95] op_sel_hi:[1,0,1] neg_lo:[0,0,1] neg_hi:[0,0,1]
	v_pk_fma_f32 v[72:73], v[72:73], v[120:121], v[84:85] op_sel:[0,1,0] neg_lo:[0,0,1] neg_hi:[0,0,1]
	v_pk_fma_f32 v[128:129], v[68:69], v[128:129], v[94:95]
	v_pk_fma_f32 v[138:139], v[68:69], v[138:139], v[72:73]
	v_pk_mul_f32 v[68:69], v[86:87], v[92:93] op_sel_hi:[1,0]
	v_pk_mul_f32 v[72:73], v[86:87], v[92:93] op_sel:[0,1]
	v_pk_fma_f32 v[68:69], v[74:75], v[120:121], v[68:69] op_sel_hi:[1,0,1] neg_lo:[0,0,1] neg_hi:[0,0,1]
	v_pk_fma_f32 v[72:73], v[74:75], v[120:121], v[72:73] op_sel:[0,1,0] neg_lo:[0,0,1] neg_hi:[0,0,1]
	v_pk_fma_f32 v[136:137], v[70:71], v[136:137], v[68:69]
	v_pk_mul_f32 v[68:69], v[60:61], v[92:93] op_sel_hi:[1,0]
	v_pk_mul_f32 v[60:61], v[60:61], v[92:93] op_sel:[0,1]
	v_pk_fma_f32 v[140:141], v[70:71], v[140:141], v[72:73]
	v_pk_fma_f32 v[68:69], v[52:53], v[120:121], v[68:69] op_sel_hi:[1,0,1] neg_lo:[0,0,1] neg_hi:[0,0,1]
	v_pk_fma_f32 v[52:53], v[52:53], v[120:121], v[60:61] op_sel:[0,1,0] neg_lo:[0,0,1] neg_hi:[0,0,1]
	v_pk_fma_f32 v[142:143], v[40:41], v[142:143], v[68:69]
	v_pk_fma_f32 v[144:145], v[40:41], v[144:145], v[52:53]
	v_pk_mul_f32 v[40:41], v[62:63], v[92:93] op_sel_hi:[1,0]
	v_pk_mul_f32 v[52:53], v[62:63], v[92:93] op_sel:[0,1]
	s_waitcnt lgkmcnt(0)
	v_pk_mul_f32 v[148:149], v[114:115], v[136:137]
	v_pk_mul_f32 v[114:115], v[114:115], v[140:141]
	v_pk_fma_f32 v[40:41], v[54:55], v[120:121], v[40:41] op_sel_hi:[1,0,1] neg_lo:[0,0,1] neg_hi:[0,0,1]
	v_pk_fma_f32 v[52:53], v[54:55], v[120:121], v[52:53] op_sel:[0,1,0] neg_lo:[0,0,1] neg_hi:[0,0,1]
	v_pk_fma_f32 v[148:149], v[112:113], v[128:129], v[148:149]
	v_pk_fma_f32 v[112:113], v[112:113], v[138:139], v[114:115]
	v_pk_mul_f32 v[114:115], v[106:107], v[136:137]
	v_pk_mul_f32 v[106:107], v[106:107], v[140:141]
	v_pk_fma_f32 v[130:131], v[42:43], v[130:131], v[40:41]
	v_pk_fma_f32 v[146:147], v[42:43], v[146:147], v[52:53]
	v_pk_fma_f32 v[114:115], v[104:105], v[128:129], v[114:115]
	v_pk_fma_f32 v[104:105], v[104:105], v[138:139], v[106:107]
	v_pk_fma_f32 v[106:107], v[88:89], v[142:143], v[148:149]
	v_pk_fma_f32 v[88:89], v[88:89], v[144:145], v[112:113]
	ds_read_b128 v[92:95], v163 offset:21968
	ds_read_b128 v[68:71], v163 offset:22208
	ds_read_b128 v[40:43], v163 offset:22224
	ds_read_b128 v[72:75], v163 offset:22464
	ds_read_b128 v[52:55], v163 offset:22480
	ds_read_b128 v[84:87], v163 offset:22720
	ds_read_b128 v[60:63], v163 offset:22736
	ds_read_b128 v[108:111], v163 offset:22976
	ds_read_b128 v[100:103], v163 offset:22992
	ds_read_b64 v[120:121], v164 offset:23232
	ds_read_b128 v[116:119], v163 offset:21952
	ds_read_b64 v[126:127], v162 offset:23488
	v_pk_fma_f32 v[112:113], v[96:97], v[142:143], v[114:115]
	v_pk_fma_f32 v[96:97], v[96:97], v[144:145], v[104:105]
	v_pk_fma_f32 v[104:105], v[90:91], v[130:131], v[106:107]
	v_pk_fma_f32 v[88:89], v[90:91], v[146:147], v[88:89]
	v_pk_fma_f32 v[90:91], v[98:99], v[130:131], v[112:113]
	v_pk_fma_f32 v[96:97], v[98:99], v[146:147], v[96:97]
	v_add_f32_e32 v89, v88, v89
	v_add_f32_e32 v88, v104, v105
	s_nop 1
	v_add_f32_dpp v88, v88, v88 quad_perm:[1,0,3,2] row_mask:0xf bank_mask:0xf bound_ctrl:1
	v_add_f32_dpp v89, v89, v89 quad_perm:[1,0,3,2] row_mask:0xf bank_mask:0xf bound_ctrl:1
	s_nop 1
	v_add_f32_dpp v88, v88, v88 quad_perm:[2,3,0,1] row_mask:0xf bank_mask:0xf bound_ctrl:1
	v_add_f32_dpp v89, v89, v89 quad_perm:[2,3,0,1] row_mask:0xf bank_mask:0xf bound_ctrl:1
	s_nop 1
	v_add_f32_dpp v88, v88, v88 row_half_mirror row_mask:0xf bank_mask:0xf bound_ctrl:1
	v_add_f32_dpp v89, v89, v89 row_half_mirror row_mask:0xf bank_mask:0xf bound_ctrl:1
	v_add_f32_e32 v90, v90, v91
	v_add_f32_e32 v91, v96, v97
	s_nop 1
	v_add_f32_dpp v90, v90, v90 quad_perm:[1,0,3,2] row_mask:0xf bank_mask:0xf bound_ctrl:1
	v_add_f32_dpp v91, v91, v91 quad_perm:[1,0,3,2] row_mask:0xf bank_mask:0xf bound_ctrl:1
	s_nop 1
	v_add_f32_dpp v90, v90, v90 quad_perm:[2,3,0,1] row_mask:0xf bank_mask:0xf bound_ctrl:1
	v_add_f32_dpp v91, v91, v91 quad_perm:[2,3,0,1] row_mask:0xf bank_mask:0xf bound_ctrl:1
	s_nop 1
	v_mov_b32_dpp v96, v90 row_half_mirror row_mask:0xf bank_mask:0xf bound_ctrl:1
	v_mov_b32_dpp v97, v91 row_half_mirror row_mask:0xf bank_mask:0xf bound_ctrl:1
	s_and_saveexec_b64 s[30:31], s[8:9]
	s_cbranch_execz .LBB0_805
	v_pk_add_f32 v[90:91], v[90:91], v[96:97]
	v_lshl_add_u64 v[96:97], v[134:135], 0, s[50:51]
	v_pk_fma_f32 v[90:91], v[122:123], v[124:125], v[90:91] op_sel:[0,1,0]
	s_nop 0
	v_pk_fma_f32 v[90:91], v[124:125], v[88:89], v[90:91] op_sel_hi:[0,1,1] neg_lo:[1,0,0] neg_hi:[1,0,0]
	flat_store_dwordx2 v[96:97], v[90:91]
.LBB0_805:
	s_or_b64 exec, exec, s[30:31]
	v_pk_mul_f32 v[90:91], v[80:81], v[88:89] op_sel_hi:[1,0]
	v_pk_mul_f32 v[80:81], v[80:81], v[88:89] op_sel:[0,1]
	v_pk_fma_f32 v[90:91], v[76:77], v[122:123], v[90:91] op_sel_hi:[1,0,1] neg_lo:[0,0,1] neg_hi:[0,0,1]
	v_pk_fma_f32 v[76:77], v[76:77], v[122:123], v[80:81] op_sel:[0,1,0] neg_lo:[0,0,1] neg_hi:[0,0,1]
	v_pk_fma_f32 v[128:129], v[64:65], v[128:129], v[90:91]
	v_pk_fma_f32 v[138:139], v[64:65], v[138:139], v[76:77]
	v_pk_mul_f32 v[64:65], v[82:83], v[88:89] op_sel_hi:[1,0]
	v_pk_mul_f32 v[76:77], v[82:83], v[88:89] op_sel:[0,1]
	v_pk_fma_f32 v[64:65], v[78:79], v[122:123], v[64:65] op_sel_hi:[1,0,1] neg_lo:[0,0,1] neg_hi:[0,0,1]
	v_pk_fma_f32 v[76:77], v[78:79], v[122:123], v[76:77] op_sel:[0,1,0] neg_lo:[0,0,1] neg_hi:[0,0,1]
	v_pk_fma_f32 v[136:137], v[66:67], v[136:137], v[64:65]
	v_pk_mul_f32 v[64:65], v[56:57], v[88:89] op_sel_hi:[1,0]
	v_pk_mul_f32 v[56:57], v[56:57], v[88:89] op_sel:[0,1]
	v_pk_fma_f32 v[140:141], v[66:67], v[140:141], v[76:77]
	v_pk_fma_f32 v[64:65], v[48:49], v[122:123], v[64:65] op_sel_hi:[1,0,1] neg_lo:[0,0,1] neg_hi:[0,0,1]
	v_pk_fma_f32 v[48:49], v[48:49], v[122:123], v[56:57] op_sel:[0,1,0] neg_lo:[0,0,1] neg_hi:[0,0,1]
	v_pk_fma_f32 v[142:143], v[44:45], v[142:143], v[64:65]
	v_pk_fma_f32 v[144:145], v[44:45], v[144:145], v[48:49]
	v_pk_mul_f32 v[44:45], v[58:59], v[88:89] op_sel_hi:[1,0]
	v_pk_mul_f32 v[48:49], v[58:59], v[88:89] op_sel:[0,1]
	s_waitcnt lgkmcnt(0)
	v_pk_mul_f32 v[148:149], v[118:119], v[136:137]
	v_pk_mul_f32 v[118:119], v[118:119], v[140:141]
	v_pk_fma_f32 v[44:45], v[50:51], v[122:123], v[44:45] op_sel_hi:[1,0,1] neg_lo:[0,0,1] neg_hi:[0,0,1]
	v_pk_fma_f32 v[48:49], v[50:51], v[122:123], v[48:49] op_sel:[0,1,0] neg_lo:[0,0,1] neg_hi:[0,0,1]
	v_pk_fma_f32 v[148:149], v[116:117], v[128:129], v[148:149]
	v_pk_fma_f32 v[116:117], v[116:117], v[138:139], v[118:119]
	v_pk_mul_f32 v[118:119], v[110:111], v[136:137]
	v_pk_mul_f32 v[110:111], v[110:111], v[140:141]
	v_pk_fma_f32 v[130:131], v[46:47], v[130:131], v[44:45]
	v_pk_fma_f32 v[146:147], v[46:47], v[146:147], v[48:49]
	v_pk_fma_f32 v[118:119], v[108:109], v[128:129], v[118:119]
	v_pk_fma_f32 v[108:109], v[108:109], v[138:139], v[110:111]
	v_pk_fma_f32 v[110:111], v[92:93], v[142:143], v[148:149]
	v_pk_fma_f32 v[92:93], v[92:93], v[144:145], v[116:117]
	ds_read_b128 v[88:91], v163 offset:23536
	ds_read_b128 v[48:51], v163 offset:23776
	ds_read_b128 v[56:59], v163 offset:23792
	ds_read_b128 v[76:79], v163 offset:24032
	ds_read_b128 v[44:47], v163 offset:24048
	ds_read_b128 v[80:83], v163 offset:24288
	ds_read_b128 v[64:67], v163 offset:24304
	ds_read_b128 v[104:107], v163 offset:24544
	ds_read_b128 v[96:99], v163 offset:24560
	ds_read_b64 v[122:123], v164 offset:24800
	ds_read_b128 v[112:115], v163 offset:23520
	ds_read_b64 v[124:125], v162 offset:25056
	v_pk_fma_f32 v[116:117], v[100:101], v[142:143], v[118:119]
	v_pk_fma_f32 v[100:101], v[100:101], v[144:145], v[108:109]
	v_pk_fma_f32 v[108:109], v[94:95], v[130:131], v[110:111]
	v_pk_fma_f32 v[92:93], v[94:95], v[146:147], v[92:93]
	v_pk_fma_f32 v[94:95], v[102:103], v[130:131], v[116:117]
	v_pk_fma_f32 v[100:101], v[102:103], v[146:147], v[100:101]
	v_add_f32_e32 v93, v92, v93
	v_add_f32_e32 v92, v108, v109
	s_nop 1
	v_add_f32_dpp v92, v92, v92 quad_perm:[1,0,3,2] row_mask:0xf bank_mask:0xf bound_ctrl:1
	v_add_f32_dpp v93, v93, v93 quad_perm:[1,0,3,2] row_mask:0xf bank_mask:0xf bound_ctrl:1
	s_nop 1
	v_add_f32_dpp v92, v92, v92 quad_perm:[2,3,0,1] row_mask:0xf bank_mask:0xf bound_ctrl:1
	v_add_f32_dpp v93, v93, v93 quad_perm:[2,3,0,1] row_mask:0xf bank_mask:0xf bound_ctrl:1
	s_nop 1
	v_add_f32_dpp v92, v92, v92 row_half_mirror row_mask:0xf bank_mask:0xf bound_ctrl:1
	v_add_f32_dpp v93, v93, v93 row_half_mirror row_mask:0xf bank_mask:0xf bound_ctrl:1
	v_add_f32_e32 v94, v94, v95
	v_add_f32_e32 v95, v100, v101
	s_nop 1
	v_add_f32_dpp v94, v94, v94 quad_perm:[1,0,3,2] row_mask:0xf bank_mask:0xf bound_ctrl:1
	v_add_f32_dpp v95, v95, v95 quad_perm:[1,0,3,2] row_mask:0xf bank_mask:0xf bound_ctrl:1
	s_nop 1
	v_add_f32_dpp v94, v94, v94 quad_perm:[2,3,0,1] row_mask:0xf bank_mask:0xf bound_ctrl:1
	v_add_f32_dpp v95, v95, v95 quad_perm:[2,3,0,1] row_mask:0xf bank_mask:0xf bound_ctrl:1
	s_nop 1
	v_mov_b32_dpp v100, v94 row_half_mirror row_mask:0xf bank_mask:0xf bound_ctrl:1
	v_mov_b32_dpp v101, v95 row_half_mirror row_mask:0xf bank_mask:0xf bound_ctrl:1
	s_and_saveexec_b64 s[30:31], s[8:9]
	s_cbranch_execz .LBB0_807
	v_pk_add_f32 v[94:95], v[94:95], v[100:101]
	v_lshl_add_u64 v[100:101], v[134:135], 0, s[52:53]
	v_pk_fma_f32 v[94:95], v[120:121], v[126:127], v[94:95] op_sel:[0,1,0]
	s_nop 0
	v_pk_fma_f32 v[94:95], v[126:127], v[92:93], v[94:95] op_sel_hi:[0,1,1] neg_lo:[1,0,0] neg_hi:[1,0,0]
	flat_store_dwordx2 v[100:101], v[94:95]
.LBB0_807:
	s_or_b64 exec, exec, s[30:31]
	v_pk_mul_f32 v[94:95], v[84:85], v[92:93] op_sel_hi:[1,0]
	v_pk_mul_f32 v[84:85], v[84:85], v[92:93] op_sel:[0,1]
	v_pk_fma_f32 v[94:95], v[72:73], v[120:121], v[94:95] op_sel_hi:[1,0,1] neg_lo:[0,0,1] neg_hi:[0,0,1]
	v_pk_fma_f32 v[84:85], v[72:73], v[120:121], v[84:85] op_sel:[0,1,0] neg_lo:[0,0,1] neg_hi:[0,0,1]
	v_pk_fma_f32 v[72:73], v[68:69], v[128:129], v[94:95]
	v_pk_fma_f32 v[68:69], v[68:69], v[138:139], v[84:85]
	v_pk_mul_f32 v[84:85], v[86:87], v[92:93] op_sel_hi:[1,0]
	v_pk_mul_f32 v[86:87], v[86:87], v[92:93] op_sel:[0,1]
	v_pk_fma_f32 v[84:85], v[74:75], v[120:121], v[84:85] op_sel_hi:[1,0,1] neg_lo:[0,0,1] neg_hi:[0,0,1]
	v_pk_fma_f32 v[86:87], v[74:75], v[120:121], v[86:87] op_sel:[0,1,0] neg_lo:[0,0,1] neg_hi:[0,0,1]
	v_pk_fma_f32 v[74:75], v[70:71], v[136:137], v[84:85]
	v_pk_mul_f32 v[84:85], v[60:61], v[92:93] op_sel_hi:[1,0]
	v_pk_mul_f32 v[60:61], v[60:61], v[92:93] op_sel:[0,1]
	v_pk_fma_f32 v[84:85], v[52:53], v[120:121], v[84:85] op_sel_hi:[1,0,1] neg_lo:[0,0,1] neg_hi:[0,0,1]
	v_pk_fma_f32 v[52:53], v[52:53], v[120:121], v[60:61] op_sel:[0,1,0] neg_lo:[0,0,1] neg_hi:[0,0,1]
	v_pk_fma_f32 v[60:61], v[40:41], v[142:143], v[84:85]
	v_pk_fma_f32 v[40:41], v[40:41], v[144:145], v[52:53]
	v_pk_mul_f32 v[52:53], v[62:63], v[92:93] op_sel_hi:[1,0]
	v_pk_mul_f32 v[62:63], v[62:63], v[92:93] op_sel:[0,1]
	v_pk_fma_f32 v[70:71], v[70:71], v[140:141], v[86:87]
	v_pk_fma_f32 v[52:53], v[54:55], v[120:121], v[52:53] op_sel_hi:[1,0,1] neg_lo:[0,0,1] neg_hi:[0,0,1]
	v_pk_fma_f32 v[54:55], v[54:55], v[120:121], v[62:63] op_sel:[0,1,0] neg_lo:[0,0,1] neg_hi:[0,0,1]
	v_pk_fma_f32 v[62:63], v[42:43], v[130:131], v[52:53]
	v_pk_fma_f32 v[42:43], v[42:43], v[146:147], v[54:55]
	s_waitcnt lgkmcnt(0)
	v_pk_mul_f32 v[52:53], v[114:115], v[74:75]
	v_pk_mul_f32 v[54:55], v[114:115], v[70:71]
	v_pk_fma_f32 v[52:53], v[112:113], v[72:73], v[52:53]
	v_pk_fma_f32 v[54:55], v[112:113], v[68:69], v[54:55]
	v_pk_mul_f32 v[84:85], v[106:107], v[74:75]
	v_pk_fma_f32 v[52:53], v[88:89], v[60:61], v[52:53]
	v_pk_fma_f32 v[84:85], v[104:105], v[72:73], v[84:85]
	v_pk_fma_f32 v[54:55], v[88:89], v[40:41], v[54:55]
	v_pk_fma_f32 v[84:85], v[96:97], v[60:61], v[84:85]
	v_pk_fma_f32 v[52:53], v[90:91], v[62:63], v[52:53]
	v_pk_fma_f32 v[54:55], v[90:91], v[42:43], v[54:55]
	v_pk_fma_f32 v[88:89], v[98:99], v[62:63], v[84:85]
	v_add_f32_e32 v52, v52, v53
	v_add_f32_e32 v53, v54, v55
	v_pk_mul_f32 v[86:87], v[106:107], v[70:71]
	s_nop 0
	v_add_f32_dpp v52, v52, v52 quad_perm:[1,0,3,2] row_mask:0xf bank_mask:0xf bound_ctrl:1
	v_add_f32_dpp v53, v53, v53 quad_perm:[1,0,3,2] row_mask:0xf bank_mask:0xf bound_ctrl:1
	v_pk_fma_f32 v[86:87], v[104:105], v[68:69], v[86:87]
	s_nop 0
	v_pk_fma_f32 v[86:87], v[96:97], v[40:41], v[86:87]
	v_add_f32_dpp v52, v52, v52 quad_perm:[2,3,0,1] row_mask:0xf bank_mask:0xf bound_ctrl:1
	v_add_f32_dpp v53, v53, v53 quad_perm:[2,3,0,1] row_mask:0xf bank_mask:0xf bound_ctrl:1
	v_pk_fma_f32 v[86:87], v[98:99], v[42:43], v[86:87]
	s_nop 0
	v_mov_b32_dpp v54, v52 row_half_mirror row_mask:0xf bank_mask:0xf bound_ctrl:1
	v_mov_b32_dpp v55, v53 row_half_mirror row_mask:0xf bank_mask:0xf bound_ctrl:1
	v_pk_add_f32 v[84:85], v[52:53], v[54:55]
	v_add_f32_e32 v52, v88, v89
	v_add_f32_e32 v53, v86, v87
	s_nop 1
	v_add_f32_dpp v52, v52, v52 quad_perm:[1,0,3,2] row_mask:0xf bank_mask:0xf bound_ctrl:1
	v_add_f32_dpp v53, v53, v53 quad_perm:[1,0,3,2] row_mask:0xf bank_mask:0xf bound_ctrl:1
	s_nop 1
	v_add_f32_dpp v52, v52, v52 quad_perm:[2,3,0,1] row_mask:0xf bank_mask:0xf bound_ctrl:1
	v_add_f32_dpp v53, v53, v53 quad_perm:[2,3,0,1] row_mask:0xf bank_mask:0xf bound_ctrl:1
	s_nop 1
	v_mov_b32_dpp v54, v52 row_half_mirror row_mask:0xf bank_mask:0xf bound_ctrl:1
	v_mov_b32_dpp v55, v53 row_half_mirror row_mask:0xf bank_mask:0xf bound_ctrl:1
	s_and_saveexec_b64 s[30:31], s[8:9]
	s_cbranch_execz .LBB0_776
	v_pk_add_f32 v[52:53], v[52:53], v[54:55]
	v_lshl_add_u64 v[54:55], v[134:135], 0, s[94:95]
	v_pk_fma_f32 v[52:53], v[122:123], v[124:125], v[52:53] op_sel:[0,1,0]
	s_nop 0
	v_pk_fma_f32 v[52:53], v[124:125], v[84:85], v[52:53] op_sel_hi:[0,1,1] neg_lo:[1,0,0] neg_hi:[1,0,0]
	flat_store_dwordx2 v[54:55], v[52:53]
	s_branch .LBB0_776

.LBB0_820:
	v_lshlrev_b32_e32 v65, 5, v64
	v_and_b32_e32 v65, 32, v65
	v_add_u32_e32 v65, v65, v154
	v_mul_lo_u32 v65, v65, s38
	s_waitcnt vmcnt(0) lgkmcnt(0)
	v_and_b32_e32 v66, 0xffff0000, v0
	v_and_b32_e32 v67, 0xffff0000, v1
	v_and_b32_e32 v68, 0xffff0000, v2
	v_and_b32_e32 v69, 0xffff0000, v3
	v_add_u32_e32 v65, v157, v65
	v_lshlrev_b32_e32 v71, 16, v3
	v_lshlrev_b32_e32 v70, 16, v2
	ds_write_b128 v65, v[66:69]
	ds_write_b128 v65, v[16:19] offset:256
	ds_write_b128 v65, v[56:59] offset:512
	ds_write_b128 v65, v[60:63] offset:768
	v_lshlrev_b32_e32 v66, 16, v12
	v_lshlrev_b32_e32 v67, 16, v13
	v_lshlrev_b32_e32 v68, 16, v14
	v_lshlrev_b32_e32 v69, 16, v15
	v_lshlrev_b32_e32 v73, 16, v1
	v_lshlrev_b32_e32 v72, 16, v0
	ds_write_b128 v65, v[66:69] offset:1280
	v_pk_mul_f32 v[68:69], v[18:19], v[70:71]
	v_pk_mul_f32 v[66:67], v[16:17], v[72:73]
	ds_write_b128 v65, v[66:69] offset:1024
	v_mov_b32_e32 v67, v61
	v_mov_b32_e32 v61, v57
	v_mov_b32_e32 v66, v56
	v_pk_mul_f32 v[56:57], v[60:61], v[72:73]
	v_mov_b32_e32 v60, v58
	v_pk_fma_f32 v[56:57], v[66:67], v[72:73], v[56:57] op_sel:[0,0,1] op_sel_hi:[1,1,0]
	v_mov_b32_e32 v61, v62
	v_pk_fma_f32 v[56:57], v[70:71], v[60:61], v[56:57] op_sel_hi:[0,1,1]
	v_mov_b32_e32 v62, v59
	v_mov_b32_e32 v58, v71
	v_pk_fma_f32 v[56:57], v[58:59], v[62:63], v[56:57] op_sel_hi:[0,1,1]
	s_nop 1
	v_add_f32_dpp v56, v56, v56 quad_perm:[1,0,3,2] row_mask:0xf bank_mask:0xf bound_ctrl:1
	v_add_f32_dpp v57, v57, v57 quad_perm:[1,0,3,2] row_mask:0xf bank_mask:0xf bound_ctrl:1
	s_nop 1
	v_add_f32_dpp v56, v56, v56 quad_perm:[2,3,0,1] row_mask:0xf bank_mask:0xf bound_ctrl:1
	v_add_f32_dpp v57, v57, v57 quad_perm:[2,3,0,1] row_mask:0xf bank_mask:0xf bound_ctrl:1
	s_nop 1
	v_add_f32_dpp v56, v56, v56 row_half_mirror row_mask:0xf bank_mask:0xf bound_ctrl:1
	v_add_f32_dpp v57, v57, v57 row_half_mirror row_mask:0xf bank_mask:0xf bound_ctrl:1
	s_nop 1
	v_mov_b32_dpp v59, v57 row_mirror row_mask:0xf bank_mask:0xf bound_ctrl:1
	v_mov_b32_dpp v58, v56 row_mirror row_mask:0xf bank_mask:0xf bound_ctrl:1
	s_and_saveexec_b64 s[30:31], s[10:11]
	v_pk_add_f32 v[56:57], v[56:57], v[58:59]
	s_nop 0
	v_pk_mov_b32 v[56:57], v[56:57], v[56:57] op_sel:[1,0]
	ds_write_b64 v65, v[56:57] offset:1536
	s_or_b64 exec, exec, s[30:31]
	s_and_b64 vcc, exec, s[6:7]
	s_mov_b64 s[30:31], -1
	s_cbranch_vccnz .LBB0_826
	v_and_b32_e32 v56, 0xffff0000, v24
	v_and_b32_e32 v57, 0xffff0000, v25
	v_and_b32_e32 v58, 0xffff0000, v26
	v_and_b32_e32 v59, 0xffff0000, v27
	s_cbranch_execz .LBB0_827

.LBB0_830:
	v_and_b32_e32 v66, 0xffff0000, v20
	v_and_b32_e32 v67, 0xffff0000, v21
	v_and_b32_e32 v68, 0xffff0000, v22
	v_and_b32_e32 v69, 0xffff0000, v23
	v_lshlrev_b32_e32 v71, 16, v23
	v_lshlrev_b32_e32 v70, 16, v22
	ds_write_b128 v65, v[66:69] offset:25088
	ds_write_b128 v65, v[36:39] offset:25344
	ds_write_b128 v65, v[56:59] offset:25600
	ds_write_b128 v65, v[60:63] offset:25856
	v_lshlrev_b32_e32 v66, 16, v32
	v_lshlrev_b32_e32 v67, 16, v33
	v_lshlrev_b32_e32 v68, 16, v34
	v_lshlrev_b32_e32 v69, 16, v35
	v_lshlrev_b32_e32 v73, 16, v21
	v_lshlrev_b32_e32 v72, 16, v20
	ds_write_b128 v65, v[66:69] offset:26368
	v_pk_mul_f32 v[68:69], v[38:39], v[70:71]
	v_pk_mul_f32 v[66:67], v[36:37], v[72:73]
	ds_write_b128 v65, v[66:69] offset:26112
	v_mov_b32_e32 v67, v61
	v_mov_b32_e32 v61, v57
	v_mov_b32_e32 v66, v56
	v_pk_mul_f32 v[56:57], v[60:61], v[72:73]
	v_mov_b32_e32 v60, v58
	v_pk_fma_f32 v[56:57], v[66:67], v[72:73], v[56:57] op_sel:[0,0,1] op_sel_hi:[1,1,0]
	v_mov_b32_e32 v61, v62
	v_pk_fma_f32 v[56:57], v[70:71], v[60:61], v[56:57] op_sel_hi:[0,1,1]
	v_mov_b32_e32 v62, v59
	v_mov_b32_e32 v58, v71
	v_pk_fma_f32 v[56:57], v[58:59], v[62:63], v[56:57] op_sel_hi:[0,1,1]
	s_nop 1
	v_add_f32_dpp v56, v56, v56 quad_perm:[1,0,3,2] row_mask:0xf bank_mask:0xf bound_ctrl:1
	v_add_f32_dpp v57, v57, v57 quad_perm:[1,0,3,2] row_mask:0xf bank_mask:0xf bound_ctrl:1
	s_nop 1
	v_add_f32_dpp v56, v56, v56 quad_perm:[2,3,0,1] row_mask:0xf bank_mask:0xf bound_ctrl:1
	v_add_f32_dpp v57, v57, v57 quad_perm:[2,3,0,1] row_mask:0xf bank_mask:0xf bound_ctrl:1
	s_nop 1
	v_add_f32_dpp v56, v56, v56 row_half_mirror row_mask:0xf bank_mask:0xf bound_ctrl:1
	v_add_f32_dpp v57, v57, v57 row_half_mirror row_mask:0xf bank_mask:0xf bound_ctrl:1
	s_nop 1
	v_mov_b32_dpp v59, v57 row_mirror row_mask:0xf bank_mask:0xf bound_ctrl:1
	v_mov_b32_dpp v58, v56 row_mirror row_mask:0xf bank_mask:0xf bound_ctrl:1
	s_and_saveexec_b64 s[30:31], s[10:11]
	v_pk_add_f32 v[56:57], v[56:57], v[58:59]
	s_nop 0
	v_pk_mov_b32 v[56:57], v[56:57], v[56:57] op_sel:[1,0]
	ds_write_b64 v65, v[56:57] offset:26624
	s_or_b64 exec, exec, s[30:31]
	v_cmp_ne_u32_e32 vcc, 6, v159
	v_mov_b32_e32 v56, 7
	s_and_saveexec_b64 s[30:31], vcc
	s_cbranch_execz .LBB0_771
	v_lshl_add_u32 v18, v159, 5, v158
	v_sub_u32_e32 v0, 0xff, v18
	v_cndmask_b32_e64 v0, v0, v18, s[0:1]
	v_add_u32_e32 v19, 16, v18
	v_sub_u32_e32 v18, 0xef, v18
	v_cndmask_b32_e64 v18, v18, v19, s[0:1]
	v_add_u32_e32 v0, s33, v0
	v_add_u32_e32 v18, s33, v18
	v_ashrrev_i32_e32 v1, 31, v0
	v_ashrrev_i32_e32 v19, 31, v18
	v_lshlrev_b64 v[0:1], 9, v[0:1]
	v_lshlrev_b64 v[18:19], 9, v[18:19]
	v_lshl_add_u64 v[0:1], v[0:1], 0, v[178:179]
	v_lshl_add_u64 v[18:19], v[18:19], 0, v[178:179]
	v_lshlrev_b64 v[16:17], 2, v[0:1]
	v_lshlrev_b64 v[32:33], 2, v[18:19]
	v_lshl_add_u64 v[0:1], s[12:13], 0, v[16:17]
	v_lshl_add_u64 v[4:5], s[14:15], 0, v[16:17]
	v_lshl_add_u64 v[8:9], s[16:17], 0, v[16:17]
	v_lshl_add_u64 v[12:13], s[18:19], 0, v[16:17]
	v_lshl_add_u64 v[16:17], s[20:21], 0, v[16:17]
	v_lshl_add_u64 v[20:21], s[12:13], 0, v[32:33]
	v_lshl_add_u64 v[24:25], s[14:15], 0, v[32:33]
	v_lshl_add_u64 v[28:29], s[16:17], 0, v[32:33]
	v_lshl_add_u64 v[34:35], s[18:19], 0, v[32:33]
	v_lshl_add_u64 v[36:37], s[20:21], 0, v[32:33]
	flat_load_dwordx4 v[0:3], v[0:1]
	s_nop 0
	flat_load_dwordx4 v[4:7], v[4:5]
	s_nop 0
	flat_load_dwordx4 v[8:11], v[8:9]
	s_nop 0
	flat_load_dwordx4 v[12:15], v[12:13]
	s_nop 0
	flat_load_dwordx4 v[16:19], v[16:17]
	s_nop 0
	flat_load_dwordx4 v[20:23], v[20:21]
	s_nop 0
	flat_load_dwordx4 v[24:27], v[24:25]
	s_nop 0
	flat_load_dwordx4 v[28:31], v[28:29]
	s_nop 0
	flat_load_dwordx4 v[32:35], v[34:35]
	s_nop 0
	flat_load_dwordx4 v[36:39], v[36:37]
	v_mov_b32_e32 v56, v64
	s_branch .LBB0_771

.LBB0_853:
	s_waitcnt vmcnt(0) lgkmcnt(0)
	v_add_u32_e32 v36, 0, v62
	v_mul_lo_u32 v37, v153, s38
	v_lshlrev_b32_e32 v39, 16, v23
	v_lshlrev_b32_e32 v38, 16, v22
	v_and_b32_e32 v64, 0xffff0000, v20
	v_and_b32_e32 v65, 0xffff0000, v21
	v_and_b32_e32 v66, 0xffff0000, v22
	v_and_b32_e32 v67, 0xffff0000, v23
	v_add_u32_e32 v36, v36, v37
	v_lshlrev_b32_e32 v22, 16, v24
	v_lshlrev_b32_e32 v23, 16, v25
	v_lshlrev_b32_e32 v24, 16, v26
	v_lshlrev_b32_e32 v25, 16, v27
	ds_write_b128 v36, v[64:67]
	ds_write_b128 v36, v[32:35] offset:256
	ds_write_b128 v36, v[28:31] offset:512
	ds_write_b128 v36, v[56:59] offset:768
	ds_write_b128 v36, v[22:25] offset:1280
	v_lshlrev_b32_e32 v25, 16, v21
	v_lshlrev_b32_e32 v24, 16, v20
	v_pk_mul_f32 v[22:23], v[34:35], v[38:39]
	v_pk_mul_f32 v[20:21], v[32:33], v[24:25]
	ds_write_b128 v36, v[20:23] offset:1024
	v_mov_b32_e32 v21, v57
	v_mov_b32_e32 v57, v29
	v_mov_b32_e32 v20, v28
	v_pk_mul_f32 v[22:23], v[56:57], v[24:25]
	v_cmp_eq_u32_e64 s[8:9], 0, v61
	v_pk_fma_f32 v[20:21], v[20:21], v[24:25], v[22:23] op_sel:[0,0,1] op_sel_hi:[1,1,0]
	v_mov_b32_e32 v22, v30
	v_mov_b32_e32 v23, v58
	v_pk_fma_f32 v[20:21], v[38:39], v[22:23], v[20:21] op_sel_hi:[0,1,1]
	v_mov_b32_e32 v58, v31
	v_mov_b32_e32 v22, v39
	v_pk_fma_f32 v[20:21], v[22:23], v[58:59], v[20:21] op_sel_hi:[0,1,1]
	s_nop 1
	v_add_f32_dpp v20, v20, v20 quad_perm:[1,0,3,2] row_mask:0xf bank_mask:0xf bound_ctrl:1
	v_add_f32_dpp v21, v21, v21 quad_perm:[1,0,3,2] row_mask:0xf bank_mask:0xf bound_ctrl:1
	s_nop 1
	v_add_f32_dpp v20, v20, v20 quad_perm:[2,3,0,1] row_mask:0xf bank_mask:0xf bound_ctrl:1
	v_add_f32_dpp v21, v21, v21 quad_perm:[2,3,0,1] row_mask:0xf bank_mask:0xf bound_ctrl:1
	s_nop 1
	v_add_f32_dpp v20, v20, v20 row_half_mirror row_mask:0xf bank_mask:0xf bound_ctrl:1
	v_add_f32_dpp v21, v21, v21 row_half_mirror row_mask:0xf bank_mask:0xf bound_ctrl:1
	s_nop 1
	v_mov_b32_dpp v23, v21 row_mirror row_mask:0xf bank_mask:0xf bound_ctrl:1
	v_mov_b32_dpp v22, v20 row_mirror row_mask:0xf bank_mask:0xf bound_ctrl:1
	s_and_saveexec_b64 s[22:23], s[8:9]
	v_pk_add_f32 v[20:21], v[20:21], v[22:23]
	s_nop 0
	v_pk_mov_b32 v[20:21], v[20:21], v[20:21] op_sel:[1,0]
	ds_write_b64 v36, v[20:21] offset:1536
	s_or_b64 exec, exec, s[22:23]
	s_and_b64 vcc, exec, s[6:7]
	s_mov_b64 s[22:23], -1
	s_cbranch_vccnz .LBB0_859
	v_and_b32_e32 v20, 0xffff0000, v16
	v_and_b32_e32 v21, 0xffff0000, v17
	v_and_b32_e32 v22, 0xffff0000, v18
	v_and_b32_e32 v23, 0xffff0000, v19
	s_cbranch_execz .LBB0_860

.LBB0_863:
	v_and_b32_e32 v12, 0xffff0000, v0
	v_and_b32_e32 v13, 0xffff0000, v1
	v_and_b32_e32 v14, 0xffff0000, v2
	v_and_b32_e32 v15, 0xffff0000, v3
	v_lshlrev_b32_e32 v8, 16, v8
	v_lshlrev_b32_e32 v9, 16, v9
	v_lshlrev_b32_e32 v10, 16, v10
	v_lshlrev_b32_e32 v11, 16, v11
	v_lshlrev_b32_e32 v25, 16, v3
	v_lshlrev_b32_e32 v24, 16, v2
	ds_write_b128 v36, v[12:15] offset:25088
	ds_write_b128 v36, v[4:7] offset:25344
	ds_write_b128 v36, v[20:23] offset:25600
	ds_write_b128 v36, v[16:19] offset:25856
	ds_write_b128 v36, v[8:11] offset:26368
	v_lshlrev_b32_e32 v9, 16, v1
	v_lshlrev_b32_e32 v8, 16, v0
	v_pk_mul_f32 v[2:3], v[6:7], v[24:25]
	v_pk_mul_f32 v[0:1], v[4:5], v[8:9]
	ds_write_b128 v36, v[0:3] offset:26112
	v_mov_b32_e32 v1, v17
	v_mov_b32_e32 v17, v21
	v_mov_b32_e32 v0, v20
	v_pk_mul_f32 v[2:3], v[16:17], v[8:9]
	s_nop 0
	v_pk_fma_f32 v[0:1], v[0:1], v[8:9], v[2:3] op_sel:[0,0,1] op_sel_hi:[1,1,0]
	v_mov_b32_e32 v2, v22
	v_mov_b32_e32 v3, v18
	v_pk_fma_f32 v[0:1], v[24:25], v[2:3], v[0:1] op_sel_hi:[0,1,1]
	v_mov_b32_e32 v18, v23
	v_mov_b32_e32 v2, v25
	v_pk_fma_f32 v[0:1], v[2:3], v[18:19], v[0:1] op_sel_hi:[0,1,1]
	s_nop 1
	v_add_f32_dpp v0, v0, v0 quad_perm:[1,0,3,2] row_mask:0xf bank_mask:0xf bound_ctrl:1
	v_add_f32_dpp v1, v1, v1 quad_perm:[1,0,3,2] row_mask:0xf bank_mask:0xf bound_ctrl:1
	s_nop 1
	v_add_f32_dpp v0, v0, v0 quad_perm:[2,3,0,1] row_mask:0xf bank_mask:0xf bound_ctrl:1
	v_add_f32_dpp v1, v1, v1 quad_perm:[2,3,0,1] row_mask:0xf bank_mask:0xf bound_ctrl:1
	s_nop 1
	v_add_f32_dpp v0, v0, v0 row_half_mirror row_mask:0xf bank_mask:0xf bound_ctrl:1
	v_add_f32_dpp v1, v1, v1 row_half_mirror row_mask:0xf bank_mask:0xf bound_ctrl:1
	s_nop 1
	v_mov_b32_dpp v3, v1 row_mirror row_mask:0xf bank_mask:0xf bound_ctrl:1
	v_mov_b32_dpp v2, v0 row_mirror row_mask:0xf bank_mask:0xf bound_ctrl:1
	s_and_saveexec_b64 s[22:23], s[8:9]
	v_pk_add_f32 v[0:1], v[0:1], v[2:3]
	s_nop 0
	v_pk_mov_b32 v[0:1], v[0:1], v[0:1] op_sel:[1,0]
	ds_write_b64 v36, v[0:1] offset:26624
	s_or_b64 exec, exec, s[22:23]
	v_readlane_b32 s8, v253, 35
	v_add_u32_e32 v0, 32, v153
	v_sub_u32_e32 v1, 0x7df, v153
	v_readlane_b32 s9, v253, 36
	v_add_u32_e32 v18, 48, v153
	v_sub_u32_e32 v19, 0x7cf, v153
	v_cndmask_b32_e64 v0, v1, v0, s[8:9]
	v_cndmask_b32_e64 v18, v19, v18, s[8:9]
	v_add_u32_e32 v0, s35, v0
	v_add_u32_e32 v18, s35, v18
	v_ashrrev_i32_e32 v1, 31, v0
	v_ashrrev_i32_e32 v19, 31, v18
	v_lshlrev_b64 v[16:17], 11, v[0:1]
	v_lshlrev_b64 v[32:33], 11, v[18:19]
	v_or_b32_e32 v16, v16, v63
	v_or_b32_e32 v32, v32, v63
	v_lshl_add_u64 v[0:1], s[12:13], 0, v[16:17]
	v_lshl_add_u64 v[4:5], s[14:15], 0, v[16:17]
	v_lshl_add_u64 v[8:9], s[16:17], 0, v[16:17]
	v_lshl_add_u64 v[12:13], s[18:19], 0, v[16:17]
	v_lshl_add_u64 v[16:17], s[20:21], 0, v[16:17]
	v_lshl_add_u64 v[20:21], s[12:13], 0, v[32:33]
	v_lshl_add_u64 v[24:25], s[14:15], 0, v[32:33]
	v_lshl_add_u64 v[28:29], s[16:17], 0, v[32:33]
	v_lshl_add_u64 v[34:35], s[18:19], 0, v[32:33]
	v_lshl_add_u64 v[36:37], s[20:21], 0, v[32:33]
	flat_load_dwordx4 v[0:3], v[0:1]
	s_nop 0
	flat_load_dwordx4 v[4:7], v[4:5]
	s_nop 0
	flat_load_dwordx4 v[8:11], v[8:9]
	s_nop 0
	flat_load_dwordx4 v[12:15], v[12:13]
	s_nop 0
	flat_load_dwordx4 v[16:19], v[16:17]
	s_nop 0
	flat_load_dwordx4 v[20:23], v[20:21]
	s_nop 0
	flat_load_dwordx4 v[24:27], v[24:25]
	s_nop 0
	flat_load_dwordx4 v[28:31], v[28:29]
	s_nop 0
	flat_load_dwordx4 v[32:35], v[34:35]
	s_nop 0
	flat_load_dwordx4 v[36:39], v[36:37]

.LBB0_873:
	v_or_b32_e32 v56, s28, v158
	v_mad_u32_u24 v159, v56, s38, 0
	v_lshl_add_u32 v160, v151, 2, v159
	v_or_b32_e32 v56, s28, v157
	v_readlane_b32 s28, v253, 35
	ds_read_b128 v[120:123], v160
	ds_read_b128 v[128:131], v160 offset:16
	ds_read_b128 v[88:91], v160 offset:256
	ds_read_b128 v[64:67], v160 offset:272
	ds_read_b128 v[100:103], v160 offset:512
	ds_read_b128 v[76:79], v160 offset:528
	ds_read_b128 v[108:111], v160 offset:768
	ds_read_b128 v[84:87], v160 offset:784
	ds_read_b128 v[136:139], v160 offset:1024
	v_sub_u32_e32 v57, 0x7ff, v56
	v_readlane_b32 s29, v253, 36
	s_waitcnt lgkmcnt(0)
	v_pk_mul_f32 v[146:147], v[46:47], v[122:123]
	v_pk_mul_f32 v[122:123], v[54:55], v[122:123]
	v_cndmask_b32_e64 v56, v57, v56, s[28:29]
	v_add_u32_e32 v56, s35, v56
	v_ashrrev_i32_e32 v57, 31, v56
	v_lshlrev_b64 v[56:57], 12, v[56:57]
	v_lshl_add_u32 v161, v150, 2, v159
	v_pk_fma_f32 v[146:147], v[44:45], v[120:121], v[146:147]
	v_pk_fma_f32 v[120:121], v[52:53], v[120:121], v[122:123]
	v_pk_mul_f32 v[122:123], v[46:47], v[138:139]
	v_pk_mul_f32 v[138:139], v[54:55], v[138:139]
	v_lshl_add_u64 v[134:135], v[132:133], 0, v[56:57]
	v_add_u32_e32 v56, 0x400, v161
	v_pk_fma_f32 v[122:123], v[44:45], v[136:137], v[122:123]
	v_pk_fma_f32 v[136:137], v[52:53], v[136:137], v[138:139]
	v_pk_fma_f32 v[138:139], v[40:41], v[128:129], v[146:147]
	v_pk_fma_f32 v[120:121], v[48:49], v[128:129], v[120:121]
	ds_read2_b64 v[56:59], v56 offset0:32 offset1:228
	ds_read_b128 v[142:145], v160 offset:1040
	ds_read_b128 v[116:119], v160 offset:1568
	ds_read_b128 v[104:107], v160 offset:1584
	ds_read_b128 v[80:83], v160 offset:1824
	ds_read_b128 v[60:63], v160 offset:1840
	ds_read_b128 v[92:95], v160 offset:2080
	ds_read_b128 v[68:71], v160 offset:2096
	ds_read_b128 v[96:99], v160 offset:2336
	ds_read_b128 v[72:75], v160 offset:2352
	ds_read_b128 v[124:127], v160 offset:2592
	ds_read_b128 v[112:115], v160 offset:2608
	ds_read_b64 v[140:141], v159 offset:3104
	s_waitcnt lgkmcnt(0)
	v_pk_fma_f32 v[128:129], v[48:49], v[142:143], v[136:137]
	v_pk_fma_f32 v[136:137], v[42:43], v[130:131], v[138:139]
	v_pk_fma_f32 v[120:121], v[50:51], v[130:131], v[120:121]
	v_add_f32_e32 v121, v120, v121
	v_add_f32_e32 v120, v136, v137
	v_pk_fma_f32 v[122:123], v[40:41], v[142:143], v[122:123]
	v_pk_fma_f32 v[128:129], v[50:51], v[144:145], v[128:129]
	v_add_f32_dpp v120, v120, v120 quad_perm:[1,0,3,2] row_mask:0xf bank_mask:0xf bound_ctrl:1
	v_add_f32_dpp v121, v121, v121 quad_perm:[1,0,3,2] row_mask:0xf bank_mask:0xf bound_ctrl:1
	v_pk_fma_f32 v[122:123], v[42:43], v[144:145], v[122:123]
	s_nop 0
	v_add_f32_dpp v120, v120, v120 quad_perm:[2,3,0,1] row_mask:0xf bank_mask:0xf bound_ctrl:1
	v_add_f32_dpp v121, v121, v121 quad_perm:[2,3,0,1] row_mask:0xf bank_mask:0xf bound_ctrl:1
	s_nop 1
	v_add_f32_dpp v120, v120, v120 row_half_mirror row_mask:0xf bank_mask:0xf bound_ctrl:1
	v_add_f32_dpp v121, v121, v121 row_half_mirror row_mask:0xf bank_mask:0xf bound_ctrl:1
	v_add_f32_e32 v122, v122, v123
	v_add_f32_e32 v123, v128, v129
	s_nop 1
	v_add_f32_dpp v122, v122, v122 quad_perm:[1,0,3,2] row_mask:0xf bank_mask:0xf bound_ctrl:1
	v_add_f32_dpp v123, v123, v123 quad_perm:[1,0,3,2] row_mask:0xf bank_mask:0xf bound_ctrl:1
	s_nop 1
	v_add_f32_dpp v122, v122, v122 quad_perm:[2,3,0,1] row_mask:0xf bank_mask:0xf bound_ctrl:1
	v_add_f32_dpp v123, v123, v123 quad_perm:[2,3,0,1] row_mask:0xf bank_mask:0xf bound_ctrl:1
	s_nop 1
	v_mov_b32_dpp v128, v122 row_half_mirror row_mask:0xf bank_mask:0xf bound_ctrl:1
	v_mov_b32_dpp v129, v123 row_half_mirror row_mask:0xf bank_mask:0xf bound_ctrl:1
	s_and_saveexec_b64 s[28:29], s[8:9]
	s_cbranch_execz .LBB0_875
	ds_read_b64 v[130:131], v159 offset:1536
	v_pk_add_f32 v[122:123], v[122:123], v[128:129]
	s_waitcnt lgkmcnt(0)
	v_pk_fma_f32 v[122:123], v[56:57], v[130:131], v[122:123] op_sel:[0,1,0]
	s_nop 0
	v_pk_fma_f32 v[122:123], v[120:121], v[130:131], v[122:123] op_sel_hi:[1,0,1] neg_lo:[1,0,0] neg_hi:[1,0,0]
	flat_store_dwordx2 v[134:135], v[122:123]
.LBB0_875:
	s_or_b64 exec, exec, s[28:29]
	v_pk_mul_f32 v[122:123], v[108:109], v[120:121] op_sel_hi:[1,0]
	v_pk_mul_f32 v[108:109], v[108:109], v[120:121] op_sel:[0,1]
	v_pk_fma_f32 v[122:123], v[100:101], v[56:57], v[122:123] op_sel_hi:[1,0,1] neg_lo:[0,0,1] neg_hi:[0,0,1]
	v_pk_fma_f32 v[100:101], v[100:101], v[56:57], v[108:109] op_sel:[0,1,0] neg_lo:[0,0,1] neg_hi:[0,0,1]
	v_pk_fma_f32 v[44:45], v[44:45], v[88:89], v[122:123]
	v_pk_fma_f32 v[52:53], v[52:53], v[88:89], v[100:101]
	v_pk_mul_f32 v[88:89], v[110:111], v[120:121] op_sel_hi:[1,0]
	v_pk_mul_f32 v[100:101], v[110:111], v[120:121] op_sel:[0,1]
	v_pk_fma_f32 v[88:89], v[102:103], v[56:57], v[88:89] op_sel_hi:[1,0,1] neg_lo:[0,0,1] neg_hi:[0,0,1]
	v_pk_fma_f32 v[100:101], v[102:103], v[56:57], v[100:101] op_sel:[0,1,0] neg_lo:[0,0,1] neg_hi:[0,0,1]
	v_pk_fma_f32 v[46:47], v[46:47], v[90:91], v[88:89]
	v_pk_mul_f32 v[88:89], v[84:85], v[120:121] op_sel_hi:[1,0]
	v_pk_mul_f32 v[84:85], v[84:85], v[120:121] op_sel:[0,1]
	v_pk_fma_f32 v[54:55], v[54:55], v[90:91], v[100:101]
	v_pk_fma_f32 v[88:89], v[76:77], v[56:57], v[88:89] op_sel_hi:[1,0,1] neg_lo:[0,0,1] neg_hi:[0,0,1]
	v_pk_fma_f32 v[76:77], v[76:77], v[56:57], v[84:85] op_sel:[0,1,0] neg_lo:[0,0,1] neg_hi:[0,0,1]
	v_pk_fma_f32 v[142:143], v[40:41], v[64:65], v[88:89]
	v_pk_fma_f32 v[144:145], v[48:49], v[64:65], v[76:77]
	v_pk_mul_f32 v[40:41], v[86:87], v[120:121] op_sel_hi:[1,0]
	v_pk_mul_f32 v[48:49], v[86:87], v[120:121] op_sel:[0,1]
	s_waitcnt lgkmcnt(0)
	v_pk_mul_f32 v[148:149], v[118:119], v[46:47]
	v_pk_mul_f32 v[118:119], v[118:119], v[54:55]
	v_pk_fma_f32 v[40:41], v[78:79], v[56:57], v[40:41] op_sel_hi:[1,0,1] neg_lo:[0,0,1] neg_hi:[0,0,1]
	v_pk_fma_f32 v[48:49], v[78:79], v[56:57], v[48:49] op_sel:[0,1,0] neg_lo:[0,0,1] neg_hi:[0,0,1]
	v_pk_fma_f32 v[148:149], v[116:117], v[44:45], v[148:149]
	v_pk_fma_f32 v[116:117], v[116:117], v[52:53], v[118:119]
	v_pk_mul_f32 v[118:119], v[126:127], v[46:47]
	v_pk_mul_f32 v[126:127], v[126:127], v[54:55]
	v_pk_fma_f32 v[56:57], v[42:43], v[66:67], v[40:41]
	v_pk_fma_f32 v[146:147], v[50:51], v[66:67], v[48:49]
	v_pk_fma_f32 v[118:119], v[124:125], v[44:45], v[118:119]
	v_pk_fma_f32 v[124:125], v[124:125], v[52:53], v[126:127]
	v_pk_fma_f32 v[126:127], v[104:105], v[142:143], v[148:149]
	v_pk_fma_f32 v[104:105], v[104:105], v[144:145], v[116:117]
	ds_read_b128 v[100:103], v160 offset:3152
	ds_read_b128 v[76:79], v160 offset:3392
	ds_read_b128 v[40:43], v160 offset:3408
	ds_read_b128 v[84:87], v160 offset:3648
	ds_read_b128 v[48:51], v160 offset:3664
	ds_read_b128 v[88:91], v160 offset:3904
	ds_read_b128 v[64:67], v160 offset:3920
	ds_read_b128 v[120:123], v160 offset:4160
	ds_read_b128 v[108:111], v160 offset:4176
	ds_read_b64 v[136:137], v161 offset:4416
	ds_read_b128 v[128:131], v160 offset:3136
	ds_read_b64 v[138:139], v159 offset:4672
	v_pk_fma_f32 v[116:117], v[112:113], v[142:143], v[118:119]
	v_pk_fma_f32 v[112:113], v[112:113], v[144:145], v[124:125]
	v_pk_fma_f32 v[118:119], v[106:107], v[56:57], v[126:127]
	v_pk_fma_f32 v[104:105], v[106:107], v[146:147], v[104:105]
	v_pk_fma_f32 v[106:107], v[114:115], v[56:57], v[116:117]
	v_pk_fma_f32 v[112:113], v[114:115], v[146:147], v[112:113]
	v_add_f32_e32 v105, v104, v105
	v_add_f32_e32 v104, v118, v119
	s_nop 1
	v_add_f32_dpp v104, v104, v104 quad_perm:[1,0,3,2] row_mask:0xf bank_mask:0xf bound_ctrl:1
	v_add_f32_dpp v105, v105, v105 quad_perm:[1,0,3,2] row_mask:0xf bank_mask:0xf bound_ctrl:1
	s_nop 1
	v_add_f32_dpp v104, v104, v104 quad_perm:[2,3,0,1] row_mask:0xf bank_mask:0xf bound_ctrl:1
	v_add_f32_dpp v105, v105, v105 quad_perm:[2,3,0,1] row_mask:0xf bank_mask:0xf bound_ctrl:1
	s_nop 1
	v_add_f32_dpp v104, v104, v104 row_half_mirror row_mask:0xf bank_mask:0xf bound_ctrl:1
	v_add_f32_dpp v105, v105, v105 row_half_mirror row_mask:0xf bank_mask:0xf bound_ctrl:1
	v_add_f32_e32 v106, v106, v107
	v_add_f32_e32 v107, v112, v113
	s_nop 1
	v_add_f32_dpp v106, v106, v106 quad_perm:[1,0,3,2] row_mask:0xf bank_mask:0xf bound_ctrl:1
	v_add_f32_dpp v107, v107, v107 quad_perm:[1,0,3,2] row_mask:0xf bank_mask:0xf bound_ctrl:1
	s_nop 1
	v_add_f32_dpp v106, v106, v106 quad_perm:[2,3,0,1] row_mask:0xf bank_mask:0xf bound_ctrl:1
	v_add_f32_dpp v107, v107, v107 quad_perm:[2,3,0,1] row_mask:0xf bank_mask:0xf bound_ctrl:1
	s_nop 1
	v_mov_b32_dpp v112, v106 row_half_mirror row_mask:0xf bank_mask:0xf bound_ctrl:1
	v_mov_b32_dpp v113, v107 row_half_mirror row_mask:0xf bank_mask:0xf bound_ctrl:1
	s_and_saveexec_b64 s[28:29], s[8:9]
	s_cbranch_execz .LBB0_877
	v_pk_add_f32 v[106:107], v[106:107], v[112:113]
	v_readlane_b32 s30, v254, 19
	v_pk_fma_f32 v[106:107], v[58:59], v[140:141], v[106:107] op_sel:[0,1,0]
	v_readlane_b32 s31, v254, 20
	v_pk_fma_f32 v[106:107], v[140:141], v[104:105], v[106:107] op_sel_hi:[0,1,1] neg_lo:[1,0,0] neg_hi:[1,0,0]
	s_nop 0
	v_lshl_add_u64 v[112:113], s[30:31], 2, v[134:135]
	flat_store_dwordx2 v[112:113], v[106:107]
.LBB0_877:
	s_or_b64 exec, exec, s[28:29]
	v_pk_mul_f32 v[106:107], v[96:97], v[104:105] op_sel_hi:[1,0]
	v_pk_mul_f32 v[96:97], v[96:97], v[104:105] op_sel:[0,1]
	v_pk_fma_f32 v[106:107], v[92:93], v[58:59], v[106:107] op_sel_hi:[1,0,1] neg_lo:[0,0,1] neg_hi:[0,0,1]
	v_pk_fma_f32 v[92:93], v[92:93], v[58:59], v[96:97] op_sel:[0,1,0] neg_lo:[0,0,1] neg_hi:[0,0,1]
	v_pk_fma_f32 v[116:117], v[80:81], v[44:45], v[106:107]
	v_pk_mul_f32 v[44:45], v[98:99], v[104:105] op_sel_hi:[1,0]
	v_pk_fma_f32 v[118:119], v[80:81], v[52:53], v[92:93]
	v_pk_fma_f32 v[44:45], v[94:95], v[58:59], v[44:45] op_sel_hi:[1,0,1] neg_lo:[0,0,1] neg_hi:[0,0,1]
	v_pk_mul_f32 v[52:53], v[98:99], v[104:105] op_sel:[0,1]
	v_pk_fma_f32 v[140:141], v[82:83], v[46:47], v[44:45]
	v_pk_mul_f32 v[44:45], v[72:73], v[104:105] op_sel_hi:[1,0]
	v_pk_mul_f32 v[46:47], v[72:73], v[104:105] op_sel:[0,1]
	v_pk_fma_f32 v[44:45], v[68:69], v[58:59], v[44:45] op_sel_hi:[1,0,1] neg_lo:[0,0,1] neg_hi:[0,0,1]
	v_pk_fma_f32 v[46:47], v[68:69], v[58:59], v[46:47] op_sel:[0,1,0] neg_lo:[0,0,1] neg_hi:[0,0,1]
	v_pk_fma_f32 v[52:53], v[94:95], v[58:59], v[52:53] op_sel:[0,1,0] neg_lo:[0,0,1] neg_hi:[0,0,1]
	v_pk_fma_f32 v[142:143], v[60:61], v[142:143], v[44:45]
	v_pk_fma_f32 v[60:61], v[60:61], v[144:145], v[46:47]
	v_pk_mul_f32 v[44:45], v[74:75], v[104:105] op_sel_hi:[1,0]
	v_pk_mul_f32 v[46:47], v[74:75], v[104:105] op_sel:[0,1]
	v_pk_fma_f32 v[148:149], v[82:83], v[54:55], v[52:53]
	v_pk_fma_f32 v[44:45], v[70:71], v[58:59], v[44:45] op_sel_hi:[1,0,1] neg_lo:[0,0,1] neg_hi:[0,0,1]
	v_pk_fma_f32 v[46:47], v[70:71], v[58:59], v[46:47] op_sel:[0,1,0] neg_lo:[0,0,1] neg_hi:[0,0,1]
	v_pk_fma_f32 v[144:145], v[62:63], v[56:57], v[44:45]
	v_pk_fma_f32 v[62:63], v[62:63], v[146:147], v[46:47]
	s_waitcnt lgkmcnt(0)
	v_pk_mul_f32 v[146:147], v[130:131], v[140:141]
	v_pk_mul_f32 v[130:131], v[130:131], v[148:149]
	v_pk_fma_f32 v[146:147], v[128:129], v[116:117], v[146:147]
	v_pk_fma_f32 v[128:129], v[128:129], v[118:119], v[130:131]
	v_pk_mul_f32 v[130:131], v[122:123], v[140:141]
	v_pk_mul_f32 v[122:123], v[122:123], v[148:149]
	v_pk_fma_f32 v[130:131], v[120:121], v[116:117], v[130:131]
	v_pk_fma_f32 v[120:121], v[120:121], v[118:119], v[122:123]
	v_pk_fma_f32 v[122:123], v[100:101], v[142:143], v[146:147]
	v_pk_fma_f32 v[100:101], v[100:101], v[60:61], v[128:129]
	ds_read_b128 v[92:95], v160 offset:4720
	ds_read_b128 v[68:71], v160 offset:4960
	ds_read_b128 v[44:47], v160 offset:4976
	ds_read_b128 v[72:75], v160 offset:5216
	ds_read_b128 v[52:55], v160 offset:5232
	ds_read_b128 v[80:83], v160 offset:5472
	ds_read_b128 v[56:59], v160 offset:5488
	ds_read_b128 v[104:107], v160 offset:5728
	ds_read_b128 v[96:99], v160 offset:5744
	ds_read_b64 v[124:125], v161 offset:5984
	ds_read_b128 v[112:115], v160 offset:4704
	ds_read_b64 v[126:127], v159 offset:6240
	v_pk_fma_f32 v[128:129], v[108:109], v[142:143], v[130:131]
	v_pk_fma_f32 v[108:109], v[108:109], v[60:61], v[120:121]
	v_pk_fma_f32 v[120:121], v[102:103], v[144:145], v[122:123]
	v_pk_fma_f32 v[100:101], v[102:103], v[62:63], v[100:101]
	v_pk_fma_f32 v[102:103], v[110:111], v[144:145], v[128:129]
	v_pk_fma_f32 v[108:109], v[110:111], v[62:63], v[108:109]
	v_add_f32_e32 v101, v100, v101
	v_add_f32_e32 v100, v120, v121
	s_nop 1
	v_add_f32_dpp v100, v100, v100 quad_perm:[1,0,3,2] row_mask:0xf bank_mask:0xf bound_ctrl:1
	v_add_f32_dpp v101, v101, v101 quad_perm:[1,0,3,2] row_mask:0xf bank_mask:0xf bound_ctrl:1
	s_nop 1
	v_add_f32_dpp v100, v100, v100 quad_perm:[2,3,0,1] row_mask:0xf bank_mask:0xf bound_ctrl:1
	v_add_f32_dpp v101, v101, v101 quad_perm:[2,3,0,1] row_mask:0xf bank_mask:0xf bound_ctrl:1
	s_nop 1
	v_add_f32_dpp v100, v100, v100 row_half_mirror row_mask:0xf bank_mask:0xf bound_ctrl:1
	v_add_f32_dpp v101, v101, v101 row_half_mirror row_mask:0xf bank_mask:0xf bound_ctrl:1
	v_add_f32_e32 v102, v102, v103
	v_add_f32_e32 v103, v108, v109
	s_nop 1
	v_add_f32_dpp v102, v102, v102 quad_perm:[1,0,3,2] row_mask:0xf bank_mask:0xf bound_ctrl:1
	v_add_f32_dpp v103, v103, v103 quad_perm:[1,0,3,2] row_mask:0xf bank_mask:0xf bound_ctrl:1
	s_nop 1
	v_add_f32_dpp v102, v102, v102 quad_perm:[2,3,0,1] row_mask:0xf bank_mask:0xf bound_ctrl:1
	v_add_f32_dpp v103, v103, v103 quad_perm:[2,3,0,1] row_mask:0xf bank_mask:0xf bound_ctrl:1
	s_nop 1
	v_mov_b32_dpp v108, v102 row_half_mirror row_mask:0xf bank_mask:0xf bound_ctrl:1
	v_mov_b32_dpp v109, v103 row_half_mirror row_mask:0xf bank_mask:0xf bound_ctrl:1
	s_and_saveexec_b64 s[28:29], s[8:9]
	s_cbranch_execz .LBB0_879
	v_pk_add_f32 v[102:103], v[102:103], v[108:109]
	v_readlane_b32 s30, v253, 38
	v_pk_fma_f32 v[102:103], v[136:137], v[138:139], v[102:103] op_sel:[0,1,0]
	v_readlane_b32 s31, v253, 39
	v_pk_fma_f32 v[102:103], v[138:139], v[100:101], v[102:103] op_sel_hi:[0,1,1] neg_lo:[1,0,0] neg_hi:[1,0,0]
	s_nop 0
	v_lshl_add_u64 v[108:109], v[134:135], 0, s[30:31]
	flat_store_dwordx2 v[108:109], v[102:103]
.LBB0_879:
	s_or_b64 exec, exec, s[28:29]
	v_pk_mul_f32 v[102:103], v[88:89], v[100:101] op_sel_hi:[1,0]
	v_pk_mul_f32 v[88:89], v[88:89], v[100:101] op_sel:[0,1]
	v_pk_fma_f32 v[102:103], v[84:85], v[136:137], v[102:103] op_sel_hi:[1,0,1] neg_lo:[0,0,1] neg_hi:[0,0,1]
	v_pk_fma_f32 v[84:85], v[84:85], v[136:137], v[88:89] op_sel:[0,1,0] neg_lo:[0,0,1] neg_hi:[0,0,1]
	v_pk_fma_f32 v[122:123], v[76:77], v[116:117], v[102:103]
	v_pk_fma_f32 v[130:131], v[76:77], v[118:119], v[84:85]
	v_pk_mul_f32 v[76:77], v[90:91], v[100:101] op_sel_hi:[1,0]
	v_pk_mul_f32 v[84:85], v[90:91], v[100:101] op_sel:[0,1]
	v_pk_fma_f32 v[76:77], v[86:87], v[136:137], v[76:77] op_sel_hi:[1,0,1] neg_lo:[0,0,1] neg_hi:[0,0,1]
	v_pk_fma_f32 v[84:85], v[86:87], v[136:137], v[84:85] op_sel:[0,1,0] neg_lo:[0,0,1] neg_hi:[0,0,1]
	v_pk_fma_f32 v[138:139], v[78:79], v[140:141], v[76:77]
	v_pk_mul_f32 v[76:77], v[64:65], v[100:101] op_sel_hi:[1,0]
	v_pk_mul_f32 v[64:65], v[64:65], v[100:101] op_sel:[0,1]
	v_pk_fma_f32 v[140:141], v[78:79], v[148:149], v[84:85]
	v_pk_fma_f32 v[76:77], v[48:49], v[136:137], v[76:77] op_sel_hi:[1,0,1] neg_lo:[0,0,1] neg_hi:[0,0,1]
	v_pk_fma_f32 v[48:49], v[48:49], v[136:137], v[64:65] op_sel:[0,1,0] neg_lo:[0,0,1] neg_hi:[0,0,1]
	v_pk_fma_f32 v[142:143], v[40:41], v[142:143], v[76:77]
	v_pk_fma_f32 v[146:147], v[40:41], v[60:61], v[48:49]
	v_pk_mul_f32 v[40:41], v[66:67], v[100:101] op_sel_hi:[1,0]
	v_pk_mul_f32 v[48:49], v[66:67], v[100:101] op_sel:[0,1]
	s_waitcnt lgkmcnt(0)
	v_pk_mul_f32 v[148:149], v[114:115], v[138:139]
	v_pk_mul_f32 v[114:115], v[114:115], v[140:141]
	v_pk_fma_f32 v[40:41], v[50:51], v[136:137], v[40:41] op_sel_hi:[1,0,1] neg_lo:[0,0,1] neg_hi:[0,0,1]
	v_pk_fma_f32 v[48:49], v[50:51], v[136:137], v[48:49] op_sel:[0,1,0] neg_lo:[0,0,1] neg_hi:[0,0,1]
	v_pk_fma_f32 v[148:149], v[112:113], v[122:123], v[148:149]
	v_pk_fma_f32 v[112:113], v[112:113], v[130:131], v[114:115]
	v_pk_mul_f32 v[114:115], v[106:107], v[138:139]
	v_pk_mul_f32 v[106:107], v[106:107], v[140:141]
	v_pk_fma_f32 v[136:137], v[42:43], v[144:145], v[40:41]
	v_pk_fma_f32 v[144:145], v[42:43], v[62:63], v[48:49]
	v_pk_fma_f32 v[114:115], v[104:105], v[122:123], v[114:115]
	v_pk_fma_f32 v[104:105], v[104:105], v[130:131], v[106:107]
	v_pk_fma_f32 v[106:107], v[92:93], v[142:143], v[148:149]
	v_pk_fma_f32 v[92:93], v[92:93], v[146:147], v[112:113]
	ds_read_b128 v[88:91], v160 offset:6288
	ds_read_b128 v[64:67], v160 offset:6528
	ds_read_b128 v[40:43], v160 offset:6544
	ds_read_b128 v[76:79], v160 offset:6784
	ds_read_b128 v[48:51], v160 offset:6800
	ds_read_b128 v[84:87], v160 offset:7040
	ds_read_b128 v[60:63], v160 offset:7056
	ds_read_b128 v[108:111], v160 offset:7296
	ds_read_b128 v[100:103], v160 offset:7312
	ds_read_b64 v[120:121], v161 offset:7552
	ds_read_b128 v[116:119], v160 offset:6272
	ds_read_b64 v[128:129], v159 offset:7808
	v_pk_fma_f32 v[112:113], v[96:97], v[142:143], v[114:115]
	v_pk_fma_f32 v[96:97], v[96:97], v[146:147], v[104:105]
	v_pk_fma_f32 v[104:105], v[94:95], v[136:137], v[106:107]
	v_pk_fma_f32 v[92:93], v[94:95], v[144:145], v[92:93]
	v_pk_fma_f32 v[94:95], v[98:99], v[136:137], v[112:113]
	v_pk_fma_f32 v[96:97], v[98:99], v[144:145], v[96:97]
	v_add_f32_e32 v93, v92, v93
	v_add_f32_e32 v92, v104, v105
	s_nop 1
	v_add_f32_dpp v92, v92, v92 quad_perm:[1,0,3,2] row_mask:0xf bank_mask:0xf bound_ctrl:1
	v_add_f32_dpp v93, v93, v93 quad_perm:[1,0,3,2] row_mask:0xf bank_mask:0xf bound_ctrl:1
	s_nop 1
	v_add_f32_dpp v92, v92, v92 quad_perm:[2,3,0,1] row_mask:0xf bank_mask:0xf bound_ctrl:1
	v_add_f32_dpp v93, v93, v93 quad_perm:[2,3,0,1] row_mask:0xf bank_mask:0xf bound_ctrl:1
	s_nop 1
	v_add_f32_dpp v92, v92, v92 row_half_mirror row_mask:0xf bank_mask:0xf bound_ctrl:1
	v_add_f32_dpp v93, v93, v93 row_half_mirror row_mask:0xf bank_mask:0xf bound_ctrl:1
	v_add_f32_e32 v94, v94, v95
	v_add_f32_e32 v95, v96, v97
	s_nop 1
	v_add_f32_dpp v94, v94, v94 quad_perm:[1,0,3,2] row_mask:0xf bank_mask:0xf bound_ctrl:1
	v_add_f32_dpp v95, v95, v95 quad_perm:[1,0,3,2] row_mask:0xf bank_mask:0xf bound_ctrl:1
	s_nop 1
	v_add_f32_dpp v94, v94, v94 quad_perm:[2,3,0,1] row_mask:0xf bank_mask:0xf bound_ctrl:1
	v_add_f32_dpp v95, v95, v95 quad_perm:[2,3,0,1] row_mask:0xf bank_mask:0xf bound_ctrl:1
	s_nop 1
	v_mov_b32_dpp v96, v94 row_half_mirror row_mask:0xf bank_mask:0xf bound_ctrl:1
	v_mov_b32_dpp v97, v95 row_half_mirror row_mask:0xf bank_mask:0xf bound_ctrl:1
	s_and_saveexec_b64 s[28:29], s[8:9]
	s_cbranch_execz .LBB0_881
	v_pk_add_f32 v[94:95], v[94:95], v[96:97]
	v_readlane_b32 s30, v253, 63
	v_pk_fma_f32 v[94:95], v[124:125], v[126:127], v[94:95] op_sel:[0,1,0]
	v_readlane_b32 s31, v254, 0
	v_pk_fma_f32 v[94:95], v[126:127], v[92:93], v[94:95] op_sel_hi:[0,1,1] neg_lo:[1,0,0] neg_hi:[1,0,0]
	s_nop 0
	v_lshl_add_u64 v[96:97], v[134:135], 0, s[30:31]
	flat_store_dwordx2 v[96:97], v[94:95]
.LBB0_881:
	s_or_b64 exec, exec, s[28:29]
	v_pk_mul_f32 v[94:95], v[80:81], v[92:93] op_sel_hi:[1,0]
	v_pk_mul_f32 v[80:81], v[80:81], v[92:93] op_sel:[0,1]
	v_pk_fma_f32 v[94:95], v[72:73], v[124:125], v[94:95] op_sel_hi:[1,0,1] neg_lo:[0,0,1] neg_hi:[0,0,1]
	v_pk_fma_f32 v[72:73], v[72:73], v[124:125], v[80:81] op_sel:[0,1,0] neg_lo:[0,0,1] neg_hi:[0,0,1]
	v_pk_fma_f32 v[126:127], v[68:69], v[122:123], v[94:95]
	v_pk_fma_f32 v[130:131], v[68:69], v[130:131], v[72:73]
	v_pk_mul_f32 v[68:69], v[82:83], v[92:93] op_sel_hi:[1,0]
	v_pk_mul_f32 v[72:73], v[82:83], v[92:93] op_sel:[0,1]
	v_pk_fma_f32 v[68:69], v[74:75], v[124:125], v[68:69] op_sel_hi:[1,0,1] neg_lo:[0,0,1] neg_hi:[0,0,1]
	v_pk_fma_f32 v[72:73], v[74:75], v[124:125], v[72:73] op_sel:[0,1,0] neg_lo:[0,0,1] neg_hi:[0,0,1]
	v_pk_fma_f32 v[138:139], v[70:71], v[138:139], v[68:69]
	v_pk_mul_f32 v[68:69], v[56:57], v[92:93] op_sel_hi:[1,0]
	v_pk_mul_f32 v[56:57], v[56:57], v[92:93] op_sel:[0,1]
	v_pk_fma_f32 v[140:141], v[70:71], v[140:141], v[72:73]
	v_pk_fma_f32 v[68:69], v[52:53], v[124:125], v[68:69] op_sel_hi:[1,0,1] neg_lo:[0,0,1] neg_hi:[0,0,1]
	v_pk_fma_f32 v[52:53], v[52:53], v[124:125], v[56:57] op_sel:[0,1,0] neg_lo:[0,0,1] neg_hi:[0,0,1]
	v_pk_fma_f32 v[142:143], v[44:45], v[142:143], v[68:69]
	v_pk_fma_f32 v[146:147], v[44:45], v[146:147], v[52:53]
	v_pk_mul_f32 v[44:45], v[58:59], v[92:93] op_sel_hi:[1,0]
	v_pk_mul_f32 v[52:53], v[58:59], v[92:93] op_sel:[0,1]
	s_waitcnt lgkmcnt(0)
	v_pk_mul_f32 v[148:149], v[118:119], v[138:139]
	v_pk_mul_f32 v[118:119], v[118:119], v[140:141]
	v_pk_fma_f32 v[44:45], v[54:55], v[124:125], v[44:45] op_sel_hi:[1,0,1] neg_lo:[0,0,1] neg_hi:[0,0,1]
	v_pk_fma_f32 v[52:53], v[54:55], v[124:125], v[52:53] op_sel:[0,1,0] neg_lo:[0,0,1] neg_hi:[0,0,1]
	v_pk_fma_f32 v[148:149], v[116:117], v[126:127], v[148:149]
	v_pk_fma_f32 v[116:117], v[116:117], v[130:131], v[118:119]
	v_pk_mul_f32 v[118:119], v[110:111], v[138:139]
	v_pk_mul_f32 v[110:111], v[110:111], v[140:141]
	v_pk_fma_f32 v[136:137], v[46:47], v[136:137], v[44:45]
	v_pk_fma_f32 v[144:145], v[46:47], v[144:145], v[52:53]
	v_pk_fma_f32 v[118:119], v[108:109], v[126:127], v[118:119]
	v_pk_fma_f32 v[108:109], v[108:109], v[130:131], v[110:111]
	v_pk_fma_f32 v[110:111], v[88:89], v[142:143], v[148:149]
	v_pk_fma_f32 v[88:89], v[88:89], v[146:147], v[116:117]
	ds_read_b128 v[92:95], v160 offset:7856
	ds_read_b128 v[68:71], v160 offset:8096
	ds_read_b128 v[44:47], v160 offset:8112
	ds_read_b128 v[72:75], v160 offset:8352
	ds_read_b128 v[52:55], v160 offset:8368
	ds_read_b128 v[80:83], v160 offset:8608
	ds_read_b128 v[56:59], v160 offset:8624
	ds_read_b128 v[104:107], v160 offset:8864
	ds_read_b128 v[96:99], v160 offset:8880
	ds_read_b64 v[122:123], v161 offset:9120
	ds_read_b128 v[112:115], v160 offset:7840
	ds_read_b64 v[124:125], v159 offset:9376
	v_pk_fma_f32 v[116:117], v[100:101], v[142:143], v[118:119]
	v_pk_fma_f32 v[100:101], v[100:101], v[146:147], v[108:109]
	v_pk_fma_f32 v[108:109], v[90:91], v[136:137], v[110:111]
	v_pk_fma_f32 v[88:89], v[90:91], v[144:145], v[88:89]
	v_pk_fma_f32 v[90:91], v[102:103], v[136:137], v[116:117]
	v_pk_fma_f32 v[100:101], v[102:103], v[144:145], v[100:101]
	v_add_f32_e32 v89, v88, v89
	v_add_f32_e32 v88, v108, v109
	s_nop 1
	v_add_f32_dpp v88, v88, v88 quad_perm:[1,0,3,2] row_mask:0xf bank_mask:0xf bound_ctrl:1
	v_add_f32_dpp v89, v89, v89 quad_perm:[1,0,3,2] row_mask:0xf bank_mask:0xf bound_ctrl:1
	s_nop 1
	v_add_f32_dpp v88, v88, v88 quad_perm:[2,3,0,1] row_mask:0xf bank_mask:0xf bound_ctrl:1
	v_add_f32_dpp v89, v89, v89 quad_perm:[2,3,0,1] row_mask:0xf bank_mask:0xf bound_ctrl:1
	s_nop 1
	v_add_f32_dpp v88, v88, v88 row_half_mirror row_mask:0xf bank_mask:0xf bound_ctrl:1
	v_add_f32_dpp v89, v89, v89 row_half_mirror row_mask:0xf bank_mask:0xf bound_ctrl:1
	v_add_f32_e32 v90, v90, v91
	v_add_f32_e32 v91, v100, v101
	s_nop 1
	v_add_f32_dpp v90, v90, v90 quad_perm:[1,0,3,2] row_mask:0xf bank_mask:0xf bound_ctrl:1
	v_add_f32_dpp v91, v91, v91 quad_perm:[1,0,3,2] row_mask:0xf bank_mask:0xf bound_ctrl:1
	s_nop 1
	v_add_f32_dpp v90, v90, v90 quad_perm:[2,3,0,1] row_mask:0xf bank_mask:0xf bound_ctrl:1
	v_add_f32_dpp v91, v91, v91 quad_perm:[2,3,0,1] row_mask:0xf bank_mask:0xf bound_ctrl:1
	s_nop 1
	v_mov_b32_dpp v100, v90 row_half_mirror row_mask:0xf bank_mask:0xf bound_ctrl:1
	v_mov_b32_dpp v101, v91 row_half_mirror row_mask:0xf bank_mask:0xf bound_ctrl:1
	s_and_saveexec_b64 s[28:29], s[8:9]
	s_cbranch_execz .LBB0_883
	v_pk_add_f32 v[90:91], v[90:91], v[100:101]
	v_readlane_b32 s30, v253, 40
	v_pk_fma_f32 v[90:91], v[120:121], v[128:129], v[90:91] op_sel:[0,1,0]
	v_readlane_b32 s31, v253, 41
	v_pk_fma_f32 v[90:91], v[128:129], v[88:89], v[90:91] op_sel_hi:[0,1,1] neg_lo:[1,0,0] neg_hi:[1,0,0]
	s_nop 0
	v_lshl_add_u64 v[100:101], v[134:135], 0, s[30:31]
	flat_store_dwordx2 v[100:101], v[90:91]
.LBB0_883:
	s_or_b64 exec, exec, s[28:29]
	v_pk_mul_f32 v[90:91], v[84:85], v[88:89] op_sel_hi:[1,0]
	v_pk_mul_f32 v[84:85], v[84:85], v[88:89] op_sel:[0,1]
	v_pk_fma_f32 v[90:91], v[76:77], v[120:121], v[90:91] op_sel_hi:[1,0,1] neg_lo:[0,0,1] neg_hi:[0,0,1]
	v_pk_fma_f32 v[76:77], v[76:77], v[120:121], v[84:85] op_sel:[0,1,0] neg_lo:[0,0,1] neg_hi:[0,0,1]
	v_pk_fma_f32 v[128:129], v[64:65], v[126:127], v[90:91]
	v_pk_fma_f32 v[130:131], v[64:65], v[130:131], v[76:77]
	v_pk_mul_f32 v[64:65], v[86:87], v[88:89] op_sel_hi:[1,0]
	v_pk_mul_f32 v[76:77], v[86:87], v[88:89] op_sel:[0,1]
	v_pk_fma_f32 v[64:65], v[78:79], v[120:121], v[64:65] op_sel_hi:[1,0,1] neg_lo:[0,0,1] neg_hi:[0,0,1]
	v_pk_fma_f32 v[76:77], v[78:79], v[120:121], v[76:77] op_sel:[0,1,0] neg_lo:[0,0,1] neg_hi:[0,0,1]
	v_pk_fma_f32 v[138:139], v[66:67], v[138:139], v[64:65]
	v_pk_mul_f32 v[64:65], v[60:61], v[88:89] op_sel_hi:[1,0]
	v_pk_mul_f32 v[60:61], v[60:61], v[88:89] op_sel:[0,1]
	v_pk_fma_f32 v[140:141], v[66:67], v[140:141], v[76:77]
	v_pk_fma_f32 v[64:65], v[48:49], v[120:121], v[64:65] op_sel_hi:[1,0,1] neg_lo:[0,0,1] neg_hi:[0,0,1]
	v_pk_fma_f32 v[48:49], v[48:49], v[120:121], v[60:61] op_sel:[0,1,0] neg_lo:[0,0,1] neg_hi:[0,0,1]
	v_pk_fma_f32 v[142:143], v[40:41], v[142:143], v[64:65]
	v_pk_fma_f32 v[146:147], v[40:41], v[146:147], v[48:49]
	v_pk_mul_f32 v[40:41], v[62:63], v[88:89] op_sel_hi:[1,0]
	v_pk_mul_f32 v[48:49], v[62:63], v[88:89] op_sel:[0,1]
	s_waitcnt lgkmcnt(0)
	v_pk_mul_f32 v[148:149], v[114:115], v[138:139]
	v_pk_mul_f32 v[114:115], v[114:115], v[140:141]
	v_pk_fma_f32 v[40:41], v[50:51], v[120:121], v[40:41] op_sel_hi:[1,0,1] neg_lo:[0,0,1] neg_hi:[0,0,1]
	v_pk_fma_f32 v[48:49], v[50:51], v[120:121], v[48:49] op_sel:[0,1,0] neg_lo:[0,0,1] neg_hi:[0,0,1]
	v_pk_fma_f32 v[148:149], v[112:113], v[128:129], v[148:149]
	v_pk_fma_f32 v[112:113], v[112:113], v[130:131], v[114:115]
	v_pk_mul_f32 v[114:115], v[106:107], v[138:139]
	v_pk_mul_f32 v[106:107], v[106:107], v[140:141]
	v_pk_fma_f32 v[136:137], v[42:43], v[136:137], v[40:41]
	v_pk_fma_f32 v[144:145], v[42:43], v[144:145], v[48:49]
	v_pk_fma_f32 v[114:115], v[104:105], v[128:129], v[114:115]
	v_pk_fma_f32 v[104:105], v[104:105], v[130:131], v[106:107]
	v_pk_fma_f32 v[106:107], v[92:93], v[142:143], v[148:149]
	v_pk_fma_f32 v[92:93], v[92:93], v[146:147], v[112:113]
	ds_read_b128 v[88:91], v160 offset:9424
	ds_read_b128 v[64:67], v160 offset:9664
	ds_read_b128 v[40:43], v160 offset:9680
	ds_read_b128 v[76:79], v160 offset:9920
	ds_read_b128 v[48:51], v160 offset:9936
	ds_read_b128 v[84:87], v160 offset:10176
	ds_read_b128 v[60:63], v160 offset:10192
	ds_read_b128 v[108:111], v160 offset:10432
	ds_read_b128 v[100:103], v160 offset:10448
	ds_read_b64 v[120:121], v161 offset:10688
	ds_read_b128 v[116:119], v160 offset:9408
	ds_read_b64 v[126:127], v159 offset:10944
	v_pk_fma_f32 v[112:113], v[96:97], v[142:143], v[114:115]
	v_pk_fma_f32 v[96:97], v[96:97], v[146:147], v[104:105]
	v_pk_fma_f32 v[104:105], v[94:95], v[136:137], v[106:107]
	v_pk_fma_f32 v[92:93], v[94:95], v[144:145], v[92:93]
	v_pk_fma_f32 v[94:95], v[98:99], v[136:137], v[112:113]
	v_pk_fma_f32 v[96:97], v[98:99], v[144:145], v[96:97]
	v_add_f32_e32 v93, v92, v93
	v_add_f32_e32 v92, v104, v105
	s_nop 1
	v_add_f32_dpp v92, v92, v92 quad_perm:[1,0,3,2] row_mask:0xf bank_mask:0xf bound_ctrl:1
	v_add_f32_dpp v93, v93, v93 quad_perm:[1,0,3,2] row_mask:0xf bank_mask:0xf bound_ctrl:1
	s_nop 1
	v_add_f32_dpp v92, v92, v92 quad_perm:[2,3,0,1] row_mask:0xf bank_mask:0xf bound_ctrl:1
	v_add_f32_dpp v93, v93, v93 quad_perm:[2,3,0,1] row_mask:0xf bank_mask:0xf bound_ctrl:1
	s_nop 1
	v_add_f32_dpp v92, v92, v92 row_half_mirror row_mask:0xf bank_mask:0xf bound_ctrl:1
	v_add_f32_dpp v93, v93, v93 row_half_mirror row_mask:0xf bank_mask:0xf bound_ctrl:1
	v_add_f32_e32 v94, v94, v95
	v_add_f32_e32 v95, v96, v97
	s_nop 1
	v_add_f32_dpp v94, v94, v94 quad_perm:[1,0,3,2] row_mask:0xf bank_mask:0xf bound_ctrl:1
	v_add_f32_dpp v95, v95, v95 quad_perm:[1,0,3,2] row_mask:0xf bank_mask:0xf bound_ctrl:1
	s_nop 1
	v_add_f32_dpp v94, v94, v94 quad_perm:[2,3,0,1] row_mask:0xf bank_mask:0xf bound_ctrl:1
	v_add_f32_dpp v95, v95, v95 quad_perm:[2,3,0,1] row_mask:0xf bank_mask:0xf bound_ctrl:1
	s_nop 1
	v_mov_b32_dpp v96, v94 row_half_mirror row_mask:0xf bank_mask:0xf bound_ctrl:1
	v_mov_b32_dpp v97, v95 row_half_mirror row_mask:0xf bank_mask:0xf bound_ctrl:1
	s_and_saveexec_b64 s[28:29], s[8:9]
	s_cbranch_execz .LBB0_885
	v_pk_add_f32 v[94:95], v[94:95], v[96:97]
	v_readlane_b32 s30, v254, 1
	v_pk_fma_f32 v[94:95], v[122:123], v[124:125], v[94:95] op_sel:[0,1,0]
	v_readlane_b32 s31, v254, 2
	v_pk_fma_f32 v[94:95], v[124:125], v[92:93], v[94:95] op_sel_hi:[0,1,1] neg_lo:[1,0,0] neg_hi:[1,0,0]
	s_nop 0
	v_lshl_add_u64 v[96:97], v[134:135], 0, s[30:31]
	flat_store_dwordx2 v[96:97], v[94:95]
.LBB0_885:
	s_or_b64 exec, exec, s[28:29]
	v_pk_mul_f32 v[94:95], v[80:81], v[92:93] op_sel_hi:[1,0]
	v_pk_mul_f32 v[80:81], v[80:81], v[92:93] op_sel:[0,1]
	v_pk_fma_f32 v[94:95], v[72:73], v[122:123], v[94:95] op_sel_hi:[1,0,1] neg_lo:[0,0,1] neg_hi:[0,0,1]
	v_pk_fma_f32 v[72:73], v[72:73], v[122:123], v[80:81] op_sel:[0,1,0] neg_lo:[0,0,1] neg_hi:[0,0,1]
	v_pk_fma_f32 v[128:129], v[68:69], v[128:129], v[94:95]
	v_pk_fma_f32 v[130:131], v[68:69], v[130:131], v[72:73]
	v_pk_mul_f32 v[68:69], v[82:83], v[92:93] op_sel_hi:[1,0]
	v_pk_mul_f32 v[72:73], v[82:83], v[92:93] op_sel:[0,1]
	v_pk_fma_f32 v[68:69], v[74:75], v[122:123], v[68:69] op_sel_hi:[1,0,1] neg_lo:[0,0,1] neg_hi:[0,0,1]
	v_pk_fma_f32 v[72:73], v[74:75], v[122:123], v[72:73] op_sel:[0,1,0] neg_lo:[0,0,1] neg_hi:[0,0,1]
	v_pk_fma_f32 v[138:139], v[70:71], v[138:139], v[68:69]
	v_pk_mul_f32 v[68:69], v[56:57], v[92:93] op_sel_hi:[1,0]
	v_pk_mul_f32 v[56:57], v[56:57], v[92:93] op_sel:[0,1]
	v_pk_fma_f32 v[140:141], v[70:71], v[140:141], v[72:73]
	v_pk_fma_f32 v[68:69], v[52:53], v[122:123], v[68:69] op_sel_hi:[1,0,1] neg_lo:[0,0,1] neg_hi:[0,0,1]
	v_pk_fma_f32 v[52:53], v[52:53], v[122:123], v[56:57] op_sel:[0,1,0] neg_lo:[0,0,1] neg_hi:[0,0,1]
	v_pk_fma_f32 v[142:143], v[44:45], v[142:143], v[68:69]
	v_pk_fma_f32 v[146:147], v[44:45], v[146:147], v[52:53]
	v_pk_mul_f32 v[44:45], v[58:59], v[92:93] op_sel_hi:[1,0]
	v_pk_mul_f32 v[52:53], v[58:59], v[92:93] op_sel:[0,1]
	s_waitcnt lgkmcnt(0)
	v_pk_mul_f32 v[148:149], v[118:119], v[138:139]
	v_pk_mul_f32 v[118:119], v[118:119], v[140:141]
	v_pk_fma_f32 v[44:45], v[54:55], v[122:123], v[44:45] op_sel_hi:[1,0,1] neg_lo:[0,0,1] neg_hi:[0,0,1]
	v_pk_fma_f32 v[52:53], v[54:55], v[122:123], v[52:53] op_sel:[0,1,0] neg_lo:[0,0,1] neg_hi:[0,0,1]
	v_pk_fma_f32 v[148:149], v[116:117], v[128:129], v[148:149]
	v_pk_fma_f32 v[116:117], v[116:117], v[130:131], v[118:119]
	v_pk_mul_f32 v[118:119], v[110:111], v[138:139]
	v_pk_mul_f32 v[110:111], v[110:111], v[140:141]
	v_pk_fma_f32 v[136:137], v[46:47], v[136:137], v[44:45]
	v_pk_fma_f32 v[144:145], v[46:47], v[144:145], v[52:53]
	v_pk_fma_f32 v[118:119], v[108:109], v[128:129], v[118:119]
	v_pk_fma_f32 v[108:109], v[108:109], v[130:131], v[110:111]
	v_pk_fma_f32 v[110:111], v[88:89], v[142:143], v[148:149]
	v_pk_fma_f32 v[88:89], v[88:89], v[146:147], v[116:117]
	ds_read_b128 v[92:95], v160 offset:10992
	ds_read_b128 v[68:71], v160 offset:11232
	ds_read_b128 v[44:47], v160 offset:11248
	ds_read_b128 v[72:75], v160 offset:11488
	ds_read_b128 v[52:55], v160 offset:11504
	ds_read_b128 v[80:83], v160 offset:11744
	ds_read_b128 v[56:59], v160 offset:11760
	ds_read_b128 v[104:107], v160 offset:12000
	ds_read_b128 v[96:99], v160 offset:12016
	ds_read_b64 v[122:123], v161 offset:12256
	ds_read_b128 v[112:115], v160 offset:10976
	ds_read_b64 v[124:125], v159 offset:12512
	v_pk_fma_f32 v[116:117], v[100:101], v[142:143], v[118:119]
	v_pk_fma_f32 v[100:101], v[100:101], v[146:147], v[108:109]
	v_pk_fma_f32 v[108:109], v[90:91], v[136:137], v[110:111]
	v_pk_fma_f32 v[88:89], v[90:91], v[144:145], v[88:89]
	v_pk_fma_f32 v[90:91], v[102:103], v[136:137], v[116:117]
	v_pk_fma_f32 v[100:101], v[102:103], v[144:145], v[100:101]
	v_add_f32_e32 v89, v88, v89
	v_add_f32_e32 v88, v108, v109
	s_nop 1
	v_add_f32_dpp v88, v88, v88 quad_perm:[1,0,3,2] row_mask:0xf bank_mask:0xf bound_ctrl:1
	v_add_f32_dpp v89, v89, v89 quad_perm:[1,0,3,2] row_mask:0xf bank_mask:0xf bound_ctrl:1
	s_nop 1
	v_add_f32_dpp v88, v88, v88 quad_perm:[2,3,0,1] row_mask:0xf bank_mask:0xf bound_ctrl:1
	v_add_f32_dpp v89, v89, v89 quad_perm:[2,3,0,1] row_mask:0xf bank_mask:0xf bound_ctrl:1
	s_nop 1
	v_add_f32_dpp v88, v88, v88 row_half_mirror row_mask:0xf bank_mask:0xf bound_ctrl:1
	v_add_f32_dpp v89, v89, v89 row_half_mirror row_mask:0xf bank_mask:0xf bound_ctrl:1
	v_add_f32_e32 v90, v90, v91
	v_add_f32_e32 v91, v100, v101
	s_nop 1
	v_add_f32_dpp v90, v90, v90 quad_perm:[1,0,3,2] row_mask:0xf bank_mask:0xf bound_ctrl:1
	v_add_f32_dpp v91, v91, v91 quad_perm:[1,0,3,2] row_mask:0xf bank_mask:0xf bound_ctrl:1
	s_nop 1
	v_add_f32_dpp v90, v90, v90 quad_perm:[2,3,0,1] row_mask:0xf bank_mask:0xf bound_ctrl:1
	v_add_f32_dpp v91, v91, v91 quad_perm:[2,3,0,1] row_mask:0xf bank_mask:0xf bound_ctrl:1
	s_nop 1
	v_mov_b32_dpp v100, v90 row_half_mirror row_mask:0xf bank_mask:0xf bound_ctrl:1
	v_mov_b32_dpp v101, v91 row_half_mirror row_mask:0xf bank_mask:0xf bound_ctrl:1
	s_and_saveexec_b64 s[28:29], s[8:9]
	s_cbranch_execz .LBB0_887
	v_pk_add_f32 v[90:91], v[90:91], v[100:101]
	v_readlane_b32 s30, v254, 3
	v_pk_fma_f32 v[90:91], v[120:121], v[126:127], v[90:91] op_sel:[0,1,0]
	v_readlane_b32 s31, v254, 4
	v_pk_fma_f32 v[90:91], v[126:127], v[88:89], v[90:91] op_sel_hi:[0,1,1] neg_lo:[1,0,0] neg_hi:[1,0,0]
	s_nop 0
	v_lshl_add_u64 v[100:101], v[134:135], 0, s[30:31]
	flat_store_dwordx2 v[100:101], v[90:91]
.LBB0_887:
	s_or_b64 exec, exec, s[28:29]
	v_pk_mul_f32 v[90:91], v[84:85], v[88:89] op_sel_hi:[1,0]
	v_pk_mul_f32 v[84:85], v[84:85], v[88:89] op_sel:[0,1]
	v_pk_fma_f32 v[90:91], v[76:77], v[120:121], v[90:91] op_sel_hi:[1,0,1] neg_lo:[0,0,1] neg_hi:[0,0,1]
	v_pk_fma_f32 v[76:77], v[76:77], v[120:121], v[84:85] op_sel:[0,1,0] neg_lo:[0,0,1] neg_hi:[0,0,1]
	v_pk_fma_f32 v[128:129], v[64:65], v[128:129], v[90:91]
	v_pk_fma_f32 v[130:131], v[64:65], v[130:131], v[76:77]
	v_pk_mul_f32 v[64:65], v[86:87], v[88:89] op_sel_hi:[1,0]
	v_pk_mul_f32 v[76:77], v[86:87], v[88:89] op_sel:[0,1]
	v_pk_fma_f32 v[64:65], v[78:79], v[120:121], v[64:65] op_sel_hi:[1,0,1] neg_lo:[0,0,1] neg_hi:[0,0,1]
	v_pk_fma_f32 v[76:77], v[78:79], v[120:121], v[76:77] op_sel:[0,1,0] neg_lo:[0,0,1] neg_hi:[0,0,1]
	v_pk_fma_f32 v[138:139], v[66:67], v[138:139], v[64:65]
	v_pk_mul_f32 v[64:65], v[60:61], v[88:89] op_sel_hi:[1,0]
	v_pk_mul_f32 v[60:61], v[60:61], v[88:89] op_sel:[0,1]
	v_pk_fma_f32 v[140:141], v[66:67], v[140:141], v[76:77]
	v_pk_fma_f32 v[64:65], v[48:49], v[120:121], v[64:65] op_sel_hi:[1,0,1] neg_lo:[0,0,1] neg_hi:[0,0,1]
	v_pk_fma_f32 v[48:49], v[48:49], v[120:121], v[60:61] op_sel:[0,1,0] neg_lo:[0,0,1] neg_hi:[0,0,1]
	v_pk_fma_f32 v[142:143], v[40:41], v[142:143], v[64:65]
	v_pk_fma_f32 v[146:147], v[40:41], v[146:147], v[48:49]
	v_pk_mul_f32 v[40:41], v[62:63], v[88:89] op_sel_hi:[1,0]
	v_pk_mul_f32 v[48:49], v[62:63], v[88:89] op_sel:[0,1]
	s_waitcnt lgkmcnt(0)
	v_pk_mul_f32 v[148:149], v[114:115], v[138:139]
	v_pk_mul_f32 v[114:115], v[114:115], v[140:141]
	v_pk_fma_f32 v[40:41], v[50:51], v[120:121], v[40:41] op_sel_hi:[1,0,1] neg_lo:[0,0,1] neg_hi:[0,0,1]
	v_pk_fma_f32 v[48:49], v[50:51], v[120:121], v[48:49] op_sel:[0,1,0] neg_lo:[0,0,1] neg_hi:[0,0,1]
	v_pk_fma_f32 v[148:149], v[112:113], v[128:129], v[148:149]
	v_pk_fma_f32 v[112:113], v[112:113], v[130:131], v[114:115]
	v_pk_mul_f32 v[114:115], v[106:107], v[138:139]
	v_pk_mul_f32 v[106:107], v[106:107], v[140:141]
	v_pk_fma_f32 v[136:137], v[42:43], v[136:137], v[40:41]
	v_pk_fma_f32 v[144:145], v[42:43], v[144:145], v[48:49]
	v_pk_fma_f32 v[114:115], v[104:105], v[128:129], v[114:115]
	v_pk_fma_f32 v[104:105], v[104:105], v[130:131], v[106:107]
	v_pk_fma_f32 v[106:107], v[92:93], v[142:143], v[148:149]
	v_pk_fma_f32 v[92:93], v[92:93], v[146:147], v[112:113]
	ds_read_b128 v[88:91], v160 offset:12560
	ds_read_b128 v[64:67], v160 offset:12800
	ds_read_b128 v[40:43], v160 offset:12816
	ds_read_b128 v[76:79], v160 offset:13056
	ds_read_b128 v[48:51], v160 offset:13072
	ds_read_b128 v[84:87], v160 offset:13312
	ds_read_b128 v[60:63], v160 offset:13328
	ds_read_b128 v[108:111], v160 offset:13568
	ds_read_b128 v[100:103], v160 offset:13584
	ds_read_b64 v[120:121], v161 offset:13824
	ds_read_b128 v[116:119], v160 offset:12544
	ds_read_b64 v[126:127], v159 offset:14080
	v_pk_fma_f32 v[112:113], v[96:97], v[142:143], v[114:115]
	v_pk_fma_f32 v[96:97], v[96:97], v[146:147], v[104:105]
	v_pk_fma_f32 v[104:105], v[94:95], v[136:137], v[106:107]
	v_pk_fma_f32 v[92:93], v[94:95], v[144:145], v[92:93]
	v_pk_fma_f32 v[94:95], v[98:99], v[136:137], v[112:113]
	v_pk_fma_f32 v[96:97], v[98:99], v[144:145], v[96:97]
	v_add_f32_e32 v93, v92, v93
	v_add_f32_e32 v92, v104, v105
	s_nop 1
	v_add_f32_dpp v92, v92, v92 quad_perm:[1,0,3,2] row_mask:0xf bank_mask:0xf bound_ctrl:1
	v_add_f32_dpp v93, v93, v93 quad_perm:[1,0,3,2] row_mask:0xf bank_mask:0xf bound_ctrl:1
	s_nop 1
	v_add_f32_dpp v92, v92, v92 quad_perm:[2,3,0,1] row_mask:0xf bank_mask:0xf bound_ctrl:1
	v_add_f32_dpp v93, v93, v93 quad_perm:[2,3,0,1] row_mask:0xf bank_mask:0xf bound_ctrl:1
	s_nop 1
	v_add_f32_dpp v92, v92, v92 row_half_mirror row_mask:0xf bank_mask:0xf bound_ctrl:1
	v_add_f32_dpp v93, v93, v93 row_half_mirror row_mask:0xf bank_mask:0xf bound_ctrl:1
	v_add_f32_e32 v94, v94, v95
	v_add_f32_e32 v95, v96, v97
	s_nop 1
	v_add_f32_dpp v94, v94, v94 quad_perm:[1,0,3,2] row_mask:0xf bank_mask:0xf bound_ctrl:1
	v_add_f32_dpp v95, v95, v95 quad_perm:[1,0,3,2] row_mask:0xf bank_mask:0xf bound_ctrl:1
	s_nop 1
	v_add_f32_dpp v94, v94, v94 quad_perm:[2,3,0,1] row_mask:0xf bank_mask:0xf bound_ctrl:1
	v_add_f32_dpp v95, v95, v95 quad_perm:[2,3,0,1] row_mask:0xf bank_mask:0xf bound_ctrl:1
	s_nop 1
	v_mov_b32_dpp v96, v94 row_half_mirror row_mask:0xf bank_mask:0xf bound_ctrl:1
	v_mov_b32_dpp v97, v95 row_half_mirror row_mask:0xf bank_mask:0xf bound_ctrl:1
	s_and_saveexec_b64 s[28:29], s[8:9]
	s_cbranch_execz .LBB0_889
	v_pk_add_f32 v[94:95], v[94:95], v[96:97]
	v_readlane_b32 s30, v254, 5
	v_pk_fma_f32 v[94:95], v[122:123], v[124:125], v[94:95] op_sel:[0,1,0]
	v_readlane_b32 s31, v254, 6
	v_pk_fma_f32 v[94:95], v[124:125], v[92:93], v[94:95] op_sel_hi:[0,1,1] neg_lo:[1,0,0] neg_hi:[1,0,0]
	s_nop 0
	v_lshl_add_u64 v[96:97], v[134:135], 0, s[30:31]
	flat_store_dwordx2 v[96:97], v[94:95]
.LBB0_889:
	s_or_b64 exec, exec, s[28:29]
	v_pk_mul_f32 v[94:95], v[80:81], v[92:93] op_sel_hi:[1,0]
	v_pk_mul_f32 v[80:81], v[80:81], v[92:93] op_sel:[0,1]
	v_pk_fma_f32 v[94:95], v[72:73], v[122:123], v[94:95] op_sel_hi:[1,0,1] neg_lo:[0,0,1] neg_hi:[0,0,1]
	v_pk_fma_f32 v[72:73], v[72:73], v[122:123], v[80:81] op_sel:[0,1,0] neg_lo:[0,0,1] neg_hi:[0,0,1]
	v_pk_fma_f32 v[128:129], v[68:69], v[128:129], v[94:95]
	v_pk_fma_f32 v[130:131], v[68:69], v[130:131], v[72:73]
	v_pk_mul_f32 v[68:69], v[82:83], v[92:93] op_sel_hi:[1,0]
	v_pk_mul_f32 v[72:73], v[82:83], v[92:93] op_sel:[0,1]
	v_pk_fma_f32 v[68:69], v[74:75], v[122:123], v[68:69] op_sel_hi:[1,0,1] neg_lo:[0,0,1] neg_hi:[0,0,1]
	v_pk_fma_f32 v[72:73], v[74:75], v[122:123], v[72:73] op_sel:[0,1,0] neg_lo:[0,0,1] neg_hi:[0,0,1]
	v_pk_fma_f32 v[138:139], v[70:71], v[138:139], v[68:69]
	v_pk_mul_f32 v[68:69], v[56:57], v[92:93] op_sel_hi:[1,0]
	v_pk_mul_f32 v[56:57], v[56:57], v[92:93] op_sel:[0,1]
	v_pk_fma_f32 v[140:141], v[70:71], v[140:141], v[72:73]
	v_pk_fma_f32 v[68:69], v[52:53], v[122:123], v[68:69] op_sel_hi:[1,0,1] neg_lo:[0,0,1] neg_hi:[0,0,1]
	v_pk_fma_f32 v[52:53], v[52:53], v[122:123], v[56:57] op_sel:[0,1,0] neg_lo:[0,0,1] neg_hi:[0,0,1]
	v_pk_fma_f32 v[142:143], v[44:45], v[142:143], v[68:69]
	v_pk_fma_f32 v[146:147], v[44:45], v[146:147], v[52:53]
	v_pk_mul_f32 v[44:45], v[58:59], v[92:93] op_sel_hi:[1,0]
	v_pk_mul_f32 v[52:53], v[58:59], v[92:93] op_sel:[0,1]
	s_waitcnt lgkmcnt(0)
	v_pk_mul_f32 v[148:149], v[118:119], v[138:139]
	v_pk_mul_f32 v[118:119], v[118:119], v[140:141]
	v_pk_fma_f32 v[44:45], v[54:55], v[122:123], v[44:45] op_sel_hi:[1,0,1] neg_lo:[0,0,1] neg_hi:[0,0,1]
	v_pk_fma_f32 v[52:53], v[54:55], v[122:123], v[52:53] op_sel:[0,1,0] neg_lo:[0,0,1] neg_hi:[0,0,1]
	v_pk_fma_f32 v[148:149], v[116:117], v[128:129], v[148:149]
	v_pk_fma_f32 v[116:117], v[116:117], v[130:131], v[118:119]
	v_pk_mul_f32 v[118:119], v[110:111], v[138:139]
	v_pk_mul_f32 v[110:111], v[110:111], v[140:141]
	v_pk_fma_f32 v[136:137], v[46:47], v[136:137], v[44:45]
	v_pk_fma_f32 v[144:145], v[46:47], v[144:145], v[52:53]
	v_pk_fma_f32 v[118:119], v[108:109], v[128:129], v[118:119]
	v_pk_fma_f32 v[108:109], v[108:109], v[130:131], v[110:111]
	v_pk_fma_f32 v[110:111], v[88:89], v[142:143], v[148:149]
	v_pk_fma_f32 v[88:89], v[88:89], v[146:147], v[116:117]
	ds_read_b128 v[92:95], v160 offset:14128
	ds_read_b128 v[68:71], v160 offset:14368
	ds_read_b128 v[44:47], v160 offset:14384
	ds_read_b128 v[72:75], v160 offset:14624
	ds_read_b128 v[52:55], v160 offset:14640
	ds_read_b128 v[80:83], v160 offset:14880
	ds_read_b128 v[56:59], v160 offset:14896
	ds_read_b128 v[104:107], v160 offset:15136
	ds_read_b128 v[96:99], v160 offset:15152
	ds_read_b64 v[122:123], v161 offset:15392
	ds_read_b128 v[112:115], v160 offset:14112
	ds_read_b64 v[124:125], v159 offset:15648
	v_pk_fma_f32 v[116:117], v[100:101], v[142:143], v[118:119]
	v_pk_fma_f32 v[100:101], v[100:101], v[146:147], v[108:109]
	v_pk_fma_f32 v[108:109], v[90:91], v[136:137], v[110:111]
	v_pk_fma_f32 v[88:89], v[90:91], v[144:145], v[88:89]
	v_pk_fma_f32 v[90:91], v[102:103], v[136:137], v[116:117]
	v_pk_fma_f32 v[100:101], v[102:103], v[144:145], v[100:101]
	v_add_f32_e32 v89, v88, v89
	v_add_f32_e32 v88, v108, v109
	s_nop 1
	v_add_f32_dpp v88, v88, v88 quad_perm:[1,0,3,2] row_mask:0xf bank_mask:0xf bound_ctrl:1
	v_add_f32_dpp v89, v89, v89 quad_perm:[1,0,3,2] row_mask:0xf bank_mask:0xf bound_ctrl:1
	s_nop 1
	v_add_f32_dpp v88, v88, v88 quad_perm:[2,3,0,1] row_mask:0xf bank_mask:0xf bound_ctrl:1
	v_add_f32_dpp v89, v89, v89 quad_perm:[2,3,0,1] row_mask:0xf bank_mask:0xf bound_ctrl:1
	s_nop 1
	v_add_f32_dpp v88, v88, v88 row_half_mirror row_mask:0xf bank_mask:0xf bound_ctrl:1
	v_add_f32_dpp v89, v89, v89 row_half_mirror row_mask:0xf bank_mask:0xf bound_ctrl:1
	v_add_f32_e32 v90, v90, v91
	v_add_f32_e32 v91, v100, v101
	s_nop 1
	v_add_f32_dpp v90, v90, v90 quad_perm:[1,0,3,2] row_mask:0xf bank_mask:0xf bound_ctrl:1
	v_add_f32_dpp v91, v91, v91 quad_perm:[1,0,3,2] row_mask:0xf bank_mask:0xf bound_ctrl:1
	s_nop 1
	v_add_f32_dpp v90, v90, v90 quad_perm:[2,3,0,1] row_mask:0xf bank_mask:0xf bound_ctrl:1
	v_add_f32_dpp v91, v91, v91 quad_perm:[2,3,0,1] row_mask:0xf bank_mask:0xf bound_ctrl:1
	s_nop 1
	v_mov_b32_dpp v100, v90 row_half_mirror row_mask:0xf bank_mask:0xf bound_ctrl:1
	v_mov_b32_dpp v101, v91 row_half_mirror row_mask:0xf bank_mask:0xf bound_ctrl:1
	s_and_saveexec_b64 s[28:29], s[8:9]
	s_cbranch_execz .LBB0_891
	v_pk_add_f32 v[90:91], v[90:91], v[100:101]
	v_readlane_b32 s30, v253, 42
	v_pk_fma_f32 v[90:91], v[120:121], v[126:127], v[90:91] op_sel:[0,1,0]
	v_readlane_b32 s31, v253, 43
	v_pk_fma_f32 v[90:91], v[126:127], v[88:89], v[90:91] op_sel_hi:[0,1,1] neg_lo:[1,0,0] neg_hi:[1,0,0]
	s_nop 0
	v_lshl_add_u64 v[100:101], v[134:135], 0, s[30:31]
	flat_store_dwordx2 v[100:101], v[90:91]
.LBB0_891:
	s_or_b64 exec, exec, s[28:29]
	v_pk_mul_f32 v[90:91], v[84:85], v[88:89] op_sel_hi:[1,0]
	v_pk_mul_f32 v[84:85], v[84:85], v[88:89] op_sel:[0,1]
	v_pk_fma_f32 v[90:91], v[76:77], v[120:121], v[90:91] op_sel_hi:[1,0,1] neg_lo:[0,0,1] neg_hi:[0,0,1]
	v_pk_fma_f32 v[76:77], v[76:77], v[120:121], v[84:85] op_sel:[0,1,0] neg_lo:[0,0,1] neg_hi:[0,0,1]
	v_pk_fma_f32 v[128:129], v[64:65], v[128:129], v[90:91]
	v_pk_fma_f32 v[130:131], v[64:65], v[130:131], v[76:77]
	v_pk_mul_f32 v[64:65], v[86:87], v[88:89] op_sel_hi:[1,0]
	v_pk_mul_f32 v[76:77], v[86:87], v[88:89] op_sel:[0,1]
	v_pk_fma_f32 v[64:65], v[78:79], v[120:121], v[64:65] op_sel_hi:[1,0,1] neg_lo:[0,0,1] neg_hi:[0,0,1]
	v_pk_fma_f32 v[76:77], v[78:79], v[120:121], v[76:77] op_sel:[0,1,0] neg_lo:[0,0,1] neg_hi:[0,0,1]
	v_pk_fma_f32 v[138:139], v[66:67], v[138:139], v[64:65]
	v_pk_mul_f32 v[64:65], v[60:61], v[88:89] op_sel_hi:[1,0]
	v_pk_mul_f32 v[60:61], v[60:61], v[88:89] op_sel:[0,1]
	v_pk_fma_f32 v[140:141], v[66:67], v[140:141], v[76:77]
	v_pk_fma_f32 v[64:65], v[48:49], v[120:121], v[64:65] op_sel_hi:[1,0,1] neg_lo:[0,0,1] neg_hi:[0,0,1]
	v_pk_fma_f32 v[48:49], v[48:49], v[120:121], v[60:61] op_sel:[0,1,0] neg_lo:[0,0,1] neg_hi:[0,0,1]
	v_pk_fma_f32 v[142:143], v[40:41], v[142:143], v[64:65]
	v_pk_fma_f32 v[146:147], v[40:41], v[146:147], v[48:49]
	v_pk_mul_f32 v[40:41], v[62:63], v[88:89] op_sel_hi:[1,0]
	v_pk_mul_f32 v[48:49], v[62:63], v[88:89] op_sel:[0,1]
	s_waitcnt lgkmcnt(0)
	v_pk_mul_f32 v[148:149], v[114:115], v[138:139]
	v_pk_mul_f32 v[114:115], v[114:115], v[140:141]
	v_pk_fma_f32 v[40:41], v[50:51], v[120:121], v[40:41] op_sel_hi:[1,0,1] neg_lo:[0,0,1] neg_hi:[0,0,1]
	v_pk_fma_f32 v[48:49], v[50:51], v[120:121], v[48:49] op_sel:[0,1,0] neg_lo:[0,0,1] neg_hi:[0,0,1]
	v_pk_fma_f32 v[148:149], v[112:113], v[128:129], v[148:149]
	v_pk_fma_f32 v[112:113], v[112:113], v[130:131], v[114:115]
	v_pk_mul_f32 v[114:115], v[106:107], v[138:139]
	v_pk_mul_f32 v[106:107], v[106:107], v[140:141]
	v_pk_fma_f32 v[136:137], v[42:43], v[136:137], v[40:41]
	v_pk_fma_f32 v[144:145], v[42:43], v[144:145], v[48:49]
	v_pk_fma_f32 v[114:115], v[104:105], v[128:129], v[114:115]
	v_pk_fma_f32 v[104:105], v[104:105], v[130:131], v[106:107]
	v_pk_fma_f32 v[106:107], v[92:93], v[142:143], v[148:149]
	v_pk_fma_f32 v[92:93], v[92:93], v[146:147], v[112:113]
	ds_read_b128 v[88:91], v160 offset:15696
	ds_read_b128 v[64:67], v160 offset:15936
	ds_read_b128 v[40:43], v160 offset:15952
	ds_read_b128 v[76:79], v160 offset:16192
	ds_read_b128 v[48:51], v160 offset:16208
	ds_read_b128 v[84:87], v160 offset:16448
	ds_read_b128 v[60:63], v160 offset:16464
	ds_read_b128 v[108:111], v160 offset:16704
	ds_read_b128 v[100:103], v160 offset:16720
	ds_read_b64 v[120:121], v161 offset:16960
	ds_read_b128 v[116:119], v160 offset:15680
	ds_read_b64 v[126:127], v159 offset:17216
	v_pk_fma_f32 v[112:113], v[96:97], v[142:143], v[114:115]
	v_pk_fma_f32 v[96:97], v[96:97], v[146:147], v[104:105]
	v_pk_fma_f32 v[104:105], v[94:95], v[136:137], v[106:107]
	v_pk_fma_f32 v[92:93], v[94:95], v[144:145], v[92:93]
	v_pk_fma_f32 v[94:95], v[98:99], v[136:137], v[112:113]
	v_pk_fma_f32 v[96:97], v[98:99], v[144:145], v[96:97]
	v_add_f32_e32 v93, v92, v93
	v_add_f32_e32 v92, v104, v105
	s_nop 1
	v_add_f32_dpp v92, v92, v92 quad_perm:[1,0,3,2] row_mask:0xf bank_mask:0xf bound_ctrl:1
	v_add_f32_dpp v93, v93, v93 quad_perm:[1,0,3,2] row_mask:0xf bank_mask:0xf bound_ctrl:1
	s_nop 1
	v_add_f32_dpp v92, v92, v92 quad_perm:[2,3,0,1] row_mask:0xf bank_mask:0xf bound_ctrl:1
	v_add_f32_dpp v93, v93, v93 quad_perm:[2,3,0,1] row_mask:0xf bank_mask:0xf bound_ctrl:1
	s_nop 1
	v_add_f32_dpp v92, v92, v92 row_half_mirror row_mask:0xf bank_mask:0xf bound_ctrl:1
	v_add_f32_dpp v93, v93, v93 row_half_mirror row_mask:0xf bank_mask:0xf bound_ctrl:1
	v_add_f32_e32 v94, v94, v95
	v_add_f32_e32 v95, v96, v97
	s_nop 1
	v_add_f32_dpp v94, v94, v94 quad_perm:[1,0,3,2] row_mask:0xf bank_mask:0xf bound_ctrl:1
	v_add_f32_dpp v95, v95, v95 quad_perm:[1,0,3,2] row_mask:0xf bank_mask:0xf bound_ctrl:1
	s_nop 1
	v_add_f32_dpp v94, v94, v94 quad_perm:[2,3,0,1] row_mask:0xf bank_mask:0xf bound_ctrl:1
	v_add_f32_dpp v95, v95, v95 quad_perm:[2,3,0,1] row_mask:0xf bank_mask:0xf bound_ctrl:1
	s_nop 1
	v_mov_b32_dpp v96, v94 row_half_mirror row_mask:0xf bank_mask:0xf bound_ctrl:1
	v_mov_b32_dpp v97, v95 row_half_mirror row_mask:0xf bank_mask:0xf bound_ctrl:1
	s_and_saveexec_b64 s[28:29], s[8:9]
	s_cbranch_execz .LBB0_893
	v_pk_add_f32 v[94:95], v[94:95], v[96:97]
	v_readlane_b32 s30, v254, 7
	v_pk_fma_f32 v[94:95], v[122:123], v[124:125], v[94:95] op_sel:[0,1,0]
	v_readlane_b32 s31, v254, 8
	v_pk_fma_f32 v[94:95], v[124:125], v[92:93], v[94:95] op_sel_hi:[0,1,1] neg_lo:[1,0,0] neg_hi:[1,0,0]
	s_nop 0
	v_lshl_add_u64 v[96:97], v[134:135], 0, s[30:31]
	flat_store_dwordx2 v[96:97], v[94:95]
.LBB0_893:
	s_or_b64 exec, exec, s[28:29]
	v_pk_mul_f32 v[94:95], v[80:81], v[92:93] op_sel_hi:[1,0]
	v_pk_mul_f32 v[80:81], v[80:81], v[92:93] op_sel:[0,1]
	v_pk_fma_f32 v[94:95], v[72:73], v[122:123], v[94:95] op_sel_hi:[1,0,1] neg_lo:[0,0,1] neg_hi:[0,0,1]
	v_pk_fma_f32 v[72:73], v[72:73], v[122:123], v[80:81] op_sel:[0,1,0] neg_lo:[0,0,1] neg_hi:[0,0,1]
	v_pk_fma_f32 v[128:129], v[68:69], v[128:129], v[94:95]
	v_pk_fma_f32 v[130:131], v[68:69], v[130:131], v[72:73]
	v_pk_mul_f32 v[68:69], v[82:83], v[92:93] op_sel_hi:[1,0]
	v_pk_mul_f32 v[72:73], v[82:83], v[92:93] op_sel:[0,1]
	v_pk_fma_f32 v[68:69], v[74:75], v[122:123], v[68:69] op_sel_hi:[1,0,1] neg_lo:[0,0,1] neg_hi:[0,0,1]
	v_pk_fma_f32 v[72:73], v[74:75], v[122:123], v[72:73] op_sel:[0,1,0] neg_lo:[0,0,1] neg_hi:[0,0,1]
	v_pk_fma_f32 v[138:139], v[70:71], v[138:139], v[68:69]
	v_pk_mul_f32 v[68:69], v[56:57], v[92:93] op_sel_hi:[1,0]
	v_pk_mul_f32 v[56:57], v[56:57], v[92:93] op_sel:[0,1]
	v_pk_fma_f32 v[140:141], v[70:71], v[140:141], v[72:73]
	v_pk_fma_f32 v[68:69], v[52:53], v[122:123], v[68:69] op_sel_hi:[1,0,1] neg_lo:[0,0,1] neg_hi:[0,0,1]
	v_pk_fma_f32 v[52:53], v[52:53], v[122:123], v[56:57] op_sel:[0,1,0] neg_lo:[0,0,1] neg_hi:[0,0,1]
	v_pk_fma_f32 v[142:143], v[44:45], v[142:143], v[68:69]
	v_pk_fma_f32 v[146:147], v[44:45], v[146:147], v[52:53]
	v_pk_mul_f32 v[44:45], v[58:59], v[92:93] op_sel_hi:[1,0]
	v_pk_mul_f32 v[52:53], v[58:59], v[92:93] op_sel:[0,1]
	s_waitcnt lgkmcnt(0)
	v_pk_mul_f32 v[148:149], v[118:119], v[138:139]
	v_pk_mul_f32 v[118:119], v[118:119], v[140:141]
	v_pk_fma_f32 v[44:45], v[54:55], v[122:123], v[44:45] op_sel_hi:[1,0,1] neg_lo:[0,0,1] neg_hi:[0,0,1]
	v_pk_fma_f32 v[52:53], v[54:55], v[122:123], v[52:53] op_sel:[0,1,0] neg_lo:[0,0,1] neg_hi:[0,0,1]
	v_pk_fma_f32 v[148:149], v[116:117], v[128:129], v[148:149]
	v_pk_fma_f32 v[116:117], v[116:117], v[130:131], v[118:119]
	v_pk_mul_f32 v[118:119], v[110:111], v[138:139]
	v_pk_mul_f32 v[110:111], v[110:111], v[140:141]
	v_pk_fma_f32 v[136:137], v[46:47], v[136:137], v[44:45]
	v_pk_fma_f32 v[144:145], v[46:47], v[144:145], v[52:53]
	v_pk_fma_f32 v[118:119], v[108:109], v[128:129], v[118:119]
	v_pk_fma_f32 v[108:109], v[108:109], v[130:131], v[110:111]
	v_pk_fma_f32 v[110:111], v[88:89], v[142:143], v[148:149]
	v_pk_fma_f32 v[88:89], v[88:89], v[146:147], v[116:117]
	ds_read_b128 v[92:95], v160 offset:17264
	ds_read_b128 v[68:71], v160 offset:17504
	ds_read_b128 v[44:47], v160 offset:17520
	ds_read_b128 v[72:75], v160 offset:17760
	ds_read_b128 v[52:55], v160 offset:17776
	ds_read_b128 v[80:83], v160 offset:18016
	ds_read_b128 v[56:59], v160 offset:18032
	ds_read_b128 v[104:107], v160 offset:18272
	ds_read_b128 v[96:99], v160 offset:18288
	ds_read_b64 v[122:123], v161 offset:18528
	ds_read_b128 v[112:115], v160 offset:17248
	ds_read_b64 v[124:125], v159 offset:18784
	v_pk_fma_f32 v[116:117], v[100:101], v[142:143], v[118:119]
	v_pk_fma_f32 v[100:101], v[100:101], v[146:147], v[108:109]
	v_pk_fma_f32 v[108:109], v[90:91], v[136:137], v[110:111]
	v_pk_fma_f32 v[88:89], v[90:91], v[144:145], v[88:89]
	v_pk_fma_f32 v[90:91], v[102:103], v[136:137], v[116:117]
	v_pk_fma_f32 v[100:101], v[102:103], v[144:145], v[100:101]
	v_add_f32_e32 v89, v88, v89
	v_add_f32_e32 v88, v108, v109
	s_nop 1
	v_add_f32_dpp v88, v88, v88 quad_perm:[1,0,3,2] row_mask:0xf bank_mask:0xf bound_ctrl:1
	v_add_f32_dpp v89, v89, v89 quad_perm:[1,0,3,2] row_mask:0xf bank_mask:0xf bound_ctrl:1
	s_nop 1
	v_add_f32_dpp v88, v88, v88 quad_perm:[2,3,0,1] row_mask:0xf bank_mask:0xf bound_ctrl:1
	v_add_f32_dpp v89, v89, v89 quad_perm:[2,3,0,1] row_mask:0xf bank_mask:0xf bound_ctrl:1
	s_nop 1
	v_add_f32_dpp v88, v88, v88 row_half_mirror row_mask:0xf bank_mask:0xf bound_ctrl:1
	v_add_f32_dpp v89, v89, v89 row_half_mirror row_mask:0xf bank_mask:0xf bound_ctrl:1
	v_add_f32_e32 v90, v90, v91
	v_add_f32_e32 v91, v100, v101
	s_nop 1
	v_add_f32_dpp v90, v90, v90 quad_perm:[1,0,3,2] row_mask:0xf bank_mask:0xf bound_ctrl:1
	v_add_f32_dpp v91, v91, v91 quad_perm:[1,0,3,2] row_mask:0xf bank_mask:0xf bound_ctrl:1
	s_nop 1
	v_add_f32_dpp v90, v90, v90 quad_perm:[2,3,0,1] row_mask:0xf bank_mask:0xf bound_ctrl:1
	v_add_f32_dpp v91, v91, v91 quad_perm:[2,3,0,1] row_mask:0xf bank_mask:0xf bound_ctrl:1
	s_nop 1
	v_mov_b32_dpp v100, v90 row_half_mirror row_mask:0xf bank_mask:0xf bound_ctrl:1
	v_mov_b32_dpp v101, v91 row_half_mirror row_mask:0xf bank_mask:0xf bound_ctrl:1
	s_and_saveexec_b64 s[28:29], s[8:9]
	s_cbranch_execz .LBB0_895
	v_pk_add_f32 v[90:91], v[90:91], v[100:101]
	v_readlane_b32 s30, v254, 9
	v_pk_fma_f32 v[90:91], v[120:121], v[126:127], v[90:91] op_sel:[0,1,0]
	v_readlane_b32 s31, v254, 10
	v_pk_fma_f32 v[90:91], v[126:127], v[88:89], v[90:91] op_sel_hi:[0,1,1] neg_lo:[1,0,0] neg_hi:[1,0,0]
	s_nop 0
	v_lshl_add_u64 v[100:101], v[134:135], 0, s[30:31]
	flat_store_dwordx2 v[100:101], v[90:91]
.LBB0_895:
	s_or_b64 exec, exec, s[28:29]
	v_pk_mul_f32 v[90:91], v[84:85], v[88:89] op_sel_hi:[1,0]
	v_pk_mul_f32 v[84:85], v[84:85], v[88:89] op_sel:[0,1]
	v_pk_fma_f32 v[90:91], v[76:77], v[120:121], v[90:91] op_sel_hi:[1,0,1] neg_lo:[0,0,1] neg_hi:[0,0,1]
	v_pk_fma_f32 v[76:77], v[76:77], v[120:121], v[84:85] op_sel:[0,1,0] neg_lo:[0,0,1] neg_hi:[0,0,1]
	v_pk_fma_f32 v[128:129], v[64:65], v[128:129], v[90:91]
	v_pk_fma_f32 v[130:131], v[64:65], v[130:131], v[76:77]
	v_pk_mul_f32 v[64:65], v[86:87], v[88:89] op_sel_hi:[1,0]
	v_pk_mul_f32 v[76:77], v[86:87], v[88:89] op_sel:[0,1]
	v_pk_fma_f32 v[64:65], v[78:79], v[120:121], v[64:65] op_sel_hi:[1,0,1] neg_lo:[0,0,1] neg_hi:[0,0,1]
	v_pk_fma_f32 v[76:77], v[78:79], v[120:121], v[76:77] op_sel:[0,1,0] neg_lo:[0,0,1] neg_hi:[0,0,1]
	v_pk_fma_f32 v[138:139], v[66:67], v[138:139], v[64:65]
	v_pk_mul_f32 v[64:65], v[60:61], v[88:89] op_sel_hi:[1,0]
	v_pk_mul_f32 v[60:61], v[60:61], v[88:89] op_sel:[0,1]
	v_pk_fma_f32 v[140:141], v[66:67], v[140:141], v[76:77]
	v_pk_fma_f32 v[64:65], v[48:49], v[120:121], v[64:65] op_sel_hi:[1,0,1] neg_lo:[0,0,1] neg_hi:[0,0,1]
	v_pk_fma_f32 v[48:49], v[48:49], v[120:121], v[60:61] op_sel:[0,1,0] neg_lo:[0,0,1] neg_hi:[0,0,1]
	v_pk_fma_f32 v[142:143], v[40:41], v[142:143], v[64:65]
	v_pk_fma_f32 v[146:147], v[40:41], v[146:147], v[48:49]
	v_pk_mul_f32 v[40:41], v[62:63], v[88:89] op_sel_hi:[1,0]
	v_pk_mul_f32 v[48:49], v[62:63], v[88:89] op_sel:[0,1]
	s_waitcnt lgkmcnt(0)
	v_pk_mul_f32 v[148:149], v[114:115], v[138:139]
	v_pk_mul_f32 v[114:115], v[114:115], v[140:141]
	v_pk_fma_f32 v[40:41], v[50:51], v[120:121], v[40:41] op_sel_hi:[1,0,1] neg_lo:[0,0,1] neg_hi:[0,0,1]
	v_pk_fma_f32 v[48:49], v[50:51], v[120:121], v[48:49] op_sel:[0,1,0] neg_lo:[0,0,1] neg_hi:[0,0,1]
	v_pk_fma_f32 v[148:149], v[112:113], v[128:129], v[148:149]
	v_pk_fma_f32 v[112:113], v[112:113], v[130:131], v[114:115]
	v_pk_mul_f32 v[114:115], v[106:107], v[138:139]
	v_pk_mul_f32 v[106:107], v[106:107], v[140:141]
	v_pk_fma_f32 v[136:137], v[42:43], v[136:137], v[40:41]
	v_pk_fma_f32 v[144:145], v[42:43], v[144:145], v[48:49]
	v_pk_fma_f32 v[114:115], v[104:105], v[128:129], v[114:115]
	v_pk_fma_f32 v[104:105], v[104:105], v[130:131], v[106:107]
	v_pk_fma_f32 v[106:107], v[92:93], v[142:143], v[148:149]
	v_pk_fma_f32 v[92:93], v[92:93], v[146:147], v[112:113]
	ds_read_b128 v[88:91], v160 offset:18832
	ds_read_b128 v[64:67], v160 offset:19072
	ds_read_b128 v[40:43], v160 offset:19088
	ds_read_b128 v[76:79], v160 offset:19328
	ds_read_b128 v[48:51], v160 offset:19344
	ds_read_b128 v[84:87], v160 offset:19584
	ds_read_b128 v[60:63], v160 offset:19600
	ds_read_b128 v[108:111], v160 offset:19840
	ds_read_b128 v[100:103], v160 offset:19856
	ds_read_b64 v[120:121], v161 offset:20096
	ds_read_b128 v[116:119], v160 offset:18816
	ds_read_b64 v[126:127], v159 offset:20352
	v_pk_fma_f32 v[112:113], v[96:97], v[142:143], v[114:115]
	v_pk_fma_f32 v[96:97], v[96:97], v[146:147], v[104:105]
	v_pk_fma_f32 v[104:105], v[94:95], v[136:137], v[106:107]
	v_pk_fma_f32 v[92:93], v[94:95], v[144:145], v[92:93]
	v_pk_fma_f32 v[94:95], v[98:99], v[136:137], v[112:113]
	v_pk_fma_f32 v[96:97], v[98:99], v[144:145], v[96:97]
	v_add_f32_e32 v93, v92, v93
	v_add_f32_e32 v92, v104, v105
	s_nop 1
	v_add_f32_dpp v92, v92, v92 quad_perm:[1,0,3,2] row_mask:0xf bank_mask:0xf bound_ctrl:1
	v_add_f32_dpp v93, v93, v93 quad_perm:[1,0,3,2] row_mask:0xf bank_mask:0xf bound_ctrl:1
	s_nop 1
	v_add_f32_dpp v92, v92, v92 quad_perm:[2,3,0,1] row_mask:0xf bank_mask:0xf bound_ctrl:1
	v_add_f32_dpp v93, v93, v93 quad_perm:[2,3,0,1] row_mask:0xf bank_mask:0xf bound_ctrl:1
	s_nop 1
	v_add_f32_dpp v92, v92, v92 row_half_mirror row_mask:0xf bank_mask:0xf bound_ctrl:1
	v_add_f32_dpp v93, v93, v93 row_half_mirror row_mask:0xf bank_mask:0xf bound_ctrl:1
	v_add_f32_e32 v94, v94, v95
	v_add_f32_e32 v95, v96, v97
	s_nop 1
	v_add_f32_dpp v94, v94, v94 quad_perm:[1,0,3,2] row_mask:0xf bank_mask:0xf bound_ctrl:1
	v_add_f32_dpp v95, v95, v95 quad_perm:[1,0,3,2] row_mask:0xf bank_mask:0xf bound_ctrl:1
	s_nop 1
	v_add_f32_dpp v94, v94, v94 quad_perm:[2,3,0,1] row_mask:0xf bank_mask:0xf bound_ctrl:1
	v_add_f32_dpp v95, v95, v95 quad_perm:[2,3,0,1] row_mask:0xf bank_mask:0xf bound_ctrl:1
	s_nop 1
	v_mov_b32_dpp v96, v94 row_half_mirror row_mask:0xf bank_mask:0xf bound_ctrl:1
	v_mov_b32_dpp v97, v95 row_half_mirror row_mask:0xf bank_mask:0xf bound_ctrl:1
	s_and_saveexec_b64 s[28:29], s[8:9]
	s_cbranch_execz .LBB0_897
	v_pk_add_f32 v[94:95], v[94:95], v[96:97]
	v_readlane_b32 s30, v254, 11
	v_pk_fma_f32 v[94:95], v[122:123], v[124:125], v[94:95] op_sel:[0,1,0]
	v_readlane_b32 s31, v254, 12
	v_pk_fma_f32 v[94:95], v[124:125], v[92:93], v[94:95] op_sel_hi:[0,1,1] neg_lo:[1,0,0] neg_hi:[1,0,0]
	s_nop 0
	v_lshl_add_u64 v[96:97], v[134:135], 0, s[30:31]
	flat_store_dwordx2 v[96:97], v[94:95]
.LBB0_897:
	s_or_b64 exec, exec, s[28:29]
	v_pk_mul_f32 v[94:95], v[80:81], v[92:93] op_sel_hi:[1,0]
	v_pk_mul_f32 v[80:81], v[80:81], v[92:93] op_sel:[0,1]
	v_pk_fma_f32 v[94:95], v[72:73], v[122:123], v[94:95] op_sel_hi:[1,0,1] neg_lo:[0,0,1] neg_hi:[0,0,1]
	v_pk_fma_f32 v[72:73], v[72:73], v[122:123], v[80:81] op_sel:[0,1,0] neg_lo:[0,0,1] neg_hi:[0,0,1]
	v_pk_fma_f32 v[128:129], v[68:69], v[128:129], v[94:95]
	v_pk_fma_f32 v[130:131], v[68:69], v[130:131], v[72:73]
	v_pk_mul_f32 v[68:69], v[82:83], v[92:93] op_sel_hi:[1,0]
	v_pk_mul_f32 v[72:73], v[82:83], v[92:93] op_sel:[0,1]
	v_pk_fma_f32 v[68:69], v[74:75], v[122:123], v[68:69] op_sel_hi:[1,0,1] neg_lo:[0,0,1] neg_hi:[0,0,1]
	v_pk_fma_f32 v[72:73], v[74:75], v[122:123], v[72:73] op_sel:[0,1,0] neg_lo:[0,0,1] neg_hi:[0,0,1]
	v_pk_fma_f32 v[138:139], v[70:71], v[138:139], v[68:69]
	v_pk_mul_f32 v[68:69], v[56:57], v[92:93] op_sel_hi:[1,0]
	v_pk_mul_f32 v[56:57], v[56:57], v[92:93] op_sel:[0,1]
	v_pk_fma_f32 v[140:141], v[70:71], v[140:141], v[72:73]
	v_pk_fma_f32 v[68:69], v[52:53], v[122:123], v[68:69] op_sel_hi:[1,0,1] neg_lo:[0,0,1] neg_hi:[0,0,1]
	v_pk_fma_f32 v[52:53], v[52:53], v[122:123], v[56:57] op_sel:[0,1,0] neg_lo:[0,0,1] neg_hi:[0,0,1]
	v_pk_fma_f32 v[142:143], v[44:45], v[142:143], v[68:69]
	v_pk_fma_f32 v[146:147], v[44:45], v[146:147], v[52:53]
	v_pk_mul_f32 v[44:45], v[58:59], v[92:93] op_sel_hi:[1,0]
	v_pk_mul_f32 v[52:53], v[58:59], v[92:93] op_sel:[0,1]
	s_waitcnt lgkmcnt(0)
	v_pk_mul_f32 v[148:149], v[118:119], v[138:139]
	v_pk_mul_f32 v[118:119], v[118:119], v[140:141]
	v_pk_fma_f32 v[44:45], v[54:55], v[122:123], v[44:45] op_sel_hi:[1,0,1] neg_lo:[0,0,1] neg_hi:[0,0,1]
	v_pk_fma_f32 v[52:53], v[54:55], v[122:123], v[52:53] op_sel:[0,1,0] neg_lo:[0,0,1] neg_hi:[0,0,1]
	v_pk_fma_f32 v[148:149], v[116:117], v[128:129], v[148:149]
	v_pk_fma_f32 v[116:117], v[116:117], v[130:131], v[118:119]
	v_pk_mul_f32 v[118:119], v[110:111], v[138:139]
	v_pk_mul_f32 v[110:111], v[110:111], v[140:141]
	v_pk_fma_f32 v[136:137], v[46:47], v[136:137], v[44:45]
	v_pk_fma_f32 v[144:145], v[46:47], v[144:145], v[52:53]
	v_pk_fma_f32 v[118:119], v[108:109], v[128:129], v[118:119]
	v_pk_fma_f32 v[108:109], v[108:109], v[130:131], v[110:111]
	v_pk_fma_f32 v[110:111], v[88:89], v[142:143], v[148:149]
	v_pk_fma_f32 v[88:89], v[88:89], v[146:147], v[116:117]
	ds_read_b128 v[92:95], v160 offset:20400
	ds_read_b128 v[68:71], v160 offset:20640
	ds_read_b128 v[44:47], v160 offset:20656
	ds_read_b128 v[72:75], v160 offset:20896
	ds_read_b128 v[52:55], v160 offset:20912
	ds_read_b128 v[80:83], v160 offset:21152
	ds_read_b128 v[56:59], v160 offset:21168
	ds_read_b128 v[104:107], v160 offset:21408
	ds_read_b128 v[96:99], v160 offset:21424
	ds_read_b64 v[122:123], v161 offset:21664
	ds_read_b128 v[112:115], v160 offset:20384
	ds_read_b64 v[124:125], v159 offset:21920
	v_pk_fma_f32 v[116:117], v[100:101], v[142:143], v[118:119]
	v_pk_fma_f32 v[100:101], v[100:101], v[146:147], v[108:109]
	v_pk_fma_f32 v[108:109], v[90:91], v[136:137], v[110:111]
	v_pk_fma_f32 v[88:89], v[90:91], v[144:145], v[88:89]
	v_pk_fma_f32 v[90:91], v[102:103], v[136:137], v[116:117]
	v_pk_fma_f32 v[100:101], v[102:103], v[144:145], v[100:101]
	v_add_f32_e32 v89, v88, v89
	v_add_f32_e32 v88, v108, v109
	s_nop 1
	v_add_f32_dpp v88, v88, v88 quad_perm:[1,0,3,2] row_mask:0xf bank_mask:0xf bound_ctrl:1
	v_add_f32_dpp v89, v89, v89 quad_perm:[1,0,3,2] row_mask:0xf bank_mask:0xf bound_ctrl:1
	s_nop 1
	v_add_f32_dpp v88, v88, v88 quad_perm:[2,3,0,1] row_mask:0xf bank_mask:0xf bound_ctrl:1
	v_add_f32_dpp v89, v89, v89 quad_perm:[2,3,0,1] row_mask:0xf bank_mask:0xf bound_ctrl:1
	s_nop 1
	v_add_f32_dpp v88, v88, v88 row_half_mirror row_mask:0xf bank_mask:0xf bound_ctrl:1
	v_add_f32_dpp v89, v89, v89 row_half_mirror row_mask:0xf bank_mask:0xf bound_ctrl:1
	v_add_f32_e32 v90, v90, v91
	v_add_f32_e32 v91, v100, v101
	s_nop 1
	v_add_f32_dpp v90, v90, v90 quad_perm:[1,0,3,2] row_mask:0xf bank_mask:0xf bound_ctrl:1
	v_add_f32_dpp v91, v91, v91 quad_perm:[1,0,3,2] row_mask:0xf bank_mask:0xf bound_ctrl:1
	s_nop 1
	v_add_f32_dpp v90, v90, v90 quad_perm:[2,3,0,1] row_mask:0xf bank_mask:0xf bound_ctrl:1
	v_add_f32_dpp v91, v91, v91 quad_perm:[2,3,0,1] row_mask:0xf bank_mask:0xf bound_ctrl:1
	s_nop 1
	v_mov_b32_dpp v100, v90 row_half_mirror row_mask:0xf bank_mask:0xf bound_ctrl:1
	v_mov_b32_dpp v101, v91 row_half_mirror row_mask:0xf bank_mask:0xf bound_ctrl:1
	s_and_saveexec_b64 s[28:29], s[8:9]
	s_cbranch_execz .LBB0_899
	v_pk_add_f32 v[90:91], v[90:91], v[100:101]
	v_readlane_b32 s30, v254, 13
	v_pk_fma_f32 v[90:91], v[120:121], v[126:127], v[90:91] op_sel:[0,1,0]
	v_readlane_b32 s31, v254, 14
	v_pk_fma_f32 v[90:91], v[126:127], v[88:89], v[90:91] op_sel_hi:[0,1,1] neg_lo:[1,0,0] neg_hi:[1,0,0]
	s_nop 0
	v_lshl_add_u64 v[100:101], v[134:135], 0, s[30:31]
	flat_store_dwordx2 v[100:101], v[90:91]
.LBB0_899:
	s_or_b64 exec, exec, s[28:29]
	v_pk_mul_f32 v[90:91], v[84:85], v[88:89] op_sel_hi:[1,0]
	v_pk_mul_f32 v[84:85], v[84:85], v[88:89] op_sel:[0,1]
	v_pk_fma_f32 v[90:91], v[76:77], v[120:121], v[90:91] op_sel_hi:[1,0,1] neg_lo:[0,0,1] neg_hi:[0,0,1]
	v_pk_fma_f32 v[76:77], v[76:77], v[120:121], v[84:85] op_sel:[0,1,0] neg_lo:[0,0,1] neg_hi:[0,0,1]
	v_pk_fma_f32 v[128:129], v[64:65], v[128:129], v[90:91]
	v_pk_fma_f32 v[130:131], v[64:65], v[130:131], v[76:77]
	v_pk_mul_f32 v[64:65], v[86:87], v[88:89] op_sel_hi:[1,0]
	v_pk_mul_f32 v[76:77], v[86:87], v[88:89] op_sel:[0,1]
	v_pk_fma_f32 v[64:65], v[78:79], v[120:121], v[64:65] op_sel_hi:[1,0,1] neg_lo:[0,0,1] neg_hi:[0,0,1]
	v_pk_fma_f32 v[76:77], v[78:79], v[120:121], v[76:77] op_sel:[0,1,0] neg_lo:[0,0,1] neg_hi:[0,0,1]
	v_pk_fma_f32 v[138:139], v[66:67], v[138:139], v[64:65]
	v_pk_mul_f32 v[64:65], v[60:61], v[88:89] op_sel_hi:[1,0]
	v_pk_mul_f32 v[60:61], v[60:61], v[88:89] op_sel:[0,1]
	v_pk_fma_f32 v[140:141], v[66:67], v[140:141], v[76:77]
	v_pk_fma_f32 v[64:65], v[48:49], v[120:121], v[64:65] op_sel_hi:[1,0,1] neg_lo:[0,0,1] neg_hi:[0,0,1]
	v_pk_fma_f32 v[48:49], v[48:49], v[120:121], v[60:61] op_sel:[0,1,0] neg_lo:[0,0,1] neg_hi:[0,0,1]
	v_pk_fma_f32 v[142:143], v[40:41], v[142:143], v[64:65]
	v_pk_fma_f32 v[146:147], v[40:41], v[146:147], v[48:49]
	v_pk_mul_f32 v[40:41], v[62:63], v[88:89] op_sel_hi:[1,0]
	v_pk_mul_f32 v[48:49], v[62:63], v[88:89] op_sel:[0,1]
	s_waitcnt lgkmcnt(0)
	v_pk_mul_f32 v[148:149], v[114:115], v[138:139]
	v_pk_mul_f32 v[114:115], v[114:115], v[140:141]
	v_pk_fma_f32 v[40:41], v[50:51], v[120:121], v[40:41] op_sel_hi:[1,0,1] neg_lo:[0,0,1] neg_hi:[0,0,1]
	v_pk_fma_f32 v[48:49], v[50:51], v[120:121], v[48:49] op_sel:[0,1,0] neg_lo:[0,0,1] neg_hi:[0,0,1]
	v_pk_fma_f32 v[148:149], v[112:113], v[128:129], v[148:149]
	v_pk_fma_f32 v[112:113], v[112:113], v[130:131], v[114:115]
	v_pk_mul_f32 v[114:115], v[106:107], v[138:139]
	v_pk_mul_f32 v[106:107], v[106:107], v[140:141]
	v_pk_fma_f32 v[136:137], v[42:43], v[136:137], v[40:41]
	v_pk_fma_f32 v[144:145], v[42:43], v[144:145], v[48:49]
	v_pk_fma_f32 v[114:115], v[104:105], v[128:129], v[114:115]
	v_pk_fma_f32 v[104:105], v[104:105], v[130:131], v[106:107]
	v_pk_fma_f32 v[106:107], v[92:93], v[142:143], v[148:149]
	v_pk_fma_f32 v[92:93], v[92:93], v[146:147], v[112:113]
	ds_read_b128 v[88:91], v160 offset:21968
	ds_read_b128 v[64:67], v160 offset:22208
	ds_read_b128 v[40:43], v160 offset:22224
	ds_read_b128 v[76:79], v160 offset:22464
	ds_read_b128 v[48:51], v160 offset:22480
	ds_read_b128 v[84:87], v160 offset:22720
	ds_read_b128 v[60:63], v160 offset:22736
	ds_read_b128 v[108:111], v160 offset:22976
	ds_read_b128 v[100:103], v160 offset:22992
	ds_read_b64 v[120:121], v161 offset:23232
	ds_read_b128 v[116:119], v160 offset:21952
	ds_read_b64 v[126:127], v159 offset:23488
	v_pk_fma_f32 v[112:113], v[96:97], v[142:143], v[114:115]
	v_pk_fma_f32 v[96:97], v[96:97], v[146:147], v[104:105]
	v_pk_fma_f32 v[104:105], v[94:95], v[136:137], v[106:107]
	v_pk_fma_f32 v[92:93], v[94:95], v[144:145], v[92:93]
	v_pk_fma_f32 v[94:95], v[98:99], v[136:137], v[112:113]
	v_pk_fma_f32 v[96:97], v[98:99], v[144:145], v[96:97]
	v_add_f32_e32 v93, v92, v93
	v_add_f32_e32 v92, v104, v105
	s_nop 1
	v_add_f32_dpp v92, v92, v92 quad_perm:[1,0,3,2] row_mask:0xf bank_mask:0xf bound_ctrl:1
	v_add_f32_dpp v93, v93, v93 quad_perm:[1,0,3,2] row_mask:0xf bank_mask:0xf bound_ctrl:1
	s_nop 1
	v_add_f32_dpp v92, v92, v92 quad_perm:[2,3,0,1] row_mask:0xf bank_mask:0xf bound_ctrl:1
	v_add_f32_dpp v93, v93, v93 quad_perm:[2,3,0,1] row_mask:0xf bank_mask:0xf bound_ctrl:1
	s_nop 1
	v_add_f32_dpp v92, v92, v92 row_half_mirror row_mask:0xf bank_mask:0xf bound_ctrl:1
	v_add_f32_dpp v93, v93, v93 row_half_mirror row_mask:0xf bank_mask:0xf bound_ctrl:1
	v_add_f32_e32 v94, v94, v95
	v_add_f32_e32 v95, v96, v97
	s_nop 1
	v_add_f32_dpp v94, v94, v94 quad_perm:[1,0,3,2] row_mask:0xf bank_mask:0xf bound_ctrl:1
	v_add_f32_dpp v95, v95, v95 quad_perm:[1,0,3,2] row_mask:0xf bank_mask:0xf bound_ctrl:1
	s_nop 1
	v_add_f32_dpp v94, v94, v94 quad_perm:[2,3,0,1] row_mask:0xf bank_mask:0xf bound_ctrl:1
	v_add_f32_dpp v95, v95, v95 quad_perm:[2,3,0,1] row_mask:0xf bank_mask:0xf bound_ctrl:1
	s_nop 1
	v_mov_b32_dpp v96, v94 row_half_mirror row_mask:0xf bank_mask:0xf bound_ctrl:1
	v_mov_b32_dpp v97, v95 row_half_mirror row_mask:0xf bank_mask:0xf bound_ctrl:1
	s_and_saveexec_b64 s[28:29], s[8:9]
	s_cbranch_execz .LBB0_901
	v_pk_add_f32 v[94:95], v[94:95], v[96:97]
	v_readlane_b32 s30, v254, 15
	v_pk_fma_f32 v[94:95], v[122:123], v[124:125], v[94:95] op_sel:[0,1,0]
	v_readlane_b32 s31, v254, 16
	v_pk_fma_f32 v[94:95], v[124:125], v[92:93], v[94:95] op_sel_hi:[0,1,1] neg_lo:[1,0,0] neg_hi:[1,0,0]
	s_nop 0
	v_lshl_add_u64 v[96:97], v[134:135], 0, s[30:31]
	flat_store_dwordx2 v[96:97], v[94:95]
.LBB0_901:
	s_or_b64 exec, exec, s[28:29]
	v_pk_mul_f32 v[94:95], v[80:81], v[92:93] op_sel_hi:[1,0]
	v_pk_mul_f32 v[80:81], v[80:81], v[92:93] op_sel:[0,1]
	v_pk_fma_f32 v[94:95], v[72:73], v[122:123], v[94:95] op_sel_hi:[1,0,1] neg_lo:[0,0,1] neg_hi:[0,0,1]
	v_pk_fma_f32 v[72:73], v[72:73], v[122:123], v[80:81] op_sel:[0,1,0] neg_lo:[0,0,1] neg_hi:[0,0,1]
	v_pk_fma_f32 v[128:129], v[68:69], v[128:129], v[94:95]
	v_pk_fma_f32 v[130:131], v[68:69], v[130:131], v[72:73]
	v_pk_mul_f32 v[68:69], v[82:83], v[92:93] op_sel_hi:[1,0]
	v_pk_mul_f32 v[72:73], v[82:83], v[92:93] op_sel:[0,1]
	v_pk_fma_f32 v[68:69], v[74:75], v[122:123], v[68:69] op_sel_hi:[1,0,1] neg_lo:[0,0,1] neg_hi:[0,0,1]
	v_pk_fma_f32 v[72:73], v[74:75], v[122:123], v[72:73] op_sel:[0,1,0] neg_lo:[0,0,1] neg_hi:[0,0,1]
	v_pk_fma_f32 v[138:139], v[70:71], v[138:139], v[68:69]
	v_pk_mul_f32 v[68:69], v[56:57], v[92:93] op_sel_hi:[1,0]
	v_pk_mul_f32 v[56:57], v[56:57], v[92:93] op_sel:[0,1]
	v_pk_fma_f32 v[140:141], v[70:71], v[140:141], v[72:73]
	v_pk_fma_f32 v[68:69], v[52:53], v[122:123], v[68:69] op_sel_hi:[1,0,1] neg_lo:[0,0,1] neg_hi:[0,0,1]
	v_pk_fma_f32 v[52:53], v[52:53], v[122:123], v[56:57] op_sel:[0,1,0] neg_lo:[0,0,1] neg_hi:[0,0,1]
	v_pk_fma_f32 v[142:143], v[44:45], v[142:143], v[68:69]
	v_pk_fma_f32 v[146:147], v[44:45], v[146:147], v[52:53]
	v_pk_mul_f32 v[44:45], v[58:59], v[92:93] op_sel_hi:[1,0]
	v_pk_mul_f32 v[52:53], v[58:59], v[92:93] op_sel:[0,1]
	s_waitcnt lgkmcnt(0)
	v_pk_mul_f32 v[148:149], v[118:119], v[138:139]
	v_pk_mul_f32 v[118:119], v[118:119], v[140:141]
	v_pk_fma_f32 v[44:45], v[54:55], v[122:123], v[44:45] op_sel_hi:[1,0,1] neg_lo:[0,0,1] neg_hi:[0,0,1]
	v_pk_fma_f32 v[52:53], v[54:55], v[122:123], v[52:53] op_sel:[0,1,0] neg_lo:[0,0,1] neg_hi:[0,0,1]
	v_pk_fma_f32 v[148:149], v[116:117], v[128:129], v[148:149]
	v_pk_fma_f32 v[116:117], v[116:117], v[130:131], v[118:119]
	v_pk_mul_f32 v[118:119], v[110:111], v[138:139]
	v_pk_mul_f32 v[110:111], v[110:111], v[140:141]
	v_pk_fma_f32 v[136:137], v[46:47], v[136:137], v[44:45]
	v_pk_fma_f32 v[144:145], v[46:47], v[144:145], v[52:53]
	v_pk_fma_f32 v[118:119], v[108:109], v[128:129], v[118:119]
	v_pk_fma_f32 v[108:109], v[108:109], v[130:131], v[110:111]
	v_pk_fma_f32 v[110:111], v[88:89], v[142:143], v[148:149]
	v_pk_fma_f32 v[88:89], v[88:89], v[146:147], v[116:117]
	ds_read_b128 v[92:95], v160 offset:23536
	ds_read_b128 v[52:55], v160 offset:23776
	ds_read_b128 v[56:59], v160 offset:23792
	ds_read_b128 v[44:47], v160 offset:24032
	ds_read_b128 v[68:71], v160 offset:24048
	ds_read_b128 v[80:83], v160 offset:24288
	ds_read_b128 v[72:75], v160 offset:24304
	ds_read_b128 v[104:107], v160 offset:24544
	ds_read_b128 v[96:99], v160 offset:24560
	ds_read_b64 v[122:123], v161 offset:24800
	ds_read_b128 v[112:115], v160 offset:23520
	ds_read_b64 v[124:125], v159 offset:25056
	v_pk_fma_f32 v[116:117], v[100:101], v[142:143], v[118:119]
	v_pk_fma_f32 v[100:101], v[100:101], v[146:147], v[108:109]
	v_pk_fma_f32 v[108:109], v[90:91], v[136:137], v[110:111]
	v_pk_fma_f32 v[88:89], v[90:91], v[144:145], v[88:89]
	v_pk_fma_f32 v[90:91], v[102:103], v[136:137], v[116:117]
	v_pk_fma_f32 v[100:101], v[102:103], v[144:145], v[100:101]
	v_add_f32_e32 v89, v88, v89
	v_add_f32_e32 v88, v108, v109
	s_nop 1
	v_add_f32_dpp v88, v88, v88 quad_perm:[1,0,3,2] row_mask:0xf bank_mask:0xf bound_ctrl:1
	v_add_f32_dpp v89, v89, v89 quad_perm:[1,0,3,2] row_mask:0xf bank_mask:0xf bound_ctrl:1
	s_nop 1
	v_add_f32_dpp v88, v88, v88 quad_perm:[2,3,0,1] row_mask:0xf bank_mask:0xf bound_ctrl:1
	v_add_f32_dpp v89, v89, v89 quad_perm:[2,3,0,1] row_mask:0xf bank_mask:0xf bound_ctrl:1
	s_nop 1
	v_add_f32_dpp v88, v88, v88 row_half_mirror row_mask:0xf bank_mask:0xf bound_ctrl:1
	v_add_f32_dpp v89, v89, v89 row_half_mirror row_mask:0xf bank_mask:0xf bound_ctrl:1
	v_add_f32_e32 v90, v90, v91
	v_add_f32_e32 v91, v100, v101
	s_nop 1
	v_add_f32_dpp v90, v90, v90 quad_perm:[1,0,3,2] row_mask:0xf bank_mask:0xf bound_ctrl:1
	v_add_f32_dpp v91, v91, v91 quad_perm:[1,0,3,2] row_mask:0xf bank_mask:0xf bound_ctrl:1
	s_nop 1
	v_add_f32_dpp v90, v90, v90 quad_perm:[2,3,0,1] row_mask:0xf bank_mask:0xf bound_ctrl:1
	v_add_f32_dpp v91, v91, v91 quad_perm:[2,3,0,1] row_mask:0xf bank_mask:0xf bound_ctrl:1
	s_nop 1
	v_mov_b32_dpp v100, v90 row_half_mirror row_mask:0xf bank_mask:0xf bound_ctrl:1
	v_mov_b32_dpp v101, v91 row_half_mirror row_mask:0xf bank_mask:0xf bound_ctrl:1
	s_and_saveexec_b64 s[28:29], s[8:9]
	s_cbranch_execz .LBB0_903
	v_pk_add_f32 v[90:91], v[90:91], v[100:101]
	v_readlane_b32 s30, v254, 17
	v_pk_fma_f32 v[90:91], v[120:121], v[126:127], v[90:91] op_sel:[0,1,0]
	v_readlane_b32 s31, v254, 18
	v_pk_fma_f32 v[90:91], v[126:127], v[88:89], v[90:91] op_sel_hi:[0,1,1] neg_lo:[1,0,0] neg_hi:[1,0,0]
	s_nop 0
	v_lshl_add_u64 v[100:101], v[134:135], 0, s[30:31]
	flat_store_dwordx2 v[100:101], v[90:91]
.LBB0_903:
	s_or_b64 exec, exec, s[28:29]
	v_pk_mul_f32 v[90:91], v[84:85], v[88:89] op_sel_hi:[1,0]
	v_pk_mul_f32 v[84:85], v[84:85], v[88:89] op_sel:[0,1]
	v_pk_fma_f32 v[90:91], v[76:77], v[120:121], v[90:91] op_sel_hi:[1,0,1] neg_lo:[0,0,1] neg_hi:[0,0,1]
	v_pk_fma_f32 v[84:85], v[76:77], v[120:121], v[84:85] op_sel:[0,1,0] neg_lo:[0,0,1] neg_hi:[0,0,1]
	v_pk_fma_f32 v[76:77], v[64:65], v[128:129], v[90:91]
	v_pk_fma_f32 v[64:65], v[64:65], v[130:131], v[84:85]
	v_pk_mul_f32 v[84:85], v[86:87], v[88:89] op_sel_hi:[1,0]
	v_pk_mul_f32 v[86:87], v[86:87], v[88:89] op_sel:[0,1]
	v_pk_fma_f32 v[84:85], v[78:79], v[120:121], v[84:85] op_sel_hi:[1,0,1] neg_lo:[0,0,1] neg_hi:[0,0,1]
	v_pk_fma_f32 v[86:87], v[78:79], v[120:121], v[86:87] op_sel:[0,1,0] neg_lo:[0,0,1] neg_hi:[0,0,1]
	v_pk_fma_f32 v[78:79], v[66:67], v[138:139], v[84:85]
	v_pk_mul_f32 v[84:85], v[60:61], v[88:89] op_sel_hi:[1,0]
	v_pk_mul_f32 v[60:61], v[60:61], v[88:89] op_sel:[0,1]
	v_pk_fma_f32 v[84:85], v[48:49], v[120:121], v[84:85] op_sel_hi:[1,0,1] neg_lo:[0,0,1] neg_hi:[0,0,1]
	v_pk_fma_f32 v[60:61], v[48:49], v[120:121], v[60:61] op_sel:[0,1,0] neg_lo:[0,0,1] neg_hi:[0,0,1]
	v_pk_fma_f32 v[48:49], v[40:41], v[142:143], v[84:85]
	v_pk_fma_f32 v[60:61], v[40:41], v[146:147], v[60:61]
	v_pk_mul_f32 v[40:41], v[62:63], v[88:89] op_sel_hi:[1,0]
	v_pk_mul_f32 v[62:63], v[62:63], v[88:89] op_sel:[0,1]
	v_pk_fma_f32 v[66:67], v[66:67], v[140:141], v[86:87]
	v_pk_fma_f32 v[40:41], v[50:51], v[120:121], v[40:41] op_sel_hi:[1,0,1] neg_lo:[0,0,1] neg_hi:[0,0,1]
	v_pk_fma_f32 v[62:63], v[50:51], v[120:121], v[62:63] op_sel:[0,1,0] neg_lo:[0,0,1] neg_hi:[0,0,1]
	v_pk_fma_f32 v[50:51], v[42:43], v[136:137], v[40:41]
	v_pk_fma_f32 v[62:63], v[42:43], v[144:145], v[62:63]
	s_waitcnt lgkmcnt(0)
	v_pk_mul_f32 v[40:41], v[114:115], v[78:79]
	v_pk_mul_f32 v[42:43], v[114:115], v[66:67]
	v_pk_fma_f32 v[40:41], v[112:113], v[76:77], v[40:41]
	v_pk_fma_f32 v[42:43], v[112:113], v[64:65], v[42:43]
	v_pk_fma_f32 v[40:41], v[92:93], v[48:49], v[40:41]
	v_pk_fma_f32 v[42:43], v[92:93], v[60:61], v[42:43]
	v_pk_fma_f32 v[40:41], v[94:95], v[50:51], v[40:41]
	v_pk_fma_f32 v[42:43], v[94:95], v[62:63], v[42:43]
	v_add_f32_e32 v40, v40, v41
	v_add_f32_e32 v41, v42, v43
	v_pk_mul_f32 v[84:85], v[106:107], v[78:79]
	v_pk_mul_f32 v[86:87], v[106:107], v[66:67]
	v_add_f32_dpp v40, v40, v40 quad_perm:[1,0,3,2] row_mask:0xf bank_mask:0xf bound_ctrl:1
	v_add_f32_dpp v41, v41, v41 quad_perm:[1,0,3,2] row_mask:0xf bank_mask:0xf bound_ctrl:1
	v_pk_fma_f32 v[84:85], v[104:105], v[76:77], v[84:85]
	v_pk_fma_f32 v[86:87], v[104:105], v[64:65], v[86:87]
	v_pk_fma_f32 v[84:85], v[96:97], v[48:49], v[84:85]
	v_pk_fma_f32 v[86:87], v[96:97], v[60:61], v[86:87]
	v_add_f32_dpp v40, v40, v40 quad_perm:[2,3,0,1] row_mask:0xf bank_mask:0xf bound_ctrl:1
	v_add_f32_dpp v41, v41, v41 quad_perm:[2,3,0,1] row_mask:0xf bank_mask:0xf bound_ctrl:1
	v_pk_fma_f32 v[84:85], v[98:99], v[50:51], v[84:85]
	v_pk_fma_f32 v[86:87], v[98:99], v[62:63], v[86:87]
	v_mov_b32_dpp v42, v40 row_half_mirror row_mask:0xf bank_mask:0xf bound_ctrl:1
	v_mov_b32_dpp v43, v41 row_half_mirror row_mask:0xf bank_mask:0xf bound_ctrl:1
	v_pk_add_f32 v[42:43], v[40:41], v[42:43]
	v_add_f32_e32 v40, v84, v85
	v_add_f32_e32 v41, v86, v87
	s_nop 1
	v_add_f32_dpp v40, v40, v40 quad_perm:[1,0,3,2] row_mask:0xf bank_mask:0xf bound_ctrl:1
	v_add_f32_dpp v41, v41, v41 quad_perm:[1,0,3,2] row_mask:0xf bank_mask:0xf bound_ctrl:1
	s_nop 1
	v_add_f32_dpp v40, v40, v40 quad_perm:[2,3,0,1] row_mask:0xf bank_mask:0xf bound_ctrl:1
	v_add_f32_dpp v41, v41, v41 quad_perm:[2,3,0,1] row_mask:0xf bank_mask:0xf bound_ctrl:1
	s_nop 1
	v_mov_b32_dpp v84, v40 row_half_mirror row_mask:0xf bank_mask:0xf bound_ctrl:1
	v_mov_b32_dpp v85, v41 row_half_mirror row_mask:0xf bank_mask:0xf bound_ctrl:1
	s_and_saveexec_b64 s[28:29], s[8:9]
	s_cbranch_execz .LBB0_872
	v_pk_add_f32 v[40:41], v[40:41], v[84:85]
	v_readlane_b32 s30, v254, 21
	v_pk_fma_f32 v[40:41], v[122:123], v[124:125], v[40:41] op_sel:[0,1,0]
	v_readlane_b32 s31, v254, 22
	v_pk_fma_f32 v[40:41], v[124:125], v[42:43], v[40:41] op_sel_hi:[0,1,1] neg_lo:[1,0,0] neg_hi:[1,0,0]
	s_nop 0
	v_lshl_add_u64 v[84:85], v[134:135], 0, s[30:31]
	flat_store_dwordx2 v[84:85], v[40:41]
	s_branch .LBB0_872

.LBB0_916:
	v_lshlrev_b32_e32 v65, 5, v64
	v_and_b32_e32 v65, 32, v65
	v_add_u32_e32 v65, v65, v153
	v_mul_lo_u32 v65, v65, s38
	s_waitcnt vmcnt(0) lgkmcnt(0)
	v_and_b32_e32 v66, 0xffff0000, v0
	v_and_b32_e32 v67, 0xffff0000, v1
	v_and_b32_e32 v68, 0xffff0000, v2
	v_and_b32_e32 v69, 0xffff0000, v3
	v_add_u32_e32 v65, v154, v65
	v_lshlrev_b32_e32 v71, 16, v3
	v_lshlrev_b32_e32 v70, 16, v2
	ds_write_b128 v65, v[66:69]
	ds_write_b128 v65, v[16:19] offset:256
	ds_write_b128 v65, v[56:59] offset:512
	ds_write_b128 v65, v[60:63] offset:768
	v_lshlrev_b32_e32 v66, 16, v12
	v_lshlrev_b32_e32 v67, 16, v13
	v_lshlrev_b32_e32 v68, 16, v14
	v_lshlrev_b32_e32 v69, 16, v15
	v_lshlrev_b32_e32 v73, 16, v1
	v_lshlrev_b32_e32 v72, 16, v0
	ds_write_b128 v65, v[66:69] offset:1280
	v_pk_mul_f32 v[68:69], v[18:19], v[70:71]
	v_pk_mul_f32 v[66:67], v[16:17], v[72:73]
	ds_write_b128 v65, v[66:69] offset:1024
	v_mov_b32_e32 v67, v61
	v_mov_b32_e32 v61, v57
	v_mov_b32_e32 v66, v56
	v_pk_mul_f32 v[56:57], v[60:61], v[72:73]
	v_mov_b32_e32 v60, v58
	v_pk_fma_f32 v[56:57], v[66:67], v[72:73], v[56:57] op_sel:[0,0,1] op_sel_hi:[1,1,0]
	v_mov_b32_e32 v61, v62
	v_pk_fma_f32 v[56:57], v[70:71], v[60:61], v[56:57] op_sel_hi:[0,1,1]
	v_mov_b32_e32 v62, v59
	v_mov_b32_e32 v58, v71
	v_pk_fma_f32 v[56:57], v[58:59], v[62:63], v[56:57] op_sel_hi:[0,1,1]
	s_nop 1
	v_add_f32_dpp v56, v56, v56 quad_perm:[1,0,3,2] row_mask:0xf bank_mask:0xf bound_ctrl:1
	v_add_f32_dpp v57, v57, v57 quad_perm:[1,0,3,2] row_mask:0xf bank_mask:0xf bound_ctrl:1
	s_nop 1
	v_add_f32_dpp v56, v56, v56 quad_perm:[2,3,0,1] row_mask:0xf bank_mask:0xf bound_ctrl:1
	v_add_f32_dpp v57, v57, v57 quad_perm:[2,3,0,1] row_mask:0xf bank_mask:0xf bound_ctrl:1
	s_nop 1
	v_add_f32_dpp v56, v56, v56 row_half_mirror row_mask:0xf bank_mask:0xf bound_ctrl:1
	v_add_f32_dpp v57, v57, v57 row_half_mirror row_mask:0xf bank_mask:0xf bound_ctrl:1
	s_nop 1
	v_mov_b32_dpp v59, v57 row_mirror row_mask:0xf bank_mask:0xf bound_ctrl:1
	v_mov_b32_dpp v58, v56 row_mirror row_mask:0xf bank_mask:0xf bound_ctrl:1
	s_and_saveexec_b64 s[28:29], s[10:11]
	v_pk_add_f32 v[56:57], v[56:57], v[58:59]
	s_nop 0
	v_pk_mov_b32 v[56:57], v[56:57], v[56:57] op_sel:[1,0]
	ds_write_b64 v65, v[56:57] offset:1536
	s_or_b64 exec, exec, s[28:29]
	s_and_b64 vcc, exec, s[6:7]
	s_mov_b64 s[28:29], -1
	s_cbranch_vccnz .LBB0_922
	v_and_b32_e32 v56, 0xffff0000, v24
	v_and_b32_e32 v57, 0xffff0000, v25
	v_and_b32_e32 v58, 0xffff0000, v26
	v_and_b32_e32 v59, 0xffff0000, v27
	s_cbranch_execz .LBB0_923

.LBB0_926:
	v_and_b32_e32 v66, 0xffff0000, v20
	v_and_b32_e32 v67, 0xffff0000, v21
	v_and_b32_e32 v68, 0xffff0000, v22
	v_and_b32_e32 v69, 0xffff0000, v23
	v_lshlrev_b32_e32 v71, 16, v23
	v_lshlrev_b32_e32 v70, 16, v22
	ds_write_b128 v65, v[66:69] offset:25088
	ds_write_b128 v65, v[36:39] offset:25344
	ds_write_b128 v65, v[56:59] offset:25600
	ds_write_b128 v65, v[60:63] offset:25856
	v_lshlrev_b32_e32 v66, 16, v32
	v_lshlrev_b32_e32 v67, 16, v33
	v_lshlrev_b32_e32 v68, 16, v34
	v_lshlrev_b32_e32 v69, 16, v35
	v_lshlrev_b32_e32 v73, 16, v21
	v_lshlrev_b32_e32 v72, 16, v20
	ds_write_b128 v65, v[66:69] offset:26368
	v_pk_mul_f32 v[68:69], v[38:39], v[70:71]
	v_pk_mul_f32 v[66:67], v[36:37], v[72:73]
	ds_write_b128 v65, v[66:69] offset:26112
	v_mov_b32_e32 v67, v61
	v_mov_b32_e32 v61, v57
	v_mov_b32_e32 v66, v56
	v_pk_mul_f32 v[56:57], v[60:61], v[72:73]
	v_mov_b32_e32 v60, v58
	v_pk_fma_f32 v[56:57], v[66:67], v[72:73], v[56:57] op_sel:[0,0,1] op_sel_hi:[1,1,0]
	v_mov_b32_e32 v61, v62
	v_pk_fma_f32 v[56:57], v[70:71], v[60:61], v[56:57] op_sel_hi:[0,1,1]
	v_mov_b32_e32 v62, v59
	v_mov_b32_e32 v58, v71
	v_pk_fma_f32 v[56:57], v[58:59], v[62:63], v[56:57] op_sel_hi:[0,1,1]
	s_nop 1
	v_add_f32_dpp v56, v56, v56 quad_perm:[1,0,3,2] row_mask:0xf bank_mask:0xf bound_ctrl:1
	v_add_f32_dpp v57, v57, v57 quad_perm:[1,0,3,2] row_mask:0xf bank_mask:0xf bound_ctrl:1
	s_nop 1
	v_add_f32_dpp v56, v56, v56 quad_perm:[2,3,0,1] row_mask:0xf bank_mask:0xf bound_ctrl:1
	v_add_f32_dpp v57, v57, v57 quad_perm:[2,3,0,1] row_mask:0xf bank_mask:0xf bound_ctrl:1
	s_nop 1
	v_add_f32_dpp v56, v56, v56 row_half_mirror row_mask:0xf bank_mask:0xf bound_ctrl:1
	v_add_f32_dpp v57, v57, v57 row_half_mirror row_mask:0xf bank_mask:0xf bound_ctrl:1
	s_nop 1
	v_mov_b32_dpp v59, v57 row_mirror row_mask:0xf bank_mask:0xf bound_ctrl:1
	v_mov_b32_dpp v58, v56 row_mirror row_mask:0xf bank_mask:0xf bound_ctrl:1
	s_and_saveexec_b64 s[28:29], s[10:11]
	v_pk_add_f32 v[56:57], v[56:57], v[58:59]
	s_nop 0
	v_pk_mov_b32 v[56:57], v[56:57], v[56:57] op_sel:[1,0]
	ds_write_b64 v65, v[56:57] offset:26624
	s_or_b64 exec, exec, s[28:29]
	v_cmp_ne_u32_e32 vcc, 62, v156
	v_mov_b32_e32 v56, 63
	s_and_saveexec_b64 s[28:29], vcc
	s_cbranch_execz .LBB0_867
	v_lshl_add_u32 v18, v156, 5, v155
	v_readlane_b32 s30, v253, 35
	v_sub_u32_e32 v0, 0x7ff, v18
	v_readlane_b32 s31, v253, 36
	v_add_u32_e32 v19, 16, v18
	v_mov_b32_e32 v56, v64
	v_cndmask_b32_e64 v0, v0, v18, s[30:31]
	v_sub_u32_e32 v18, 0x7ef, v18
	v_cndmask_b32_e64 v18, v18, v19, s[30:31]
	v_add_u32_e32 v0, s35, v0
	v_add_u32_e32 v18, s35, v18
	v_ashrrev_i32_e32 v1, 31, v0
	v_ashrrev_i32_e32 v19, 31, v18
	v_lshlrev_b64 v[0:1], 9, v[0:1]
	v_lshlrev_b64 v[18:19], 9, v[18:19]
	v_lshl_add_u64 v[0:1], v[0:1], 0, v[178:179]
	v_lshl_add_u64 v[18:19], v[18:19], 0, v[178:179]
	v_lshlrev_b64 v[16:17], 2, v[0:1]
	v_lshlrev_b64 v[32:33], 2, v[18:19]
	v_lshl_add_u64 v[0:1], s[12:13], 0, v[16:17]
	v_lshl_add_u64 v[4:5], s[14:15], 0, v[16:17]
	v_lshl_add_u64 v[8:9], s[16:17], 0, v[16:17]
	v_lshl_add_u64 v[12:13], s[18:19], 0, v[16:17]
	v_lshl_add_u64 v[16:17], s[20:21], 0, v[16:17]
	v_lshl_add_u64 v[20:21], s[12:13], 0, v[32:33]
	v_lshl_add_u64 v[24:25], s[14:15], 0, v[32:33]
	v_lshl_add_u64 v[28:29], s[16:17], 0, v[32:33]
	v_lshl_add_u64 v[34:35], s[18:19], 0, v[32:33]
	v_lshl_add_u64 v[36:37], s[20:21], 0, v[32:33]
	flat_load_dwordx4 v[0:3], v[0:1]
	s_nop 0
	flat_load_dwordx4 v[4:7], v[4:5]
	s_nop 0
	flat_load_dwordx4 v[8:11], v[8:9]
	s_nop 0
	flat_load_dwordx4 v[12:15], v[12:13]
	s_nop 0
	flat_load_dwordx4 v[16:19], v[16:17]
	s_nop 0
	flat_load_dwordx4 v[20:23], v[20:21]
	s_nop 0
	flat_load_dwordx4 v[24:27], v[24:25]
	s_nop 0
	flat_load_dwordx4 v[28:31], v[28:29]
	s_nop 0
	flat_load_dwordx4 v[32:35], v[34:35]
	s_nop 0
	flat_load_dwordx4 v[36:39], v[36:37]
	s_branch .LBB0_867
